# GEMM MFMA clusters: 36 back-to-back s_setprio 0 / s_setprio 1 pairs removed (one continuous priority-1 cluster per K-tile phase)
# speedup vs baseline: 1.0021x; 1.0018x over previous
; #define STAGE(bufoff, gbase) STAGE_(bufoff, gbase, voffA)
; #define STAGEB(bufoff, gbase) STAGE_(bufoff, gbase, voffB)
; #define LDA(dst, b, h) do { _Pragma("unroll") for (int m = 0; m < 4; ++m) _Pragma("unroll") for (int k = 0; k < 2; ++k) dst[m][k] = *LDSP(const bf16x8, lds + SA(b, h) + aoff + m * 2048 + k * 1024); } while (0)
; #define LDB(dst, b, h) do { _Pragma("unroll") for (int n = 0; n < 2; ++n) _Pragma("unroll") for (int k = 0; k < 2; ++k) dst[n][k] = *LDSP(const bf16x8, lds + SB(b, h) + boff + n * 2048 + k * 1024); } while (0)
; #define MMA(ai, bj, AT, BT) do { __builtin_amdgcn_s_setprio(1); \
;     _Pragma("unroll") for (int m = 0; m < 4; ++m) _Pragma("unroll") for (int n = 0; n < 2; ++n) _Pragma("unroll") for (int k = 0; k < 2; ++k) \
;       acc[ai][bj][m][n] = __builtin_amdgcn_mfma_f32_16x16x32_bf16(BT[n][k], AT[m][k], acc[ai][bj][m][n], 0, 0, 0); \
;     __builtin_amdgcn_s_setprio(0); } while (0)
; #define WAIT_V(n) asm volatile("s_waitcnt vmcnt(" #n ")" ::: "memory")
; #define WAIT_L(n) asm volatile("s_waitcnt lgkmcnt(" #n ")" ::: "memory")
; #define BAR __builtin_amdgcn_s_barrier()
; #define SCHED __builtin_amdgcn_sched_barrier(0)
; #define WAIT_V(n) asm volatile("s_waitcnt vmcnt(" #n ")" ::: "memory")
; #define BAR do { __builtin_amdgcn_sched_barrier(0); __builtin_amdgcn_s_barrier(); asm volatile("" ::: "memory"); __builtin_amdgcn_sched_barrier(0); } while (0)
; template <bool SP2, bool ALIGN_EPI, bool DUAL, class Epi> DI void gemm_phase2(const bf16_t* A, const bf16_t* Bt, const bf16_t* A2, const bf16_t* Bt2, int M, int N, int K, const Epi& E, lds_t* lds) {
;     ...
;       const char* a1 = cA + (size_t)(t + 1) * kstep;
;       const char* a2 = last ? nA : cA + (size_t)(t + 2) * kstep; const char* b2 = last ? nB : cB + (size_t)(t + 2) * kstep;
;       const char* a3 = a2 + kstep; const char* b3 = b2 + kstep;
;       if constexpr (SP2) {
;         LDB(B0, 0, 0); LDB(B1, 0, 1); SCHED; LDA(At, 0, 0); STAGE(SA(1, 1), a1 + hstep);
;         WAIT_V(8); WAIT_L(0); BAR; MMA(0, 0, At, B0); MMA(0, 1, At, B1); BAR; SCHED;
;         LDA(At, 0, 1); STAGEB(SB(0, 0), b2); STAGEB(SB(0, 1), b2 + bstep); STAGE(SA(0, 0), a2);
;         WAIT_V(8); WAIT_L(0); BAR; MMA(1, 0, At, B0); MMA(1, 1, At, B1); BAR; SCHED;
.LBB0_157:
	ds_read_b128 v[144:147], v161
	ds_read_b128 v[148:151], v161 offset:1024
	ds_read_b128 v[166:169], v161 offset:2048
	ds_read_b128 v[170:173], v161 offset:3072
	ds_read_b128 v[174:177], v162
	ds_read_b128 v[178:181], v162 offset:1024
	ds_read_b128 v[182:185], v162 offset:2048
	ds_read_b128 v[186:189], v162 offset:3072
	s_add_u32 s22, s8, 0xfffc0080
	s_addc_u32 s23, s9, -1
	s_cmp_eq_u32 s21, 12
	s_cselect_b32 s91, s0, s23
	s_cselect_b32 s90, s1, s22
	s_cselect_b32 s89, s11, s20
	s_cselect_b32 s88, s18, s19
	v_lshl_add_u64 v[152:153], s[8:9], 0, v[140:141]
	s_add_i32 m0, s3, 0xc000
	ds_read_b128 v[190:193], v163
	ds_read_b128 v[194:197], v163 offset:1024
	ds_read_b128 v[198:201], v163 offset:2048
	ds_read_b128 v[202:205], v163 offset:3072
	ds_read_b128 v[206:209], v163 offset:4096
	ds_read_b128 v[214:217], v163 offset:5120
	ds_read_b128 v[218:221], v163 offset:6144
	ds_read_b128 v[222:225], v163 offset:7168
	global_load_lds_dwordx4 v[152:153], off
	v_lshl_add_u64 v[152:153], s[8:9], 0, v[142:143]
	s_add_i32 m0, s3, 0xe000
	s_nop 0
	global_load_lds_dwordx4 v[152:153], off
	s_waitcnt vmcnt(8)
	s_waitcnt lgkmcnt(0)
	s_barrier
	s_setprio 1
	s_waitcnt lgkmcnt(0)
	v_mfma_f32_16x16x32_bf16 v[124:127], v[144:147], v[190:193], v[124:127]
	v_mfma_f32_16x16x32_bf16 v[120:123], v[166:169], v[190:193], v[120:123]
	v_mfma_f32_16x16x32_bf16 v[108:111], v[144:147], v[198:201], v[108:111]
	v_mfma_f32_16x16x32_bf16 v[104:107], v[166:169], v[198:201], v[104:107]
	v_mfma_f32_16x16x32_bf16 v[92:95], v[144:147], v[206:209], v[92:95]
	v_mfma_f32_16x16x32_bf16 v[88:91], v[166:169], v[206:209], v[88:91]
	v_mfma_f32_16x16x32_bf16 v[76:79], v[144:147], v[218:221], v[76:79]
	v_mfma_f32_16x16x32_bf16 v[72:75], v[166:169], v[218:221], v[72:75]
	v_mfma_f32_16x16x32_bf16 v[124:127], v[148:151], v[194:197], v[124:127]
	v_mfma_f32_16x16x32_bf16 v[120:123], v[170:173], v[194:197], v[120:123]
	v_mfma_f32_16x16x32_bf16 v[108:111], v[148:151], v[202:205], v[108:111]
	v_mfma_f32_16x16x32_bf16 v[104:107], v[170:173], v[202:205], v[104:107]
	v_mfma_f32_16x16x32_bf16 v[92:95], v[148:151], v[214:217], v[92:95]
	v_mfma_f32_16x16x32_bf16 v[88:91], v[170:173], v[214:217], v[88:91]
	v_mfma_f32_16x16x32_bf16 v[76:79], v[148:151], v[222:225], v[76:79]
	v_mfma_f32_16x16x32_bf16 v[72:75], v[170:173], v[222:225], v[72:75]
	v_mfma_f32_16x16x32_bf16 v[116:119], v[174:177], v[190:193], v[116:119]
	v_mfma_f32_16x16x32_bf16 v[112:115], v[182:185], v[190:193], v[112:115]
	v_mfma_f32_16x16x32_bf16 v[100:103], v[174:177], v[198:201], v[100:103]
	v_mfma_f32_16x16x32_bf16 v[96:99], v[182:185], v[198:201], v[96:99]
	v_mfma_f32_16x16x32_bf16 v[84:87], v[174:177], v[206:209], v[84:87]
	v_mfma_f32_16x16x32_bf16 v[80:83], v[182:185], v[206:209], v[80:83]
	v_mfma_f32_16x16x32_bf16 v[68:71], v[174:177], v[218:221], v[68:71]
	v_mfma_f32_16x16x32_bf16 v[64:67], v[182:185], v[218:221], v[64:67]
	v_mfma_f32_16x16x32_bf16 v[116:119], v[178:181], v[194:197], v[116:119]
	v_mfma_f32_16x16x32_bf16 v[112:115], v[186:189], v[194:197], v[112:115]
	v_mfma_f32_16x16x32_bf16 v[100:103], v[178:181], v[202:205], v[100:103]
	v_mfma_f32_16x16x32_bf16 v[96:99], v[186:189], v[202:205], v[96:99]
	v_mfma_f32_16x16x32_bf16 v[84:87], v[178:181], v[214:217], v[84:87]
	v_mfma_f32_16x16x32_bf16 v[80:83], v[186:189], v[214:217], v[80:83]
	v_mfma_f32_16x16x32_bf16 v[68:71], v[178:181], v[222:225], v[68:71]
	v_mfma_f32_16x16x32_bf16 v[64:67], v[186:189], v[222:225], v[64:67]
	s_setprio 0
	s_barrier
	s_add_i32 s22, s12, s2
	v_lshl_add_u64 v[152:153], s[88:89], 0, v[130:131]
	s_mov_b32 m0, s22
	ds_read_b128 v[190:193], v163 offset:16384
	ds_read_b128 v[194:197], v163 offset:17408
	ds_read_b128 v[198:201], v163 offset:18432
	ds_read_b128 v[202:205], v163 offset:19456
	ds_read_b128 v[206:209], v163 offset:20480
	ds_read_b128 v[214:217], v163 offset:21504
	ds_read_b128 v[218:221], v163 offset:22528
	ds_read_b128 v[222:225], v163 offset:23552
	global_load_lds_dwordx4 v[152:153], off
	s_add_i32 m0, s22, 0x2000
	s_add_u32 s22, s88, 0x10000
	v_lshl_add_u64 v[210:211], s[88:89], 0, v[134:135]
	s_addc_u32 s23, s89, 0
	s_add_i32 s33, s13, s2
	global_load_lds_dwordx4 v[210:211], off
	v_lshl_add_u64 v[226:227], s[22:23], 0, v[130:131]
	s_mov_b32 m0, s33
	v_lshl_add_u64 v[228:229], s[90:91], 0, v[132:133]
	global_load_lds_dwordx4 v[226:227], off
	v_lshl_add_u64 v[226:227], s[22:23], 0, v[134:135]
	s_add_i32 m0, s33, 0x2000
	s_nop 0
	global_load_lds_dwordx4 v[226:227], off
	v_lshl_add_u64 v[226:227], s[90:91], 0, v[128:129]
	s_mov_b32 m0, s3
	s_nop 0
	global_load_lds_dwordx4 v[226:227], off
	s_mov_b32 m0, s14
	s_nop 0
	global_load_lds_dwordx4 v[228:229], off
	s_waitcnt vmcnt(8)
	s_waitcnt lgkmcnt(0)
	s_barrier
; #define STAGE(bufoff, gbase) STAGE_(bufoff, gbase, voffA)
; #define LDA(dst, b, h) do { _Pragma("unroll") for (int m = 0; m < 4; ++m) _Pragma("unroll") for (int k = 0; k < 2; ++k) dst[m][k] = *LDSP(const bf16x8, lds + SA(b, h) + aoff + m * 2048 + k * 1024); } while (0)
; #define LDB(dst, b, h) do { _Pragma("unroll") for (int n = 0; n < 2; ++n) _Pragma("unroll") for (int k = 0; k < 2; ++k) dst[n][k] = *LDSP(const bf16x8, lds + SB(b, h) + boff + n * 2048 + k * 1024); } while (0)
; #define MMA(ai, bj, AT, BT) do { __builtin_amdgcn_s_setprio(1); \
;     _Pragma("unroll") for (int m = 0; m < 4; ++m) _Pragma("unroll") for (int n = 0; n < 2; ++n) _Pragma("unroll") for (int k = 0; k < 2; ++k) \
;       acc[ai][bj][m][n] = __builtin_amdgcn_mfma_f32_16x16x32_bf16(BT[n][k], AT[m][k], acc[ai][bj][m][n], 0, 0, 0); \
;     __builtin_amdgcn_s_setprio(0); } while (0)
; #define WAIT_V(n) asm volatile("s_waitcnt vmcnt(" #n ")" ::: "memory")
; #define WAIT_L(n) asm volatile("s_waitcnt lgkmcnt(" #n ")" ::: "memory")
; #define BAR __builtin_amdgcn_s_barrier()
; #define SCHED __builtin_amdgcn_sched_barrier(0)
; #define WAIT_V(n) asm volatile("s_waitcnt vmcnt(" #n ")" ::: "memory")
; #define BAR do { __builtin_amdgcn_sched_barrier(0); __builtin_amdgcn_s_barrier(); asm volatile("" ::: "memory"); __builtin_amdgcn_sched_barrier(0); } while (0)
; template <bool SP2, bool ALIGN_EPI, bool DUAL, class Epi> DI void gemm_phase2(const bf16_t* A, const bf16_t* Bt, const bf16_t* A2, const bf16_t* Bt2, int M, int N, int K, const Epi& E, lds_t* lds) {
;     ...
;         WAIT_V(8); WAIT_L(0); BAR; MMA(1, 0, At, B0); MMA(1, 1, At, B1); BAR; SCHED;
;         LDB(B0, 1, 0); LDB(B1, 1, 1); SCHED; LDA(At, 1, 0); STAGE(SA(0, 1), a2 + hstep);
;         WAIT_V(8); WAIT_L(0); BAR; MMA(0, 0, At, B0); MMA(0, 1, At, B1); BAR; SCHED;
	s_setprio 1
	s_waitcnt lgkmcnt(0)
	v_mfma_f32_16x16x32_bf16 v[60:63], v[144:147], v[190:193], v[60:63]
	v_mfma_f32_16x16x32_bf16 v[56:59], v[166:169], v[190:193], v[56:59]
	v_mfma_f32_16x16x32_bf16 v[44:47], v[144:147], v[198:201], v[44:47]
	v_mfma_f32_16x16x32_bf16 v[40:43], v[166:169], v[198:201], v[40:43]
	v_mfma_f32_16x16x32_bf16 v[28:31], v[144:147], v[206:209], v[28:31]
	v_mfma_f32_16x16x32_bf16 v[24:27], v[166:169], v[206:209], v[24:27]
	v_mfma_f32_16x16x32_bf16 v[12:15], v[144:147], v[218:221], v[12:15]
	v_mfma_f32_16x16x32_bf16 v[8:11], v[166:169], v[218:221], v[8:11]
	v_mfma_f32_16x16x32_bf16 v[60:63], v[148:151], v[194:197], v[60:63]
	v_mfma_f32_16x16x32_bf16 v[56:59], v[170:173], v[194:197], v[56:59]
	v_mfma_f32_16x16x32_bf16 v[44:47], v[148:151], v[202:205], v[44:47]
	v_mfma_f32_16x16x32_bf16 v[40:43], v[170:173], v[202:205], v[40:43]
	v_mfma_f32_16x16x32_bf16 v[28:31], v[148:151], v[214:217], v[28:31]
	v_mfma_f32_16x16x32_bf16 v[24:27], v[170:173], v[214:217], v[24:27]
	v_mfma_f32_16x16x32_bf16 v[12:15], v[148:151], v[222:225], v[12:15]
	v_mfma_f32_16x16x32_bf16 v[8:11], v[170:173], v[222:225], v[8:11]
	v_mfma_f32_16x16x32_bf16 v[52:55], v[174:177], v[190:193], v[52:55]
	v_mfma_f32_16x16x32_bf16 v[48:51], v[182:185], v[190:193], v[48:51]
	v_mfma_f32_16x16x32_bf16 v[36:39], v[174:177], v[198:201], v[36:39]
	v_mfma_f32_16x16x32_bf16 v[32:35], v[182:185], v[198:201], v[32:35]
	v_mfma_f32_16x16x32_bf16 v[20:23], v[174:177], v[206:209], v[20:23]
	v_mfma_f32_16x16x32_bf16 v[16:19], v[182:185], v[206:209], v[16:19]
	v_mfma_f32_16x16x32_bf16 v[4:7], v[174:177], v[218:221], v[4:7]
	v_mfma_f32_16x16x32_bf16 v[0:3], v[182:185], v[218:221], v[0:3]
	v_mfma_f32_16x16x32_bf16 v[52:55], v[178:181], v[194:197], v[52:55]
	v_mfma_f32_16x16x32_bf16 v[48:51], v[186:189], v[194:197], v[48:51]
	v_mfma_f32_16x16x32_bf16 v[36:39], v[178:181], v[202:205], v[36:39]
	v_mfma_f32_16x16x32_bf16 v[32:35], v[186:189], v[202:205], v[32:35]
	v_mfma_f32_16x16x32_bf16 v[20:23], v[178:181], v[214:217], v[20:23]
	v_mfma_f32_16x16x32_bf16 v[16:19], v[186:189], v[214:217], v[16:19]
	v_mfma_f32_16x16x32_bf16 v[4:7], v[178:181], v[222:225], v[4:7]
	v_mfma_f32_16x16x32_bf16 v[0:3], v[186:189], v[222:225], v[0:3]
	s_setprio 0
	s_barrier
	s_add_i32 s33, 0, 0x18000
	s_add_i32 s34, 0, 0x1c000
	v_add_u32_e32 v170, s33, v157
	v_add_u32_e32 v186, s34, v157
	ds_read_b128 v[144:147], v170
	ds_read_b128 v[148:151], v170 offset:1024
	ds_read_b128 v[166:169], v170 offset:2048
	ds_read_b128 v[170:173], v170 offset:3072
	ds_read_b128 v[174:177], v186
	ds_read_b128 v[178:181], v186 offset:1024
	ds_read_b128 v[182:185], v186 offset:2048
	ds_read_b128 v[186:189], v186 offset:3072
	s_add_u32 s22, s90, 0x40000
	s_addc_u32 s23, s91, 0
	s_mov_b32 m0, s15
	v_lshl_add_u64 v[230:231], s[22:23], 0, v[128:129]
	ds_read_b128 v[190:193], v163 offset:32768
	ds_read_b128 v[194:197], v163 offset:33792
	ds_read_b128 v[198:201], v163 offset:34816
	ds_read_b128 v[202:205], v163 offset:35840
	ds_read_b128 v[206:209], v163 offset:36864
	ds_read_b128 v[214:217], v163 offset:37888
	ds_read_b128 v[218:221], v163 offset:38912
	ds_read_b128 v[222:225], v163 offset:39936
	global_load_lds_dwordx4 v[230:231], off
	v_lshl_add_u64 v[230:231], s[22:23], 0, v[132:133]
	s_mov_b32 m0, s35
	s_nop 0
	global_load_lds_dwordx4 v[230:231], off
	s_waitcnt vmcnt(8)
	s_waitcnt lgkmcnt(0)
	s_barrier
	s_setprio 1
	s_waitcnt lgkmcnt(0)
	v_mfma_f32_16x16x32_bf16 v[124:127], v[144:147], v[190:193], v[124:127]
	v_mfma_f32_16x16x32_bf16 v[120:123], v[166:169], v[190:193], v[120:123]
	v_mfma_f32_16x16x32_bf16 v[108:111], v[144:147], v[198:201], v[108:111]
	v_mfma_f32_16x16x32_bf16 v[104:107], v[166:169], v[198:201], v[104:107]
	v_mfma_f32_16x16x32_bf16 v[92:95], v[144:147], v[206:209], v[92:95]
	v_mfma_f32_16x16x32_bf16 v[88:91], v[166:169], v[206:209], v[88:91]
	v_mfma_f32_16x16x32_bf16 v[76:79], v[144:147], v[218:221], v[76:79]
	v_mfma_f32_16x16x32_bf16 v[72:75], v[166:169], v[218:221], v[72:75]
	v_mfma_f32_16x16x32_bf16 v[124:127], v[148:151], v[194:197], v[124:127]
	v_mfma_f32_16x16x32_bf16 v[120:123], v[170:173], v[194:197], v[120:123]
	v_mfma_f32_16x16x32_bf16 v[108:111], v[148:151], v[202:205], v[108:111]
	v_mfma_f32_16x16x32_bf16 v[104:107], v[170:173], v[202:205], v[104:107]
	v_mfma_f32_16x16x32_bf16 v[92:95], v[148:151], v[214:217], v[92:95]
	v_mfma_f32_16x16x32_bf16 v[88:91], v[170:173], v[214:217], v[88:91]
	v_mfma_f32_16x16x32_bf16 v[76:79], v[148:151], v[222:225], v[76:79]
	v_mfma_f32_16x16x32_bf16 v[72:75], v[170:173], v[222:225], v[72:75]
	v_mfma_f32_16x16x32_bf16 v[116:119], v[174:177], v[190:193], v[116:119]
	v_mfma_f32_16x16x32_bf16 v[112:115], v[182:185], v[190:193], v[112:115]
	v_mfma_f32_16x16x32_bf16 v[100:103], v[174:177], v[198:201], v[100:103]
	v_mfma_f32_16x16x32_bf16 v[96:99], v[182:185], v[198:201], v[96:99]
	v_mfma_f32_16x16x32_bf16 v[84:87], v[174:177], v[206:209], v[84:87]
	v_mfma_f32_16x16x32_bf16 v[80:83], v[182:185], v[206:209], v[80:83]
	v_mfma_f32_16x16x32_bf16 v[68:71], v[174:177], v[218:221], v[68:71]
	v_mfma_f32_16x16x32_bf16 v[64:67], v[182:185], v[218:221], v[64:67]
	v_mfma_f32_16x16x32_bf16 v[116:119], v[178:181], v[194:197], v[116:119]
	v_mfma_f32_16x16x32_bf16 v[112:115], v[186:189], v[194:197], v[112:115]
	v_mfma_f32_16x16x32_bf16 v[100:103], v[178:181], v[202:205], v[100:103]
	v_mfma_f32_16x16x32_bf16 v[96:99], v[186:189], v[202:205], v[96:99]
	v_mfma_f32_16x16x32_bf16 v[84:87], v[178:181], v[214:217], v[84:87]
	v_mfma_f32_16x16x32_bf16 v[80:83], v[186:189], v[214:217], v[80:83]
	v_mfma_f32_16x16x32_bf16 v[68:71], v[178:181], v[222:225], v[68:71]
	v_mfma_f32_16x16x32_bf16 v[64:67], v[186:189], v[222:225], v[64:67]
	s_setprio 0
	s_barrier
; #define STAGE(bufoff, gbase) STAGE_(bufoff, gbase, voffA)
; #define STAGEB(bufoff, gbase) STAGE_(bufoff, gbase, voffB)
; #define LDA(dst, b, h) do { _Pragma("unroll") for (int m = 0; m < 4; ++m) _Pragma("unroll") for (int k = 0; k < 2; ++k) dst[m][k] = *LDSP(const bf16x8, lds + SA(b, h) + aoff + m * 2048 + k * 1024); } while (0)
; #define LDB(dst, b, h) do { _Pragma("unroll") for (int n = 0; n < 2; ++n) _Pragma("unroll") for (int k = 0; k < 2; ++k) dst[n][k] = *LDSP(const bf16x8, lds + SB(b, h) + boff + n * 2048 + k * 1024); } while (0)
; #define MMA(ai, bj, AT, BT) do { __builtin_amdgcn_s_setprio(1); \
;     _Pragma("unroll") for (int m = 0; m < 4; ++m) _Pragma("unroll") for (int n = 0; n < 2; ++n) _Pragma("unroll") for (int k = 0; k < 2; ++k) \
;       acc[ai][bj][m][n] = __builtin_amdgcn_mfma_f32_16x16x32_bf16(BT[n][k], AT[m][k], acc[ai][bj][m][n], 0, 0, 0); \
;     __builtin_amdgcn_s_setprio(0); } while (0)
; #define WAIT_V(n) asm volatile("s_waitcnt vmcnt(" #n ")" ::: "memory")
; #define WAIT_L(n) asm volatile("s_waitcnt lgkmcnt(" #n ")" ::: "memory")
; template <bool SP2, bool ALIGN_EPI, bool DUAL, class Epi> DI void gemm_phase2(const bf16_t* A, const bf16_t* Bt, const bf16_t* A2, const bf16_t* Bt2, int M, int N, int K, const Epi& E, lds_t* lds) {
;     ...
;     for (int t = 0; t < nt; t += 2) {
;       const bool last = (t == nt - 2);
;       const char* a1 = cA + (size_t)(t + 1) * kstep;
;       const char* a2 = last ? nA : cA + (size_t)(t + 2) * kstep; const char* b2 = last ? nB : cB + (size_t)(t + 2) * kstep;
;       const char* a3 = a2 + kstep; const char* b3 = b2 + kstep;
;       if constexpr (SP2) {
;         LDB(B0, 0, 0); LDB(B1, 0, 1); SCHED; LDA(At, 0, 0); STAGE(SA(1, 1), a1 + hstep);
;         WAIT_V(8); WAIT_L(0); BAR; MMA(0, 0, At, B0); MMA(0, 1, At, B1); BAR; SCHED;
;         LDA(At, 0, 1); STAGEB(SB(0, 0), b2); STAGEB(SB(0, 1), b2 + bstep); STAGE(SA(0, 0), a2);
;         WAIT_V(8); WAIT_L(0); BAR; MMA(1, 0, At, B0); MMA(1, 1, At, B1); BAR; SCHED;
;         LDB(B0, 1, 0); LDB(B1, 1, 1); SCHED; LDA(At, 1, 0); STAGE(SA(0, 1), a2 + hstep);
;         WAIT_V(8); WAIT_L(0); BAR; MMA(0, 0, At, B0); MMA(0, 1, At, B1); BAR; SCHED;
;         LDA(At, 1, 1); STAGEB(SB(1, 0), b3); STAGEB(SB(1, 1), b3 + bstep); STAGE(SA(1, 0), a3);
;         WAIT_V(8); WAIT_L(0); BAR; MMA(1, 0, At, B0); MMA(1, 1, At, B1); BAR; SCHED;
	s_add_i32 s22, s33, s2
	v_lshl_add_u64 v[152:153], v[152:153], 0, s[58:59]
	s_mov_b32 m0, s22
	ds_read_b128 v[190:193], v163 offset:49152
	ds_read_b128 v[194:197], v163 offset:50176
	ds_read_b128 v[198:201], v163 offset:51200
	ds_read_b128 v[202:205], v163 offset:52224
	ds_read_b128 v[206:209], v163 offset:53248
	ds_read_b128 v[214:217], v163 offset:54272
	ds_read_b128 v[218:221], v163 offset:55296
	ds_read_b128 v[222:225], v163 offset:56320
	global_load_lds_dwordx4 v[152:153], off
	s_add_i32 m0, s22, 0x2000
	s_add_u32 s22, s88, 0x10080
	v_lshl_add_u64 v[152:153], v[210:211], 0, s[58:59]
	s_addc_u32 s23, s89, 0
	s_add_i32 s33, s34, s2
	global_load_lds_dwordx4 v[152:153], off
	v_lshl_add_u64 v[152:153], s[22:23], 0, v[130:131]
	s_mov_b32 m0, s33
	s_nop 0
	global_load_lds_dwordx4 v[152:153], off
	v_lshl_add_u64 v[152:153], s[22:23], 0, v[134:135]
	s_add_i32 m0, s33, 0x2000
	s_nop 0
	global_load_lds_dwordx4 v[152:153], off
	v_lshl_add_u64 v[152:153], v[226:227], 0, s[58:59]
	s_mov_b32 m0, s52
	s_nop 0
	global_load_lds_dwordx4 v[152:153], off
	v_lshl_add_u64 v[152:153], v[228:229], 0, s[58:59]
	s_mov_b32 m0, s53
	s_nop 0
	global_load_lds_dwordx4 v[152:153], off
	s_waitcnt vmcnt(8)
	s_waitcnt lgkmcnt(0)
	s_barrier
	s_setprio 1
	s_waitcnt lgkmcnt(0)
	v_mfma_f32_16x16x32_bf16 v[60:63], v[144:147], v[190:193], v[60:63]
	v_mfma_f32_16x16x32_bf16 v[56:59], v[166:169], v[190:193], v[56:59]
	v_mfma_f32_16x16x32_bf16 v[44:47], v[144:147], v[198:201], v[44:47]
	v_mfma_f32_16x16x32_bf16 v[40:43], v[166:169], v[198:201], v[40:43]
	v_mfma_f32_16x16x32_bf16 v[28:31], v[144:147], v[206:209], v[28:31]
	v_mfma_f32_16x16x32_bf16 v[24:27], v[166:169], v[206:209], v[24:27]
	v_mfma_f32_16x16x32_bf16 v[12:15], v[144:147], v[218:221], v[12:15]
	v_mfma_f32_16x16x32_bf16 v[8:11], v[166:169], v[218:221], v[8:11]
	v_mfma_f32_16x16x32_bf16 v[60:63], v[148:151], v[194:197], v[60:63]
	v_mfma_f32_16x16x32_bf16 v[56:59], v[170:173], v[194:197], v[56:59]
	v_mfma_f32_16x16x32_bf16 v[44:47], v[148:151], v[202:205], v[44:47]
	v_mfma_f32_16x16x32_bf16 v[40:43], v[170:173], v[202:205], v[40:43]
	v_mfma_f32_16x16x32_bf16 v[28:31], v[148:151], v[214:217], v[28:31]
	v_mfma_f32_16x16x32_bf16 v[24:27], v[170:173], v[214:217], v[24:27]
	v_mfma_f32_16x16x32_bf16 v[12:15], v[148:151], v[222:225], v[12:15]
	v_mfma_f32_16x16x32_bf16 v[8:11], v[170:173], v[222:225], v[8:11]
	v_mfma_f32_16x16x32_bf16 v[52:55], v[174:177], v[190:193], v[52:55]
	v_mfma_f32_16x16x32_bf16 v[48:51], v[182:185], v[190:193], v[48:51]
	v_mfma_f32_16x16x32_bf16 v[36:39], v[174:177], v[198:201], v[36:39]
	v_mfma_f32_16x16x32_bf16 v[32:35], v[182:185], v[198:201], v[32:35]
	v_mfma_f32_16x16x32_bf16 v[20:23], v[174:177], v[206:209], v[20:23]
	v_mfma_f32_16x16x32_bf16 v[16:19], v[182:185], v[206:209], v[16:19]
	v_mfma_f32_16x16x32_bf16 v[4:7], v[174:177], v[218:221], v[4:7]
	v_mfma_f32_16x16x32_bf16 v[0:3], v[182:185], v[218:221], v[0:3]
	v_mfma_f32_16x16x32_bf16 v[52:55], v[178:181], v[194:197], v[52:55]
	v_mfma_f32_16x16x32_bf16 v[48:51], v[186:189], v[194:197], v[48:51]
	v_mfma_f32_16x16x32_bf16 v[36:39], v[178:181], v[202:205], v[36:39]
	v_mfma_f32_16x16x32_bf16 v[32:35], v[186:189], v[202:205], v[32:35]
	v_mfma_f32_16x16x32_bf16 v[20:23], v[178:181], v[214:217], v[20:23]
	v_mfma_f32_16x16x32_bf16 v[16:19], v[186:189], v[214:217], v[16:19]
	v_mfma_f32_16x16x32_bf16 v[4:7], v[178:181], v[222:225], v[4:7]
	v_mfma_f32_16x16x32_bf16 v[0:3], v[186:189], v[222:225], v[0:3]
	s_setprio 0
	s_barrier
	s_add_i32 s21, s21, 2
	s_add_u32 s8, s8, 0x100
	s_addc_u32 s9, s9, 0
	s_add_u32 s19, s19, 0x100
	s_addc_u32 s20, s20, 0
	s_cmp_gt_u32 s21, 13
	s_cbranch_scc0 .LBB0_157
	s_and_b64 vcc, exec, s[60:61]
	s_cbranch_vccz .LBB0_160
	s_barrier

; #define STAGE(bufoff, gbase) STAGE_(bufoff, gbase, voffA)
; #define STAGEB(bufoff, gbase) STAGE_(bufoff, gbase, voffB)
; #define LDA(dst, b, h) do { _Pragma("unroll") for (int m = 0; m < 4; ++m) _Pragma("unroll") for (int k = 0; k < 2; ++k) dst[m][k] = *LDSP(const bf16x8, lds + SA(b, h) + aoff + m * 2048 + k * 1024); } while (0)
; #define LDB(dst, b, h) do { _Pragma("unroll") for (int n = 0; n < 2; ++n) _Pragma("unroll") for (int k = 0; k < 2; ++k) dst[n][k] = *LDSP(const bf16x8, lds + SB(b, h) + boff + n * 2048 + k * 1024); } while (0)
; #define MMA(ai, bj, AT, BT) do { __builtin_amdgcn_s_setprio(1); \
;     _Pragma("unroll") for (int m = 0; m < 4; ++m) _Pragma("unroll") for (int n = 0; n < 2; ++n) _Pragma("unroll") for (int k = 0; k < 2; ++k) \
;       acc[ai][bj][m][n] = __builtin_amdgcn_mfma_f32_16x16x32_bf16(BT[n][k], AT[m][k], acc[ai][bj][m][n], 0, 0, 0); \
;     __builtin_amdgcn_s_setprio(0); } while (0)
; #define WAIT_V(n) asm volatile("s_waitcnt vmcnt(" #n ")" ::: "memory")
; #define WAIT_L(n) asm volatile("s_waitcnt lgkmcnt(" #n ")" ::: "memory")
; #define BAR __builtin_amdgcn_s_barrier()
; #define SCHED __builtin_amdgcn_sched_barrier(0)
; #define WAIT_V(n) asm volatile("s_waitcnt vmcnt(" #n ")" ::: "memory")
; #define BAR do { __builtin_amdgcn_sched_barrier(0); __builtin_amdgcn_s_barrier(); asm volatile("" ::: "memory"); __builtin_amdgcn_sched_barrier(0); } while (0)
; template <bool SP2, bool ALIGN_EPI, bool DUAL, class Epi> DI void gemm_phase2(const bf16_t* A, const bf16_t* Bt, const bf16_t* A2, const bf16_t* Bt2, int M, int N, int K, const Epi& E, lds_t* lds) {
;     ...
;       const bool last = (t == nt - 2);
;       const char* a1 = cA + (size_t)(t + 1) * kstep;
;       const char* a2 = last ? nA : cA + (size_t)(t + 2) * kstep; const char* b2 = last ? nB : cB + (size_t)(t + 2) * kstep;
;       const char* a3 = a2 + kstep; const char* b3 = b2 + kstep;
;       if constexpr (SP2) {
;         LDB(B0, 0, 0); LDB(B1, 0, 1); SCHED; LDA(At, 0, 0); STAGE(SA(1, 1), a1 + hstep);
;         WAIT_V(8); WAIT_L(0); BAR; MMA(0, 0, At, B0); MMA(0, 1, At, B1); BAR; SCHED;
;         LDA(At, 0, 1); STAGEB(SB(0, 0), b2); STAGEB(SB(0, 1), b2 + bstep); STAGE(SA(0, 0), a2);
;         WAIT_V(8); WAIT_L(0); BAR; MMA(1, 0, At, B0); MMA(1, 1, At, B1); BAR; SCHED;
.LBB0_341:
	ds_read_b128 v[148:151], v145
	ds_read_b128 v[156:159], v145 offset:1024
	ds_read_b128 v[160:163], v145 offset:2048
	ds_read_b128 v[164:167], v145 offset:3072
	ds_read_b128 v[168:171], v146
	ds_read_b128 v[172:175], v146 offset:1024
	ds_read_b128 v[176:179], v146 offset:2048
	ds_read_b128 v[180:183], v146 offset:3072
	s_add_u32 s52, s68, 0xfffc0080
	s_addc_u32 s53, s69, -1
	s_cmp_eq_u32 s35, 12
	s_cselect_b32 s89, s0, s53
	s_cselect_b32 s88, s1, s52
	s_cselect_b32 s87, s11, s34
	s_cselect_b32 s86, s23, s33
	v_lshl_add_u64 v[152:153], s[68:69], 0, v[136:137]
	s_add_i32 m0, s3, 0xc000
	ds_read_b128 v[184:187], v147
	ds_read_b128 v[188:191], v147 offset:1024
	ds_read_b128 v[192:195], v147 offset:2048
	ds_read_b128 v[196:199], v147 offset:3072
	ds_read_b128 v[200:203], v147 offset:4096
	ds_read_b128 v[204:207], v147 offset:5120
	ds_read_b128 v[208:211], v147 offset:6144
	ds_read_b128 v[214:217], v147 offset:7168
	global_load_lds_dwordx4 v[152:153], off
	v_lshl_add_u64 v[152:153], s[68:69], 0, v[138:139]
	s_add_i32 m0, s3, 0xe000
	s_nop 0
	global_load_lds_dwordx4 v[152:153], off
	s_waitcnt vmcnt(8)
	s_waitcnt lgkmcnt(0)
	s_barrier
	s_setprio 1
	s_waitcnt lgkmcnt(0)
	v_mfma_f32_16x16x32_bf16 v[124:127], v[148:151], v[184:187], v[124:127]
	v_mfma_f32_16x16x32_bf16 v[120:123], v[160:163], v[184:187], v[120:123]
	v_mfma_f32_16x16x32_bf16 v[108:111], v[148:151], v[192:195], v[108:111]
	v_mfma_f32_16x16x32_bf16 v[104:107], v[160:163], v[192:195], v[104:107]
	v_mfma_f32_16x16x32_bf16 v[92:95], v[148:151], v[200:203], v[92:95]
	v_mfma_f32_16x16x32_bf16 v[88:91], v[160:163], v[200:203], v[88:91]
	v_mfma_f32_16x16x32_bf16 v[76:79], v[148:151], v[208:211], v[76:79]
	v_mfma_f32_16x16x32_bf16 v[72:75], v[160:163], v[208:211], v[72:75]
	v_mfma_f32_16x16x32_bf16 v[124:127], v[156:159], v[188:191], v[124:127]
	v_mfma_f32_16x16x32_bf16 v[120:123], v[164:167], v[188:191], v[120:123]
	v_mfma_f32_16x16x32_bf16 v[108:111], v[156:159], v[196:199], v[108:111]
	v_mfma_f32_16x16x32_bf16 v[104:107], v[164:167], v[196:199], v[104:107]
	v_mfma_f32_16x16x32_bf16 v[92:95], v[156:159], v[204:207], v[92:95]
	v_mfma_f32_16x16x32_bf16 v[88:91], v[164:167], v[204:207], v[88:91]
	v_mfma_f32_16x16x32_bf16 v[76:79], v[156:159], v[214:217], v[76:79]
	v_mfma_f32_16x16x32_bf16 v[72:75], v[164:167], v[214:217], v[72:75]
	v_mfma_f32_16x16x32_bf16 v[116:119], v[168:171], v[184:187], v[116:119]
	v_mfma_f32_16x16x32_bf16 v[112:115], v[176:179], v[184:187], v[112:115]
	v_mfma_f32_16x16x32_bf16 v[100:103], v[168:171], v[192:195], v[100:103]
	v_mfma_f32_16x16x32_bf16 v[96:99], v[176:179], v[192:195], v[96:99]
	v_mfma_f32_16x16x32_bf16 v[84:87], v[168:171], v[200:203], v[84:87]
	v_mfma_f32_16x16x32_bf16 v[80:83], v[176:179], v[200:203], v[80:83]
	v_mfma_f32_16x16x32_bf16 v[68:71], v[168:171], v[208:211], v[68:71]
	v_mfma_f32_16x16x32_bf16 v[64:67], v[176:179], v[208:211], v[64:67]
	v_mfma_f32_16x16x32_bf16 v[116:119], v[172:175], v[188:191], v[116:119]
	v_mfma_f32_16x16x32_bf16 v[112:115], v[180:183], v[188:191], v[112:115]
	v_mfma_f32_16x16x32_bf16 v[100:103], v[172:175], v[196:199], v[100:103]
	v_mfma_f32_16x16x32_bf16 v[96:99], v[180:183], v[196:199], v[96:99]
	v_mfma_f32_16x16x32_bf16 v[84:87], v[172:175], v[204:207], v[84:87]
	v_mfma_f32_16x16x32_bf16 v[80:83], v[180:183], v[204:207], v[80:83]
	v_mfma_f32_16x16x32_bf16 v[68:71], v[172:175], v[214:217], v[68:71]
	v_mfma_f32_16x16x32_bf16 v[64:67], v[180:183], v[214:217], v[64:67]
	s_setprio 0
	s_barrier
	s_add_i32 s52, s19, s2
	v_lshl_add_u64 v[152:153], s[86:87], 0, v[130:131]
	s_mov_b32 m0, s52
	ds_read_b128 v[184:187], v147 offset:16384
	ds_read_b128 v[188:191], v147 offset:17408
	ds_read_b128 v[192:195], v147 offset:18432
	ds_read_b128 v[196:199], v147 offset:19456
	ds_read_b128 v[200:203], v147 offset:20480
	ds_read_b128 v[204:207], v147 offset:21504
	ds_read_b128 v[208:211], v147 offset:22528
	ds_read_b128 v[214:217], v147 offset:23552
	global_load_lds_dwordx4 v[152:153], off
	s_add_i32 m0, s52, 0x2000
	s_add_u32 s52, s86, 0x10000
	v_lshl_add_u64 v[218:219], s[86:87], 0, v[134:135]
	s_addc_u32 s53, s87, 0
	s_add_i32 s61, s20, s2
	global_load_lds_dwordx4 v[218:219], off
	v_lshl_add_u64 v[220:221], s[52:53], 0, v[130:131]
	s_mov_b32 m0, s61
	v_lshl_add_u64 v[222:223], s[88:89], 0, v[132:133]
	global_load_lds_dwordx4 v[220:221], off
	v_lshl_add_u64 v[220:221], s[52:53], 0, v[134:135]
	s_add_i32 m0, s61, 0x2000
	s_nop 0
	global_load_lds_dwordx4 v[220:221], off
	v_lshl_add_u64 v[220:221], s[88:89], 0, v[128:129]
	s_mov_b32 m0, s3
	s_nop 0
	global_load_lds_dwordx4 v[220:221], off
	s_mov_b32 m0, s12
	s_nop 0
	global_load_lds_dwordx4 v[222:223], off
	s_waitcnt vmcnt(8)
	s_waitcnt lgkmcnt(0)
	s_barrier
; #define STAGE(bufoff, gbase) STAGE_(bufoff, gbase, voffA)
; #define LDA(dst, b, h) do { _Pragma("unroll") for (int m = 0; m < 4; ++m) _Pragma("unroll") for (int k = 0; k < 2; ++k) dst[m][k] = *LDSP(const bf16x8, lds + SA(b, h) + aoff + m * 2048 + k * 1024); } while (0)
; #define LDB(dst, b, h) do { _Pragma("unroll") for (int n = 0; n < 2; ++n) _Pragma("unroll") for (int k = 0; k < 2; ++k) dst[n][k] = *LDSP(const bf16x8, lds + SB(b, h) + boff + n * 2048 + k * 1024); } while (0)
; #define MMA(ai, bj, AT, BT) do { __builtin_amdgcn_s_setprio(1); \
;     _Pragma("unroll") for (int m = 0; m < 4; ++m) _Pragma("unroll") for (int n = 0; n < 2; ++n) _Pragma("unroll") for (int k = 0; k < 2; ++k) \
;       acc[ai][bj][m][n] = __builtin_amdgcn_mfma_f32_16x16x32_bf16(BT[n][k], AT[m][k], acc[ai][bj][m][n], 0, 0, 0); \
;     __builtin_amdgcn_s_setprio(0); } while (0)
; #define WAIT_V(n) asm volatile("s_waitcnt vmcnt(" #n ")" ::: "memory")
; #define WAIT_L(n) asm volatile("s_waitcnt lgkmcnt(" #n ")" ::: "memory")
; #define BAR __builtin_amdgcn_s_barrier()
; #define SCHED __builtin_amdgcn_sched_barrier(0)
; #define WAIT_V(n) asm volatile("s_waitcnt vmcnt(" #n ")" ::: "memory")
; #define BAR do { __builtin_amdgcn_sched_barrier(0); __builtin_amdgcn_s_barrier(); asm volatile("" ::: "memory"); __builtin_amdgcn_sched_barrier(0); } while (0)
; template <bool SP2, bool ALIGN_EPI, bool DUAL, class Epi> DI void gemm_phase2(const bf16_t* A, const bf16_t* Bt, const bf16_t* A2, const bf16_t* Bt2, int M, int N, int K, const Epi& E, lds_t* lds) {
;     ...
;         WAIT_V(8); WAIT_L(0); BAR; MMA(1, 0, At, B0); MMA(1, 1, At, B1); BAR; SCHED;
;         LDB(B0, 1, 0); LDB(B1, 1, 1); SCHED; LDA(At, 1, 0); STAGE(SA(0, 1), a2 + hstep);
;         WAIT_V(8); WAIT_L(0); BAR; MMA(0, 0, At, B0); MMA(0, 1, At, B1); BAR; SCHED;
	s_setprio 1
	s_waitcnt lgkmcnt(0)
	v_mfma_f32_16x16x32_bf16 v[60:63], v[148:151], v[184:187], v[60:63]
	v_mfma_f32_16x16x32_bf16 v[56:59], v[160:163], v[184:187], v[56:59]
	v_mfma_f32_16x16x32_bf16 v[44:47], v[148:151], v[192:195], v[44:47]
	v_mfma_f32_16x16x32_bf16 v[40:43], v[160:163], v[192:195], v[40:43]
	v_mfma_f32_16x16x32_bf16 v[28:31], v[148:151], v[200:203], v[28:31]
	v_mfma_f32_16x16x32_bf16 v[24:27], v[160:163], v[200:203], v[24:27]
	v_mfma_f32_16x16x32_bf16 v[12:15], v[148:151], v[208:211], v[12:15]
	v_mfma_f32_16x16x32_bf16 v[8:11], v[160:163], v[208:211], v[8:11]
	v_mfma_f32_16x16x32_bf16 v[60:63], v[156:159], v[188:191], v[60:63]
	v_mfma_f32_16x16x32_bf16 v[56:59], v[164:167], v[188:191], v[56:59]
	v_mfma_f32_16x16x32_bf16 v[44:47], v[156:159], v[196:199], v[44:47]
	v_mfma_f32_16x16x32_bf16 v[40:43], v[164:167], v[196:199], v[40:43]
	v_mfma_f32_16x16x32_bf16 v[28:31], v[156:159], v[204:207], v[28:31]
	v_mfma_f32_16x16x32_bf16 v[24:27], v[164:167], v[204:207], v[24:27]
	v_mfma_f32_16x16x32_bf16 v[12:15], v[156:159], v[214:217], v[12:15]
	v_mfma_f32_16x16x32_bf16 v[8:11], v[164:167], v[214:217], v[8:11]
	v_mfma_f32_16x16x32_bf16 v[52:55], v[168:171], v[184:187], v[52:55]
	v_mfma_f32_16x16x32_bf16 v[48:51], v[176:179], v[184:187], v[48:51]
	v_mfma_f32_16x16x32_bf16 v[36:39], v[168:171], v[192:195], v[36:39]
	v_mfma_f32_16x16x32_bf16 v[32:35], v[176:179], v[192:195], v[32:35]
	v_mfma_f32_16x16x32_bf16 v[20:23], v[168:171], v[200:203], v[20:23]
	v_mfma_f32_16x16x32_bf16 v[16:19], v[176:179], v[200:203], v[16:19]
	v_mfma_f32_16x16x32_bf16 v[4:7], v[168:171], v[208:211], v[4:7]
	v_mfma_f32_16x16x32_bf16 v[0:3], v[176:179], v[208:211], v[0:3]
	v_mfma_f32_16x16x32_bf16 v[52:55], v[172:175], v[188:191], v[52:55]
	v_mfma_f32_16x16x32_bf16 v[48:51], v[180:183], v[188:191], v[48:51]
	v_mfma_f32_16x16x32_bf16 v[36:39], v[172:175], v[196:199], v[36:39]
	v_mfma_f32_16x16x32_bf16 v[32:35], v[180:183], v[196:199], v[32:35]
	v_mfma_f32_16x16x32_bf16 v[20:23], v[172:175], v[204:207], v[20:23]
	v_mfma_f32_16x16x32_bf16 v[16:19], v[180:183], v[204:207], v[16:19]
	v_mfma_f32_16x16x32_bf16 v[4:7], v[172:175], v[214:217], v[4:7]
	v_mfma_f32_16x16x32_bf16 v[0:3], v[180:183], v[214:217], v[0:3]
	s_setprio 0
	s_barrier
	s_add_i32 s61, 0, 0x18000
	v_add_u32_e32 v155, s61, v140
	s_add_i32 s65, 0, 0x1c000
	ds_read_b128 v[148:151], v155
	ds_read_b128 v[156:159], v155 offset:1024
	ds_read_b128 v[160:163], v155 offset:2048
	ds_read_b128 v[164:167], v155 offset:3072
	v_add_u32_e32 v155, s65, v140
	ds_read_b128 v[168:171], v155
	ds_read_b128 v[172:175], v155 offset:1024
	ds_read_b128 v[176:179], v155 offset:2048
	ds_read_b128 v[180:183], v155 offset:3072
	s_add_u32 s52, s88, 0x40000
	s_addc_u32 s53, s89, 0
	s_mov_b32 m0, s13
	v_lshl_add_u64 v[224:225], s[52:53], 0, v[128:129]
	ds_read_b128 v[184:187], v147 offset:32768
	ds_read_b128 v[188:191], v147 offset:33792
	ds_read_b128 v[192:195], v147 offset:34816
	ds_read_b128 v[196:199], v147 offset:35840
	ds_read_b128 v[200:203], v147 offset:36864
	ds_read_b128 v[204:207], v147 offset:37888
	ds_read_b128 v[208:211], v147 offset:38912
	ds_read_b128 v[214:217], v147 offset:39936
	global_load_lds_dwordx4 v[224:225], off
	v_lshl_add_u64 v[224:225], s[52:53], 0, v[132:133]
	s_mov_b32 m0, s14
	s_nop 0
	global_load_lds_dwordx4 v[224:225], off
	s_waitcnt vmcnt(8)
	s_waitcnt lgkmcnt(0)
	s_barrier
	s_setprio 1
	s_waitcnt lgkmcnt(0)
	v_mfma_f32_16x16x32_bf16 v[124:127], v[148:151], v[184:187], v[124:127]
	v_mfma_f32_16x16x32_bf16 v[120:123], v[160:163], v[184:187], v[120:123]
	v_mfma_f32_16x16x32_bf16 v[108:111], v[148:151], v[192:195], v[108:111]
	v_mfma_f32_16x16x32_bf16 v[104:107], v[160:163], v[192:195], v[104:107]
	v_mfma_f32_16x16x32_bf16 v[92:95], v[148:151], v[200:203], v[92:95]
	v_mfma_f32_16x16x32_bf16 v[88:91], v[160:163], v[200:203], v[88:91]
	v_mfma_f32_16x16x32_bf16 v[76:79], v[148:151], v[208:211], v[76:79]
	v_mfma_f32_16x16x32_bf16 v[72:75], v[160:163], v[208:211], v[72:75]
	v_mfma_f32_16x16x32_bf16 v[124:127], v[156:159], v[188:191], v[124:127]
	v_mfma_f32_16x16x32_bf16 v[120:123], v[164:167], v[188:191], v[120:123]
	v_mfma_f32_16x16x32_bf16 v[108:111], v[156:159], v[196:199], v[108:111]
	v_mfma_f32_16x16x32_bf16 v[104:107], v[164:167], v[196:199], v[104:107]
	v_mfma_f32_16x16x32_bf16 v[92:95], v[156:159], v[204:207], v[92:95]
	v_mfma_f32_16x16x32_bf16 v[88:91], v[164:167], v[204:207], v[88:91]
	v_mfma_f32_16x16x32_bf16 v[76:79], v[156:159], v[214:217], v[76:79]
	v_mfma_f32_16x16x32_bf16 v[72:75], v[164:167], v[214:217], v[72:75]
	v_mfma_f32_16x16x32_bf16 v[116:119], v[168:171], v[184:187], v[116:119]
	v_mfma_f32_16x16x32_bf16 v[112:115], v[176:179], v[184:187], v[112:115]
	v_mfma_f32_16x16x32_bf16 v[100:103], v[168:171], v[192:195], v[100:103]
	v_mfma_f32_16x16x32_bf16 v[96:99], v[176:179], v[192:195], v[96:99]
	v_mfma_f32_16x16x32_bf16 v[84:87], v[168:171], v[200:203], v[84:87]
	v_mfma_f32_16x16x32_bf16 v[80:83], v[176:179], v[200:203], v[80:83]
	v_mfma_f32_16x16x32_bf16 v[68:71], v[168:171], v[208:211], v[68:71]
	v_mfma_f32_16x16x32_bf16 v[64:67], v[176:179], v[208:211], v[64:67]
	v_mfma_f32_16x16x32_bf16 v[116:119], v[172:175], v[188:191], v[116:119]
	v_mfma_f32_16x16x32_bf16 v[112:115], v[180:183], v[188:191], v[112:115]
	v_mfma_f32_16x16x32_bf16 v[100:103], v[172:175], v[196:199], v[100:103]
	v_mfma_f32_16x16x32_bf16 v[96:99], v[180:183], v[196:199], v[96:99]
	v_mfma_f32_16x16x32_bf16 v[84:87], v[172:175], v[204:207], v[84:87]
	v_mfma_f32_16x16x32_bf16 v[80:83], v[180:183], v[204:207], v[80:83]
	v_mfma_f32_16x16x32_bf16 v[68:71], v[172:175], v[214:217], v[68:71]
	v_mfma_f32_16x16x32_bf16 v[64:67], v[180:183], v[214:217], v[64:67]
	s_setprio 0
	s_barrier
; #define STAGE(bufoff, gbase) STAGE_(bufoff, gbase, voffA)
; #define STAGEB(bufoff, gbase) STAGE_(bufoff, gbase, voffB)
; #define LDA(dst, b, h) do { _Pragma("unroll") for (int m = 0; m < 4; ++m) _Pragma("unroll") for (int k = 0; k < 2; ++k) dst[m][k] = *LDSP(const bf16x8, lds + SA(b, h) + aoff + m * 2048 + k * 1024); } while (0)
; #define LDB(dst, b, h) do { _Pragma("unroll") for (int n = 0; n < 2; ++n) _Pragma("unroll") for (int k = 0; k < 2; ++k) dst[n][k] = *LDSP(const bf16x8, lds + SB(b, h) + boff + n * 2048 + k * 1024); } while (0)
; #define MMA(ai, bj, AT, BT) do { __builtin_amdgcn_s_setprio(1); \
;     _Pragma("unroll") for (int m = 0; m < 4; ++m) _Pragma("unroll") for (int n = 0; n < 2; ++n) _Pragma("unroll") for (int k = 0; k < 2; ++k) \
;       acc[ai][bj][m][n] = __builtin_amdgcn_mfma_f32_16x16x32_bf16(BT[n][k], AT[m][k], acc[ai][bj][m][n], 0, 0, 0); \
;     __builtin_amdgcn_s_setprio(0); } while (0)
; #define WAIT_V(n) asm volatile("s_waitcnt vmcnt(" #n ")" ::: "memory")
; #define WAIT_L(n) asm volatile("s_waitcnt lgkmcnt(" #n ")" ::: "memory")
; template <bool SP2, bool ALIGN_EPI, bool DUAL, class Epi> DI void gemm_phase2(const bf16_t* A, const bf16_t* Bt, const bf16_t* A2, const bf16_t* Bt2, int M, int N, int K, const Epi& E, lds_t* lds) {
;     ...
;     for (int t = 0; t < nt; t += 2) {
;       const bool last = (t == nt - 2);
;       const char* a1 = cA + (size_t)(t + 1) * kstep;
;       const char* a2 = last ? nA : cA + (size_t)(t + 2) * kstep; const char* b2 = last ? nB : cB + (size_t)(t + 2) * kstep;
;       const char* a3 = a2 + kstep; const char* b3 = b2 + kstep;
;       if constexpr (SP2) {
;         LDB(B0, 0, 0); LDB(B1, 0, 1); SCHED; LDA(At, 0, 0); STAGE(SA(1, 1), a1 + hstep);
;         WAIT_V(8); WAIT_L(0); BAR; MMA(0, 0, At, B0); MMA(0, 1, At, B1); BAR; SCHED;
;         LDA(At, 0, 1); STAGEB(SB(0, 0), b2); STAGEB(SB(0, 1), b2 + bstep); STAGE(SA(0, 0), a2);
;         WAIT_V(8); WAIT_L(0); BAR; MMA(1, 0, At, B0); MMA(1, 1, At, B1); BAR; SCHED;
;         LDB(B0, 1, 0); LDB(B1, 1, 1); SCHED; LDA(At, 1, 0); STAGE(SA(0, 1), a2 + hstep);
;         WAIT_V(8); WAIT_L(0); BAR; MMA(0, 0, At, B0); MMA(0, 1, At, B1); BAR; SCHED;
;         LDA(At, 1, 1); STAGEB(SB(1, 0), b3); STAGEB(SB(1, 1), b3 + bstep); STAGE(SA(1, 0), a3);
;         WAIT_V(8); WAIT_L(0); BAR; MMA(1, 0, At, B0); MMA(1, 1, At, B1); BAR; SCHED;
	s_add_i32 s52, s61, s2
	v_lshl_add_u64 v[152:153], v[152:153], 0, s[8:9]
	s_mov_b32 m0, s52
	ds_read_b128 v[184:187], v147 offset:49152
	ds_read_b128 v[188:191], v147 offset:50176
	ds_read_b128 v[192:195], v147 offset:51200
	ds_read_b128 v[196:199], v147 offset:52224
	ds_read_b128 v[200:203], v147 offset:53248
	ds_read_b128 v[204:207], v147 offset:54272
	ds_read_b128 v[208:211], v147 offset:55296
	ds_read_b128 v[214:217], v147 offset:56320
	global_load_lds_dwordx4 v[152:153], off
	s_add_i32 m0, s52, 0x2000
	s_add_u32 s52, s86, 0x10080
	v_lshl_add_u64 v[152:153], v[218:219], 0, s[8:9]
	s_addc_u32 s53, s87, 0
	s_add_i32 s61, s65, s2
	global_load_lds_dwordx4 v[152:153], off
	v_lshl_add_u64 v[152:153], s[52:53], 0, v[130:131]
	s_mov_b32 m0, s61
	s_nop 0
	global_load_lds_dwordx4 v[152:153], off
	v_lshl_add_u64 v[152:153], s[52:53], 0, v[134:135]
	s_add_i32 m0, s61, 0x2000
	s_nop 0
	global_load_lds_dwordx4 v[152:153], off
	v_lshl_add_u64 v[152:153], v[220:221], 0, s[8:9]
	s_mov_b32 m0, s15
	s_nop 0
	global_load_lds_dwordx4 v[152:153], off
	v_lshl_add_u64 v[152:153], v[222:223], 0, s[8:9]
	s_mov_b32 m0, s18
	s_nop 0
	global_load_lds_dwordx4 v[152:153], off
	s_waitcnt vmcnt(8)
	s_waitcnt lgkmcnt(0)
	s_barrier
	s_setprio 1
	s_waitcnt lgkmcnt(0)
	v_mfma_f32_16x16x32_bf16 v[60:63], v[148:151], v[184:187], v[60:63]
	v_mfma_f32_16x16x32_bf16 v[56:59], v[160:163], v[184:187], v[56:59]
	v_mfma_f32_16x16x32_bf16 v[44:47], v[148:151], v[192:195], v[44:47]
	v_mfma_f32_16x16x32_bf16 v[40:43], v[160:163], v[192:195], v[40:43]
	v_mfma_f32_16x16x32_bf16 v[28:31], v[148:151], v[200:203], v[28:31]
	v_mfma_f32_16x16x32_bf16 v[24:27], v[160:163], v[200:203], v[24:27]
	v_mfma_f32_16x16x32_bf16 v[12:15], v[148:151], v[208:211], v[12:15]
	v_mfma_f32_16x16x32_bf16 v[8:11], v[160:163], v[208:211], v[8:11]
	v_mfma_f32_16x16x32_bf16 v[60:63], v[156:159], v[188:191], v[60:63]
	v_mfma_f32_16x16x32_bf16 v[56:59], v[164:167], v[188:191], v[56:59]
	v_mfma_f32_16x16x32_bf16 v[44:47], v[156:159], v[196:199], v[44:47]
	v_mfma_f32_16x16x32_bf16 v[40:43], v[164:167], v[196:199], v[40:43]
	v_mfma_f32_16x16x32_bf16 v[28:31], v[156:159], v[204:207], v[28:31]
	v_mfma_f32_16x16x32_bf16 v[24:27], v[164:167], v[204:207], v[24:27]
	v_mfma_f32_16x16x32_bf16 v[12:15], v[156:159], v[214:217], v[12:15]
	v_mfma_f32_16x16x32_bf16 v[8:11], v[164:167], v[214:217], v[8:11]
	v_mfma_f32_16x16x32_bf16 v[52:55], v[168:171], v[184:187], v[52:55]
	v_mfma_f32_16x16x32_bf16 v[48:51], v[176:179], v[184:187], v[48:51]
	v_mfma_f32_16x16x32_bf16 v[36:39], v[168:171], v[192:195], v[36:39]
	v_mfma_f32_16x16x32_bf16 v[32:35], v[176:179], v[192:195], v[32:35]
	v_mfma_f32_16x16x32_bf16 v[20:23], v[168:171], v[200:203], v[20:23]
	v_mfma_f32_16x16x32_bf16 v[16:19], v[176:179], v[200:203], v[16:19]
	v_mfma_f32_16x16x32_bf16 v[4:7], v[168:171], v[208:211], v[4:7]
	v_mfma_f32_16x16x32_bf16 v[0:3], v[176:179], v[208:211], v[0:3]
	v_mfma_f32_16x16x32_bf16 v[52:55], v[172:175], v[188:191], v[52:55]
	v_mfma_f32_16x16x32_bf16 v[48:51], v[180:183], v[188:191], v[48:51]
	v_mfma_f32_16x16x32_bf16 v[36:39], v[172:175], v[196:199], v[36:39]
	v_mfma_f32_16x16x32_bf16 v[32:35], v[180:183], v[196:199], v[32:35]
	v_mfma_f32_16x16x32_bf16 v[20:23], v[172:175], v[204:207], v[20:23]
	v_mfma_f32_16x16x32_bf16 v[16:19], v[180:183], v[204:207], v[16:19]
	v_mfma_f32_16x16x32_bf16 v[4:7], v[172:175], v[214:217], v[4:7]
	v_mfma_f32_16x16x32_bf16 v[0:3], v[180:183], v[214:217], v[0:3]
	s_setprio 0
	s_barrier
	s_add_i32 s35, s35, 2
	s_add_u32 s68, s68, 0x100
	s_addc_u32 s69, s69, 0
	s_add_u32 s33, s33, 0x100
	s_addc_u32 s34, s34, 0
	s_cmp_gt_u32 s35, 13
	s_cbranch_scc0 .LBB0_341
	s_and_b64 vcc, exec, s[54:55]
	s_cbranch_vccz .LBB0_344
	s_barrier

; #define STAGE(bufoff, gbase) STAGE_(bufoff, gbase, voffA)
; #define STAGEB(bufoff, gbase) STAGE_(bufoff, gbase, voffB)
; #define LDA(dst, b, h) do { _Pragma("unroll") for (int m = 0; m < 4; ++m) _Pragma("unroll") for (int k = 0; k < 2; ++k) dst[m][k] = *LDSP(const bf16x8, lds + SA(b, h) + aoff + m * 2048 + k * 1024); } while (0)
; #define LDB(dst, b, h) do { _Pragma("unroll") for (int n = 0; n < 2; ++n) _Pragma("unroll") for (int k = 0; k < 2; ++k) dst[n][k] = *LDSP(const bf16x8, lds + SB(b, h) + boff + n * 2048 + k * 1024); } while (0)
; #define MMA(ai, bj, AT, BT) do { __builtin_amdgcn_s_setprio(1); \
;     _Pragma("unroll") for (int m = 0; m < 4; ++m) _Pragma("unroll") for (int n = 0; n < 2; ++n) _Pragma("unroll") for (int k = 0; k < 2; ++k) \
;       acc[ai][bj][m][n] = __builtin_amdgcn_mfma_f32_16x16x32_bf16(BT[n][k], AT[m][k], acc[ai][bj][m][n], 0, 0, 0); \
;     __builtin_amdgcn_s_setprio(0); } while (0)
; #define WAIT_V(n) asm volatile("s_waitcnt vmcnt(" #n ")" ::: "memory")
; #define WAIT_L(n) asm volatile("s_waitcnt lgkmcnt(" #n ")" ::: "memory")
; #define BAR __builtin_amdgcn_s_barrier()
; #define SCHED __builtin_amdgcn_sched_barrier(0)
; #define WAIT_V(n) asm volatile("s_waitcnt vmcnt(" #n ")" ::: "memory")
; #define BAR do { __builtin_amdgcn_sched_barrier(0); __builtin_amdgcn_s_barrier(); asm volatile("" ::: "memory"); __builtin_amdgcn_sched_barrier(0); } while (0)
; template <bool SP2, bool ALIGN_EPI, bool DUAL, class Epi> DI void gemm_phase2(const bf16_t* A, const bf16_t* Bt, const bf16_t* A2, const bf16_t* Bt2, int M, int N, int K, const Epi& E, lds_t* lds) {
;     ...
;       const bool last = (t == nt - 2);
;       const char* a1 = cA + (size_t)(t + 1) * kstep;
;       const char* a2 = last ? nA : cA + (size_t)(t + 2) * kstep; const char* b2 = last ? nB : cB + (size_t)(t + 2) * kstep;
;       const char* a3 = a2 + kstep; const char* b3 = b2 + kstep;
;       if constexpr (SP2) {
;         LDB(B0, 0, 0); LDB(B1, 0, 1); SCHED; LDA(At, 0, 0); STAGE(SA(1, 1), a1 + hstep);
;         WAIT_V(8); WAIT_L(0); BAR; MMA(0, 0, At, B0); MMA(0, 1, At, B1); BAR; SCHED;
;         LDA(At, 0, 1); STAGEB(SB(0, 0), b2); STAGEB(SB(0, 1), b2 + bstep); STAGE(SA(0, 0), a2);
;         WAIT_V(8); WAIT_L(0); BAR; MMA(1, 0, At, B0); MMA(1, 1, At, B1); BAR; SCHED;
.LBB0_482:
	v_add_u32_e32 v151, s20, v141
	ds_read_b128 v[152:155], v151
	ds_read_b128 v[156:159], v151 offset:1024
	ds_read_b128 v[160:163], v151 offset:2048
	ds_read_b128 v[164:167], v151 offset:3072
	v_add_u32_e32 v151, s21, v141
	ds_read_b128 v[168:171], v151
	ds_read_b128 v[172:175], v151 offset:1024
	ds_read_b128 v[176:179], v151 offset:2048
	ds_read_b128 v[180:183], v151 offset:3072
	s_add_u32 s41, s60, 0xfffc0080
	s_addc_u32 s59, s61, -1
	s_cmp_eq_u32 s37, 12
	s_cselect_b32 s65, s2, s59
	s_cselect_b32 s64, s3, s41
	s_cselect_b32 s63, s0, s35
	s_cselect_b32 s62, s1, s34
	v_lshl_add_u64 v[220:221], s[60:61], 0, v[136:137]
	s_add_i32 m0, s9, 0xc000
	ds_read_b128 v[184:187], v149
	ds_read_b128 v[188:191], v149 offset:1024
	ds_read_b128 v[192:195], v149 offset:2048
	ds_read_b128 v[196:199], v149 offset:3072
	ds_read_b128 v[200:203], v149 offset:4096
	ds_read_b128 v[204:207], v149 offset:5120
	ds_read_b128 v[208:211], v149 offset:6144
	ds_read_b128 v[216:219], v149 offset:7168
	global_load_lds_dwordx4 v[220:221], off
	v_lshl_add_u64 v[220:221], s[60:61], 0, v[138:139]
	s_add_i32 m0, s9, 0xe000
	s_nop 0
	global_load_lds_dwordx4 v[220:221], off
	s_waitcnt vmcnt(8)
	s_waitcnt lgkmcnt(0)
	s_barrier
	s_setprio 1
	s_waitcnt lgkmcnt(0)
	v_mfma_f32_16x16x32_bf16 v[124:127], v[152:155], v[184:187], v[124:127]
	v_mfma_f32_16x16x32_bf16 v[120:123], v[160:163], v[184:187], v[120:123]
	v_mfma_f32_16x16x32_bf16 v[116:119], v[152:155], v[192:195], v[116:119]
	v_mfma_f32_16x16x32_bf16 v[112:115], v[160:163], v[192:195], v[112:115]
	v_mfma_f32_16x16x32_bf16 v[108:111], v[152:155], v[200:203], v[108:111]
	v_mfma_f32_16x16x32_bf16 v[104:107], v[160:163], v[200:203], v[104:107]
	v_mfma_f32_16x16x32_bf16 v[100:103], v[152:155], v[208:211], v[100:103]
	v_mfma_f32_16x16x32_bf16 v[96:99], v[160:163], v[208:211], v[96:99]
	v_mfma_f32_16x16x32_bf16 v[124:127], v[156:159], v[188:191], v[124:127]
	v_mfma_f32_16x16x32_bf16 v[120:123], v[164:167], v[188:191], v[120:123]
	v_mfma_f32_16x16x32_bf16 v[116:119], v[156:159], v[196:199], v[116:119]
	v_mfma_f32_16x16x32_bf16 v[112:115], v[164:167], v[196:199], v[112:115]
	v_mfma_f32_16x16x32_bf16 v[108:111], v[156:159], v[204:207], v[108:111]
	v_mfma_f32_16x16x32_bf16 v[104:107], v[164:167], v[204:207], v[104:107]
	v_mfma_f32_16x16x32_bf16 v[100:103], v[156:159], v[216:219], v[100:103]
	v_mfma_f32_16x16x32_bf16 v[96:99], v[164:167], v[216:219], v[96:99]
	v_mfma_f32_16x16x32_bf16 v[92:95], v[168:171], v[184:187], v[92:95]
	v_mfma_f32_16x16x32_bf16 v[88:91], v[176:179], v[184:187], v[88:91]
	v_mfma_f32_16x16x32_bf16 v[84:87], v[168:171], v[192:195], v[84:87]
	v_mfma_f32_16x16x32_bf16 v[80:83], v[176:179], v[192:195], v[80:83]
	v_mfma_f32_16x16x32_bf16 v[76:79], v[168:171], v[200:203], v[76:79]
	v_mfma_f32_16x16x32_bf16 v[72:75], v[176:179], v[200:203], v[72:75]
	v_mfma_f32_16x16x32_bf16 v[68:71], v[168:171], v[208:211], v[68:71]
	v_mfma_f32_16x16x32_bf16 v[64:67], v[176:179], v[208:211], v[64:67]
	v_mfma_f32_16x16x32_bf16 v[92:95], v[172:175], v[188:191], v[92:95]
	v_mfma_f32_16x16x32_bf16 v[88:91], v[180:183], v[188:191], v[88:91]
	v_mfma_f32_16x16x32_bf16 v[84:87], v[172:175], v[196:199], v[84:87]
	v_mfma_f32_16x16x32_bf16 v[80:83], v[180:183], v[196:199], v[80:83]
	v_mfma_f32_16x16x32_bf16 v[76:79], v[172:175], v[204:207], v[76:79]
	v_mfma_f32_16x16x32_bf16 v[72:75], v[180:183], v[204:207], v[72:75]
	v_mfma_f32_16x16x32_bf16 v[68:71], v[172:175], v[216:219], v[68:71]
	v_mfma_f32_16x16x32_bf16 v[64:67], v[180:183], v[216:219], v[64:67]
	s_setprio 0
	s_barrier
	s_add_i32 s41, s20, s8
	v_lshl_add_u64 v[220:221], s[62:63], 0, v[130:131]
	s_mov_b32 m0, s41
	ds_read_b128 v[184:187], v149 offset:16384
	ds_read_b128 v[188:191], v149 offset:17408
	ds_read_b128 v[192:195], v149 offset:18432
	ds_read_b128 v[196:199], v149 offset:19456
	ds_read_b128 v[200:203], v149 offset:20480
	ds_read_b128 v[204:207], v149 offset:21504
	ds_read_b128 v[208:211], v149 offset:22528
	ds_read_b128 v[216:219], v149 offset:23552
	global_load_lds_dwordx4 v[220:221], off
	s_add_i32 m0, s41, 0x2000
	s_add_u32 s66, s62, 0x10000
	v_lshl_add_u64 v[222:223], s[62:63], 0, v[134:135]
	s_addc_u32 s67, s63, 0
	s_add_i32 s41, s21, s8
	global_load_lds_dwordx4 v[222:223], off
	v_lshl_add_u64 v[224:225], s[66:67], 0, v[130:131]
	s_mov_b32 m0, s41
	v_lshl_add_u64 v[226:227], s[64:65], 0, v[132:133]
	global_load_lds_dwordx4 v[224:225], off
	v_lshl_add_u64 v[224:225], s[66:67], 0, v[134:135]
	s_add_i32 m0, s41, 0x2000
	s_nop 0
	global_load_lds_dwordx4 v[224:225], off
	v_lshl_add_u64 v[224:225], s[64:65], 0, v[128:129]
	s_mov_b32 m0, s9
	s_nop 0
	global_load_lds_dwordx4 v[224:225], off
	s_mov_b32 m0, s10
	s_nop 0
	global_load_lds_dwordx4 v[226:227], off
	s_waitcnt vmcnt(8)
	s_waitcnt lgkmcnt(0)
	s_barrier
; #define STAGE(bufoff, gbase) STAGE_(bufoff, gbase, voffA)
; #define LDA(dst, b, h) do { _Pragma("unroll") for (int m = 0; m < 4; ++m) _Pragma("unroll") for (int k = 0; k < 2; ++k) dst[m][k] = *LDSP(const bf16x8, lds + SA(b, h) + aoff + m * 2048 + k * 1024); } while (0)
; #define LDB(dst, b, h) do { _Pragma("unroll") for (int n = 0; n < 2; ++n) _Pragma("unroll") for (int k = 0; k < 2; ++k) dst[n][k] = *LDSP(const bf16x8, lds + SB(b, h) + boff + n * 2048 + k * 1024); } while (0)
; #define MMA(ai, bj, AT, BT) do { __builtin_amdgcn_s_setprio(1); \
;     _Pragma("unroll") for (int m = 0; m < 4; ++m) _Pragma("unroll") for (int n = 0; n < 2; ++n) _Pragma("unroll") for (int k = 0; k < 2; ++k) \
;       acc[ai][bj][m][n] = __builtin_amdgcn_mfma_f32_16x16x32_bf16(BT[n][k], AT[m][k], acc[ai][bj][m][n], 0, 0, 0); \
;     __builtin_amdgcn_s_setprio(0); } while (0)
; #define WAIT_V(n) asm volatile("s_waitcnt vmcnt(" #n ")" ::: "memory")
; #define WAIT_L(n) asm volatile("s_waitcnt lgkmcnt(" #n ")" ::: "memory")
; #define BAR __builtin_amdgcn_s_barrier()
; #define SCHED __builtin_amdgcn_sched_barrier(0)
; #define WAIT_V(n) asm volatile("s_waitcnt vmcnt(" #n ")" ::: "memory")
; #define BAR do { __builtin_amdgcn_sched_barrier(0); __builtin_amdgcn_s_barrier(); asm volatile("" ::: "memory"); __builtin_amdgcn_sched_barrier(0); } while (0)
; template <bool SP2, bool ALIGN_EPI, bool DUAL, class Epi> DI void gemm_phase2(const bf16_t* A, const bf16_t* Bt, const bf16_t* A2, const bf16_t* Bt2, int M, int N, int K, const Epi& E, lds_t* lds) {
;     ...
;         WAIT_V(8); WAIT_L(0); BAR; MMA(1, 0, At, B0); MMA(1, 1, At, B1); BAR; SCHED;
;         LDB(B0, 1, 0); LDB(B1, 1, 1); SCHED; LDA(At, 1, 0); STAGE(SA(0, 1), a2 + hstep);
;         WAIT_V(8); WAIT_L(0); BAR; MMA(0, 0, At, B0); MMA(0, 1, At, B1); BAR; SCHED;
	s_setprio 1
	s_waitcnt lgkmcnt(0)
	v_mfma_f32_16x16x32_bf16 v[60:63], v[152:155], v[184:187], v[60:63]
	v_mfma_f32_16x16x32_bf16 v[56:59], v[160:163], v[184:187], v[56:59]
	v_mfma_f32_16x16x32_bf16 v[52:55], v[152:155], v[192:195], v[52:55]
	v_mfma_f32_16x16x32_bf16 v[48:51], v[160:163], v[192:195], v[48:51]
	v_mfma_f32_16x16x32_bf16 v[44:47], v[152:155], v[200:203], v[44:47]
	v_mfma_f32_16x16x32_bf16 v[40:43], v[160:163], v[200:203], v[40:43]
	v_mfma_f32_16x16x32_bf16 v[36:39], v[152:155], v[208:211], v[36:39]
	v_mfma_f32_16x16x32_bf16 v[32:35], v[160:163], v[208:211], v[32:35]
	v_mfma_f32_16x16x32_bf16 v[60:63], v[156:159], v[188:191], v[60:63]
	v_mfma_f32_16x16x32_bf16 v[56:59], v[164:167], v[188:191], v[56:59]
	v_mfma_f32_16x16x32_bf16 v[52:55], v[156:159], v[196:199], v[52:55]
	v_mfma_f32_16x16x32_bf16 v[48:51], v[164:167], v[196:199], v[48:51]
	v_mfma_f32_16x16x32_bf16 v[44:47], v[156:159], v[204:207], v[44:47]
	v_mfma_f32_16x16x32_bf16 v[40:43], v[164:167], v[204:207], v[40:43]
	v_mfma_f32_16x16x32_bf16 v[36:39], v[156:159], v[216:219], v[36:39]
	v_mfma_f32_16x16x32_bf16 v[32:35], v[164:167], v[216:219], v[32:35]
	v_mfma_f32_16x16x32_bf16 v[28:31], v[168:171], v[184:187], v[28:31]
	v_mfma_f32_16x16x32_bf16 v[24:27], v[176:179], v[184:187], v[24:27]
	v_mfma_f32_16x16x32_bf16 v[20:23], v[168:171], v[192:195], v[20:23]
	v_mfma_f32_16x16x32_bf16 v[16:19], v[176:179], v[192:195], v[16:19]
	v_mfma_f32_16x16x32_bf16 v[12:15], v[168:171], v[200:203], v[12:15]
	v_mfma_f32_16x16x32_bf16 v[8:11], v[176:179], v[200:203], v[8:11]
	v_mfma_f32_16x16x32_bf16 v[4:7], v[168:171], v[208:211], v[4:7]
	v_mfma_f32_16x16x32_bf16 v[0:3], v[176:179], v[208:211], v[0:3]
	v_mfma_f32_16x16x32_bf16 v[28:31], v[172:175], v[188:191], v[28:31]
	v_mfma_f32_16x16x32_bf16 v[24:27], v[180:183], v[188:191], v[24:27]
	v_mfma_f32_16x16x32_bf16 v[20:23], v[172:175], v[196:199], v[20:23]
	v_mfma_f32_16x16x32_bf16 v[16:19], v[180:183], v[196:199], v[16:19]
	v_mfma_f32_16x16x32_bf16 v[12:15], v[172:175], v[204:207], v[12:15]
	v_mfma_f32_16x16x32_bf16 v[8:11], v[180:183], v[204:207], v[8:11]
	v_mfma_f32_16x16x32_bf16 v[4:7], v[172:175], v[216:219], v[4:7]
	v_mfma_f32_16x16x32_bf16 v[0:3], v[180:183], v[216:219], v[0:3]
	s_setprio 0
	s_barrier
	s_add_i32 s41, 0, 0x18000
	v_add_u32_e32 v151, s41, v141
	s_add_i32 s59, 0, 0x1c000
	ds_read_b128 v[152:155], v151
	ds_read_b128 v[156:159], v151 offset:1024
	ds_read_b128 v[160:163], v151 offset:2048
	ds_read_b128 v[164:167], v151 offset:3072
	v_add_u32_e32 v151, s59, v141
	ds_read_b128 v[168:171], v151
	ds_read_b128 v[172:175], v151 offset:1024
	ds_read_b128 v[176:179], v151 offset:2048
	ds_read_b128 v[180:183], v151 offset:3072
	s_add_u32 s64, s64, 0x40000
	s_addc_u32 s65, s65, 0
	s_mov_b32 m0, s11
	v_lshl_add_u64 v[228:229], s[64:65], 0, v[128:129]
	ds_read_b128 v[184:187], v149 offset:32768
	ds_read_b128 v[188:191], v149 offset:33792
	ds_read_b128 v[192:195], v149 offset:34816
	ds_read_b128 v[196:199], v149 offset:35840
	ds_read_b128 v[200:203], v149 offset:36864
	ds_read_b128 v[204:207], v149 offset:37888
	ds_read_b128 v[208:211], v149 offset:38912
	ds_read_b128 v[216:219], v149 offset:39936
	global_load_lds_dwordx4 v[228:229], off
	v_lshl_add_u64 v[228:229], s[64:65], 0, v[132:133]
	s_mov_b32 m0, s14
	s_nop 0
	global_load_lds_dwordx4 v[228:229], off
	s_waitcnt vmcnt(8)
	s_waitcnt lgkmcnt(0)
	s_barrier
	s_setprio 1
	s_waitcnt lgkmcnt(0)
	v_mfma_f32_16x16x32_bf16 v[124:127], v[152:155], v[184:187], v[124:127]
	v_mfma_f32_16x16x32_bf16 v[120:123], v[160:163], v[184:187], v[120:123]
	v_mfma_f32_16x16x32_bf16 v[116:119], v[152:155], v[192:195], v[116:119]
	v_mfma_f32_16x16x32_bf16 v[112:115], v[160:163], v[192:195], v[112:115]
	v_mfma_f32_16x16x32_bf16 v[108:111], v[152:155], v[200:203], v[108:111]
	v_mfma_f32_16x16x32_bf16 v[104:107], v[160:163], v[200:203], v[104:107]
	v_mfma_f32_16x16x32_bf16 v[100:103], v[152:155], v[208:211], v[100:103]
	v_mfma_f32_16x16x32_bf16 v[96:99], v[160:163], v[208:211], v[96:99]
	v_mfma_f32_16x16x32_bf16 v[124:127], v[156:159], v[188:191], v[124:127]
	v_mfma_f32_16x16x32_bf16 v[120:123], v[164:167], v[188:191], v[120:123]
	v_mfma_f32_16x16x32_bf16 v[116:119], v[156:159], v[196:199], v[116:119]
	v_mfma_f32_16x16x32_bf16 v[112:115], v[164:167], v[196:199], v[112:115]
	v_mfma_f32_16x16x32_bf16 v[108:111], v[156:159], v[204:207], v[108:111]
	v_mfma_f32_16x16x32_bf16 v[104:107], v[164:167], v[204:207], v[104:107]
	v_mfma_f32_16x16x32_bf16 v[100:103], v[156:159], v[216:219], v[100:103]
	v_mfma_f32_16x16x32_bf16 v[96:99], v[164:167], v[216:219], v[96:99]
	v_mfma_f32_16x16x32_bf16 v[92:95], v[168:171], v[184:187], v[92:95]
	v_mfma_f32_16x16x32_bf16 v[88:91], v[176:179], v[184:187], v[88:91]
	v_mfma_f32_16x16x32_bf16 v[84:87], v[168:171], v[192:195], v[84:87]
	v_mfma_f32_16x16x32_bf16 v[80:83], v[176:179], v[192:195], v[80:83]
	v_mfma_f32_16x16x32_bf16 v[76:79], v[168:171], v[200:203], v[76:79]
	v_mfma_f32_16x16x32_bf16 v[72:75], v[176:179], v[200:203], v[72:75]
	v_mfma_f32_16x16x32_bf16 v[68:71], v[168:171], v[208:211], v[68:71]
	v_mfma_f32_16x16x32_bf16 v[64:67], v[176:179], v[208:211], v[64:67]
	v_mfma_f32_16x16x32_bf16 v[92:95], v[172:175], v[188:191], v[92:95]
	v_mfma_f32_16x16x32_bf16 v[88:91], v[180:183], v[188:191], v[88:91]
	v_mfma_f32_16x16x32_bf16 v[84:87], v[172:175], v[196:199], v[84:87]
	v_mfma_f32_16x16x32_bf16 v[80:83], v[180:183], v[196:199], v[80:83]
	v_mfma_f32_16x16x32_bf16 v[76:79], v[172:175], v[204:207], v[76:79]
	v_mfma_f32_16x16x32_bf16 v[72:75], v[180:183], v[204:207], v[72:75]
	v_mfma_f32_16x16x32_bf16 v[68:71], v[172:175], v[216:219], v[68:71]
	v_mfma_f32_16x16x32_bf16 v[64:67], v[180:183], v[216:219], v[64:67]
	s_setprio 0
	s_barrier
; #define STAGE(bufoff, gbase) STAGE_(bufoff, gbase, voffA)
; #define STAGEB(bufoff, gbase) STAGE_(bufoff, gbase, voffB)
; #define LDA(dst, b, h) do { _Pragma("unroll") for (int m = 0; m < 4; ++m) _Pragma("unroll") for (int k = 0; k < 2; ++k) dst[m][k] = *LDSP(const bf16x8, lds + SA(b, h) + aoff + m * 2048 + k * 1024); } while (0)
; #define LDB(dst, b, h) do { _Pragma("unroll") for (int n = 0; n < 2; ++n) _Pragma("unroll") for (int k = 0; k < 2; ++k) dst[n][k] = *LDSP(const bf16x8, lds + SB(b, h) + boff + n * 2048 + k * 1024); } while (0)
; #define MMA(ai, bj, AT, BT) do { __builtin_amdgcn_s_setprio(1); \
;     _Pragma("unroll") for (int m = 0; m < 4; ++m) _Pragma("unroll") for (int n = 0; n < 2; ++n) _Pragma("unroll") for (int k = 0; k < 2; ++k) \
;       acc[ai][bj][m][n] = __builtin_amdgcn_mfma_f32_16x16x32_bf16(BT[n][k], AT[m][k], acc[ai][bj][m][n], 0, 0, 0); \
;     __builtin_amdgcn_s_setprio(0); } while (0)
; #define WAIT_V(n) asm volatile("s_waitcnt vmcnt(" #n ")" ::: "memory")
; #define WAIT_L(n) asm volatile("s_waitcnt lgkmcnt(" #n ")" ::: "memory")
; template <bool SP2, bool ALIGN_EPI, bool DUAL, class Epi> DI void gemm_phase2(const bf16_t* A, const bf16_t* Bt, const bf16_t* A2, const bf16_t* Bt2, int M, int N, int K, const Epi& E, lds_t* lds) {
;     ...
;     for (int t = 0; t < nt; t += 2) {
;       const bool last = (t == nt - 2);
;       const char* a1 = cA + (size_t)(t + 1) * kstep;
;       const char* a2 = last ? nA : cA + (size_t)(t + 2) * kstep; const char* b2 = last ? nB : cB + (size_t)(t + 2) * kstep;
;       const char* a3 = a2 + kstep; const char* b3 = b2 + kstep;
;       if constexpr (SP2) {
;         LDB(B0, 0, 0); LDB(B1, 0, 1); SCHED; LDA(At, 0, 0); STAGE(SA(1, 1), a1 + hstep);
;         WAIT_V(8); WAIT_L(0); BAR; MMA(0, 0, At, B0); MMA(0, 1, At, B1); BAR; SCHED;
;         LDA(At, 0, 1); STAGEB(SB(0, 0), b2); STAGEB(SB(0, 1), b2 + bstep); STAGE(SA(0, 0), a2);
;         WAIT_V(8); WAIT_L(0); BAR; MMA(1, 0, At, B0); MMA(1, 1, At, B1); BAR; SCHED;
;         LDB(B0, 1, 0); LDB(B1, 1, 1); SCHED; LDA(At, 1, 0); STAGE(SA(0, 1), a2 + hstep);
;         WAIT_V(8); WAIT_L(0); BAR; MMA(0, 0, At, B0); MMA(0, 1, At, B1); BAR; SCHED;
;         LDA(At, 1, 1); STAGEB(SB(1, 0), b3); STAGEB(SB(1, 1), b3 + bstep); STAGE(SA(1, 0), a3);
;         WAIT_V(8); WAIT_L(0); BAR; MMA(1, 0, At, B0); MMA(1, 1, At, B1); BAR; SCHED;
	s_add_i32 s41, s41, s8
	v_lshl_add_u64 v[220:221], v[220:221], 0, s[30:31]
	s_mov_b32 m0, s41
	ds_read_b128 v[184:187], v149 offset:49152
	ds_read_b128 v[188:191], v149 offset:50176
	ds_read_b128 v[192:195], v149 offset:51200
	ds_read_b128 v[196:199], v149 offset:52224
	ds_read_b128 v[200:203], v149 offset:53248
	ds_read_b128 v[204:207], v149 offset:54272
	ds_read_b128 v[208:211], v149 offset:55296
	ds_read_b128 v[216:219], v149 offset:56320
	global_load_lds_dwordx4 v[220:221], off
	s_add_i32 m0, s41, 0x2000
	s_add_u32 s62, s62, 0x10080
	v_lshl_add_u64 v[220:221], v[222:223], 0, s[30:31]
	s_addc_u32 s63, s63, 0
	s_add_i32 s41, s59, s8
	global_load_lds_dwordx4 v[220:221], off
	v_lshl_add_u64 v[220:221], s[62:63], 0, v[130:131]
	s_mov_b32 m0, s41
	s_nop 0
	global_load_lds_dwordx4 v[220:221], off
	v_lshl_add_u64 v[220:221], s[62:63], 0, v[134:135]
	s_add_i32 m0, s41, 0x2000
	s_nop 0
	global_load_lds_dwordx4 v[220:221], off
	v_lshl_add_u64 v[220:221], v[224:225], 0, s[30:31]
	s_mov_b32 m0, s18
	s_nop 0
	global_load_lds_dwordx4 v[220:221], off
	v_lshl_add_u64 v[220:221], v[226:227], 0, s[30:31]
	s_mov_b32 m0, s19
	s_nop 0
	global_load_lds_dwordx4 v[220:221], off
	s_waitcnt vmcnt(8)
	s_waitcnt lgkmcnt(0)
	s_barrier
	s_setprio 1
	s_waitcnt lgkmcnt(0)
	v_mfma_f32_16x16x32_bf16 v[60:63], v[152:155], v[184:187], v[60:63]
	v_mfma_f32_16x16x32_bf16 v[56:59], v[160:163], v[184:187], v[56:59]
	v_mfma_f32_16x16x32_bf16 v[52:55], v[152:155], v[192:195], v[52:55]
	v_mfma_f32_16x16x32_bf16 v[48:51], v[160:163], v[192:195], v[48:51]
	v_mfma_f32_16x16x32_bf16 v[44:47], v[152:155], v[200:203], v[44:47]
	v_mfma_f32_16x16x32_bf16 v[40:43], v[160:163], v[200:203], v[40:43]
	v_mfma_f32_16x16x32_bf16 v[36:39], v[152:155], v[208:211], v[36:39]
	v_mfma_f32_16x16x32_bf16 v[32:35], v[160:163], v[208:211], v[32:35]
	v_mfma_f32_16x16x32_bf16 v[60:63], v[156:159], v[188:191], v[60:63]
	v_mfma_f32_16x16x32_bf16 v[56:59], v[164:167], v[188:191], v[56:59]
	v_mfma_f32_16x16x32_bf16 v[52:55], v[156:159], v[196:199], v[52:55]
	v_mfma_f32_16x16x32_bf16 v[48:51], v[164:167], v[196:199], v[48:51]
	v_mfma_f32_16x16x32_bf16 v[44:47], v[156:159], v[204:207], v[44:47]
	v_mfma_f32_16x16x32_bf16 v[40:43], v[164:167], v[204:207], v[40:43]
	v_mfma_f32_16x16x32_bf16 v[36:39], v[156:159], v[216:219], v[36:39]
	v_mfma_f32_16x16x32_bf16 v[32:35], v[164:167], v[216:219], v[32:35]
	v_mfma_f32_16x16x32_bf16 v[28:31], v[168:171], v[184:187], v[28:31]
	v_mfma_f32_16x16x32_bf16 v[24:27], v[176:179], v[184:187], v[24:27]
	v_mfma_f32_16x16x32_bf16 v[20:23], v[168:171], v[192:195], v[20:23]
	v_mfma_f32_16x16x32_bf16 v[16:19], v[176:179], v[192:195], v[16:19]
	v_mfma_f32_16x16x32_bf16 v[12:15], v[168:171], v[200:203], v[12:15]
	v_mfma_f32_16x16x32_bf16 v[8:11], v[176:179], v[200:203], v[8:11]
	v_mfma_f32_16x16x32_bf16 v[4:7], v[168:171], v[208:211], v[4:7]
	v_mfma_f32_16x16x32_bf16 v[0:3], v[176:179], v[208:211], v[0:3]
	v_mfma_f32_16x16x32_bf16 v[28:31], v[172:175], v[188:191], v[28:31]
	v_mfma_f32_16x16x32_bf16 v[24:27], v[180:183], v[188:191], v[24:27]
	v_mfma_f32_16x16x32_bf16 v[20:23], v[172:175], v[196:199], v[20:23]
	v_mfma_f32_16x16x32_bf16 v[16:19], v[180:183], v[196:199], v[16:19]
	v_mfma_f32_16x16x32_bf16 v[12:15], v[172:175], v[204:207], v[12:15]
	v_mfma_f32_16x16x32_bf16 v[8:11], v[180:183], v[204:207], v[8:11]
	v_mfma_f32_16x16x32_bf16 v[4:7], v[172:175], v[216:219], v[4:7]
	v_mfma_f32_16x16x32_bf16 v[0:3], v[180:183], v[216:219], v[0:3]
	s_setprio 0
	s_barrier
	s_add_i32 s37, s37, 2
	s_add_u32 s60, s60, 0x100
	s_addc_u32 s61, s61, 0
	s_add_u32 s34, s34, 0x100
	s_addc_u32 s35, s35, 0
	s_cmp_gt_u32 s37, 13
	s_cbranch_scc0 .LBB0_482
	s_and_b64 vcc, exec, s[38:39]
	s_cbranch_vccz .LBB0_485
	s_barrier

; #define STAGE(bufoff, gbase) STAGE_(bufoff, gbase, voffA)
; #define STAGEB(bufoff, gbase) STAGE_(bufoff, gbase, voffB)
; #define LDA(dst, b, h) do { _Pragma("unroll") for (int m = 0; m < 4; ++m) _Pragma("unroll") for (int k = 0; k < 2; ++k) dst[m][k] = *LDSP(const bf16x8, lds + SA(b, h) + aoff + m * 2048 + k * 1024); } while (0)
; #define LDB(dst, b, h) do { _Pragma("unroll") for (int n = 0; n < 2; ++n) _Pragma("unroll") for (int k = 0; k < 2; ++k) dst[n][k] = *LDSP(const bf16x8, lds + SB(b, h) + boff + n * 2048 + k * 1024); } while (0)
; #define MMA(ai, bj, AT, BT) do { __builtin_amdgcn_s_setprio(1); \
;     _Pragma("unroll") for (int m = 0; m < 4; ++m) _Pragma("unroll") for (int n = 0; n < 2; ++n) _Pragma("unroll") for (int k = 0; k < 2; ++k) \
;       acc[ai][bj][m][n] = __builtin_amdgcn_mfma_f32_16x16x32_bf16(BT[n][k], AT[m][k], acc[ai][bj][m][n], 0, 0, 0); \
;     __builtin_amdgcn_s_setprio(0); } while (0)
; #define WAIT_V(n) asm volatile("s_waitcnt vmcnt(" #n ")" ::: "memory")
; #define WAIT_L(n) asm volatile("s_waitcnt lgkmcnt(" #n ")" ::: "memory")
; #define BAR __builtin_amdgcn_s_barrier()
; #define SCHED __builtin_amdgcn_sched_barrier(0)
; #define WAIT_V(n) asm volatile("s_waitcnt vmcnt(" #n ")" ::: "memory")
; #define BAR do { __builtin_amdgcn_sched_barrier(0); __builtin_amdgcn_s_barrier(); asm volatile("" ::: "memory"); __builtin_amdgcn_sched_barrier(0); } while (0)
; template <bool SP2, bool ALIGN_EPI, bool DUAL, class Epi> DI void gemm_phase2(const bf16_t* A, const bf16_t* Bt, const bf16_t* A2, const bf16_t* Bt2, int M, int N, int K, const Epi& E, lds_t* lds) {
;     ...
;       const bool last = (t == nt - 2);
;       const char* a1 = cA + (size_t)(t + 1) * kstep;
;       const char* a2 = last ? nA : cA + (size_t)(t + 2) * kstep; const char* b2 = last ? nB : cB + (size_t)(t + 2) * kstep;
;       const char* a3 = a2 + kstep; const char* b3 = b2 + kstep;
;       if constexpr (SP2) {
;         LDB(B0, 0, 0); LDB(B1, 0, 1); SCHED; LDA(At, 0, 0); STAGE(SA(1, 1), a1 + hstep);
;         WAIT_V(8); WAIT_L(0); BAR; MMA(0, 0, At, B0); MMA(0, 1, At, B1); BAR; SCHED;
;         LDA(At, 0, 1); STAGEB(SB(0, 0), b2); STAGEB(SB(0, 1), b2 + bstep); STAGE(SA(0, 0), a2);
;         WAIT_V(8); WAIT_L(0); BAR; MMA(1, 0, At, B0); MMA(1, 1, At, B1); BAR; SCHED;
.LBB0_551:
	ds_read_b128 v[152:155], v148
	ds_read_b128 v[156:159], v148 offset:1024
	ds_read_b128 v[160:163], v148 offset:2048
	ds_read_b128 v[164:167], v148 offset:3072
	ds_read_b128 v[168:171], v149
	ds_read_b128 v[172:175], v149 offset:1024
	ds_read_b128 v[176:179], v149 offset:2048
	ds_read_b128 v[180:183], v149 offset:3072
	s_add_u32 s35, s60, 0xfffc0080
	s_addc_u32 s37, s61, -1
	s_cmp_eq_u32 s34, 12
	s_cselect_b32 s65, s0, s37
	s_cselect_b32 s64, s1, s35
	s_cselect_b32 s63, s21, s33
	s_cselect_b32 s62, s22, s23
	v_lshl_add_u64 v[140:141], s[60:61], 0, v[136:137]
	s_add_i32 m0, s3, 0xc000
	ds_read_b128 v[184:187], v150
	ds_read_b128 v[188:191], v150 offset:1024
	ds_read_b128 v[192:195], v150 offset:2048
	ds_read_b128 v[196:199], v150 offset:3072
	ds_read_b128 v[200:203], v150 offset:4096
	ds_read_b128 v[204:207], v150 offset:5120
	ds_read_b128 v[208:211], v150 offset:6144
	ds_read_b128 v[216:219], v150 offset:7168
	global_load_lds_dwordx4 v[140:141], off
	v_lshl_add_u64 v[140:141], s[60:61], 0, v[138:139]
	s_add_i32 m0, s3, 0xe000
	s_nop 0
	global_load_lds_dwordx4 v[140:141], off
	s_waitcnt vmcnt(8)
	s_waitcnt lgkmcnt(0)
	s_barrier
	s_setprio 1
	s_waitcnt lgkmcnt(0)
	v_mfma_f32_16x16x32_bf16 v[124:127], v[152:155], v[184:187], v[124:127]
	v_mfma_f32_16x16x32_bf16 v[120:123], v[160:163], v[184:187], v[120:123]
	v_mfma_f32_16x16x32_bf16 v[108:111], v[152:155], v[192:195], v[108:111]
	v_mfma_f32_16x16x32_bf16 v[104:107], v[160:163], v[192:195], v[104:107]
	v_mfma_f32_16x16x32_bf16 v[92:95], v[152:155], v[200:203], v[92:95]
	v_mfma_f32_16x16x32_bf16 v[88:91], v[160:163], v[200:203], v[88:91]
	v_mfma_f32_16x16x32_bf16 v[76:79], v[152:155], v[208:211], v[76:79]
	v_mfma_f32_16x16x32_bf16 v[72:75], v[160:163], v[208:211], v[72:75]
	v_mfma_f32_16x16x32_bf16 v[124:127], v[156:159], v[188:191], v[124:127]
	v_mfma_f32_16x16x32_bf16 v[120:123], v[164:167], v[188:191], v[120:123]
	v_mfma_f32_16x16x32_bf16 v[108:111], v[156:159], v[196:199], v[108:111]
	v_mfma_f32_16x16x32_bf16 v[104:107], v[164:167], v[196:199], v[104:107]
	v_mfma_f32_16x16x32_bf16 v[92:95], v[156:159], v[204:207], v[92:95]
	v_mfma_f32_16x16x32_bf16 v[88:91], v[164:167], v[204:207], v[88:91]
	v_mfma_f32_16x16x32_bf16 v[76:79], v[156:159], v[216:219], v[76:79]
	v_mfma_f32_16x16x32_bf16 v[72:75], v[164:167], v[216:219], v[72:75]
	v_mfma_f32_16x16x32_bf16 v[116:119], v[168:171], v[184:187], v[116:119]
	v_mfma_f32_16x16x32_bf16 v[112:115], v[176:179], v[184:187], v[112:115]
	v_mfma_f32_16x16x32_bf16 v[100:103], v[168:171], v[192:195], v[100:103]
	v_mfma_f32_16x16x32_bf16 v[96:99], v[176:179], v[192:195], v[96:99]
	v_mfma_f32_16x16x32_bf16 v[84:87], v[168:171], v[200:203], v[84:87]
	v_mfma_f32_16x16x32_bf16 v[80:83], v[176:179], v[200:203], v[80:83]
	v_mfma_f32_16x16x32_bf16 v[68:71], v[168:171], v[208:211], v[68:71]
	v_mfma_f32_16x16x32_bf16 v[64:67], v[176:179], v[208:211], v[64:67]
	v_mfma_f32_16x16x32_bf16 v[116:119], v[172:175], v[188:191], v[116:119]
	v_mfma_f32_16x16x32_bf16 v[112:115], v[180:183], v[188:191], v[112:115]
	v_mfma_f32_16x16x32_bf16 v[100:103], v[172:175], v[196:199], v[100:103]
	v_mfma_f32_16x16x32_bf16 v[96:99], v[180:183], v[196:199], v[96:99]
	v_mfma_f32_16x16x32_bf16 v[84:87], v[172:175], v[204:207], v[84:87]
	v_mfma_f32_16x16x32_bf16 v[80:83], v[180:183], v[204:207], v[80:83]
	v_mfma_f32_16x16x32_bf16 v[68:71], v[172:175], v[216:219], v[68:71]
	v_mfma_f32_16x16x32_bf16 v[64:67], v[180:183], v[216:219], v[64:67]
	s_setprio 0
	s_barrier
	s_add_i32 s35, s18, s2
	v_lshl_add_u64 v[140:141], s[62:63], 0, v[130:131]
	s_mov_b32 m0, s35
	ds_read_b128 v[184:187], v150 offset:16384
	ds_read_b128 v[188:191], v150 offset:17408
	ds_read_b128 v[192:195], v150 offset:18432
	ds_read_b128 v[196:199], v150 offset:19456
	ds_read_b128 v[200:203], v150 offset:20480
	ds_read_b128 v[204:207], v150 offset:21504
	ds_read_b128 v[208:211], v150 offset:22528
	ds_read_b128 v[216:219], v150 offset:23552
	global_load_lds_dwordx4 v[140:141], off
	s_add_i32 m0, s35, 0x2000
	s_add_u32 s66, s62, 0x10000
	v_lshl_add_u64 v[220:221], s[62:63], 0, v[134:135]
	s_addc_u32 s67, s63, 0
	s_add_i32 s35, s19, s2
	global_load_lds_dwordx4 v[220:221], off
	v_lshl_add_u64 v[222:223], s[66:67], 0, v[130:131]
	s_mov_b32 m0, s35
	v_lshl_add_u64 v[224:225], s[64:65], 0, v[132:133]
	global_load_lds_dwordx4 v[222:223], off
	v_lshl_add_u64 v[222:223], s[66:67], 0, v[134:135]
	s_add_i32 m0, s35, 0x2000
	s_nop 0
	global_load_lds_dwordx4 v[222:223], off
	v_lshl_add_u64 v[222:223], s[64:65], 0, v[128:129]
	s_mov_b32 m0, s3
	s_nop 0
	global_load_lds_dwordx4 v[222:223], off
	s_mov_b32 m0, s8
	s_nop 0
	global_load_lds_dwordx4 v[224:225], off
	s_waitcnt vmcnt(8)
	s_waitcnt lgkmcnt(0)
	s_barrier
; #define STAGE(bufoff, gbase) STAGE_(bufoff, gbase, voffA)
; #define LDA(dst, b, h) do { _Pragma("unroll") for (int m = 0; m < 4; ++m) _Pragma("unroll") for (int k = 0; k < 2; ++k) dst[m][k] = *LDSP(const bf16x8, lds + SA(b, h) + aoff + m * 2048 + k * 1024); } while (0)
; #define LDB(dst, b, h) do { _Pragma("unroll") for (int n = 0; n < 2; ++n) _Pragma("unroll") for (int k = 0; k < 2; ++k) dst[n][k] = *LDSP(const bf16x8, lds + SB(b, h) + boff + n * 2048 + k * 1024); } while (0)
; #define MMA(ai, bj, AT, BT) do { __builtin_amdgcn_s_setprio(1); \
;     _Pragma("unroll") for (int m = 0; m < 4; ++m) _Pragma("unroll") for (int n = 0; n < 2; ++n) _Pragma("unroll") for (int k = 0; k < 2; ++k) \
;       acc[ai][bj][m][n] = __builtin_amdgcn_mfma_f32_16x16x32_bf16(BT[n][k], AT[m][k], acc[ai][bj][m][n], 0, 0, 0); \
;     __builtin_amdgcn_s_setprio(0); } while (0)
; #define WAIT_V(n) asm volatile("s_waitcnt vmcnt(" #n ")" ::: "memory")
; #define WAIT_L(n) asm volatile("s_waitcnt lgkmcnt(" #n ")" ::: "memory")
; #define BAR __builtin_amdgcn_s_barrier()
; #define SCHED __builtin_amdgcn_sched_barrier(0)
; #define WAIT_V(n) asm volatile("s_waitcnt vmcnt(" #n ")" ::: "memory")
; #define BAR do { __builtin_amdgcn_sched_barrier(0); __builtin_amdgcn_s_barrier(); asm volatile("" ::: "memory"); __builtin_amdgcn_sched_barrier(0); } while (0)
; template <bool SP2, bool ALIGN_EPI, bool DUAL, class Epi> DI void gemm_phase2(const bf16_t* A, const bf16_t* Bt, const bf16_t* A2, const bf16_t* Bt2, int M, int N, int K, const Epi& E, lds_t* lds) {
;     ...
;         WAIT_V(8); WAIT_L(0); BAR; MMA(1, 0, At, B0); MMA(1, 1, At, B1); BAR; SCHED;
;         LDB(B0, 1, 0); LDB(B1, 1, 1); SCHED; LDA(At, 1, 0); STAGE(SA(0, 1), a2 + hstep);
;         WAIT_V(8); WAIT_L(0); BAR; MMA(0, 0, At, B0); MMA(0, 1, At, B1); BAR; SCHED;
	s_setprio 1
	s_waitcnt lgkmcnt(0)
	v_mfma_f32_16x16x32_bf16 v[60:63], v[152:155], v[184:187], v[60:63]
	v_mfma_f32_16x16x32_bf16 v[56:59], v[160:163], v[184:187], v[56:59]
	v_mfma_f32_16x16x32_bf16 v[44:47], v[152:155], v[192:195], v[44:47]
	v_mfma_f32_16x16x32_bf16 v[40:43], v[160:163], v[192:195], v[40:43]
	v_mfma_f32_16x16x32_bf16 v[28:31], v[152:155], v[200:203], v[28:31]
	v_mfma_f32_16x16x32_bf16 v[24:27], v[160:163], v[200:203], v[24:27]
	v_mfma_f32_16x16x32_bf16 v[12:15], v[152:155], v[208:211], v[12:15]
	v_mfma_f32_16x16x32_bf16 v[8:11], v[160:163], v[208:211], v[8:11]
	v_mfma_f32_16x16x32_bf16 v[60:63], v[156:159], v[188:191], v[60:63]
	v_mfma_f32_16x16x32_bf16 v[56:59], v[164:167], v[188:191], v[56:59]
	v_mfma_f32_16x16x32_bf16 v[44:47], v[156:159], v[196:199], v[44:47]
	v_mfma_f32_16x16x32_bf16 v[40:43], v[164:167], v[196:199], v[40:43]
	v_mfma_f32_16x16x32_bf16 v[28:31], v[156:159], v[204:207], v[28:31]
	v_mfma_f32_16x16x32_bf16 v[24:27], v[164:167], v[204:207], v[24:27]
	v_mfma_f32_16x16x32_bf16 v[12:15], v[156:159], v[216:219], v[12:15]
	v_mfma_f32_16x16x32_bf16 v[8:11], v[164:167], v[216:219], v[8:11]
	v_mfma_f32_16x16x32_bf16 v[52:55], v[168:171], v[184:187], v[52:55]
	v_mfma_f32_16x16x32_bf16 v[48:51], v[176:179], v[184:187], v[48:51]
	v_mfma_f32_16x16x32_bf16 v[36:39], v[168:171], v[192:195], v[36:39]
	v_mfma_f32_16x16x32_bf16 v[32:35], v[176:179], v[192:195], v[32:35]
	v_mfma_f32_16x16x32_bf16 v[20:23], v[168:171], v[200:203], v[20:23]
	v_mfma_f32_16x16x32_bf16 v[16:19], v[176:179], v[200:203], v[16:19]
	v_mfma_f32_16x16x32_bf16 v[4:7], v[168:171], v[208:211], v[4:7]
	v_mfma_f32_16x16x32_bf16 v[0:3], v[176:179], v[208:211], v[0:3]
	v_mfma_f32_16x16x32_bf16 v[52:55], v[172:175], v[188:191], v[52:55]
	v_mfma_f32_16x16x32_bf16 v[48:51], v[180:183], v[188:191], v[48:51]
	v_mfma_f32_16x16x32_bf16 v[36:39], v[172:175], v[196:199], v[36:39]
	v_mfma_f32_16x16x32_bf16 v[32:35], v[180:183], v[196:199], v[32:35]
	v_mfma_f32_16x16x32_bf16 v[20:23], v[172:175], v[204:207], v[20:23]
	v_mfma_f32_16x16x32_bf16 v[16:19], v[180:183], v[204:207], v[16:19]
	v_mfma_f32_16x16x32_bf16 v[4:7], v[172:175], v[216:219], v[4:7]
	v_mfma_f32_16x16x32_bf16 v[0:3], v[180:183], v[216:219], v[0:3]
	s_setprio 0
	s_barrier
	s_add_i32 s35, 0, 0x18000
	s_add_i32 s37, 0, 0x1c000
	v_add_u32_e32 v164, s35, v143
	v_add_u32_e32 v180, s37, v143
	ds_read_b128 v[152:155], v164
	ds_read_b128 v[156:159], v164 offset:1024
	ds_read_b128 v[160:163], v164 offset:2048
	ds_read_b128 v[164:167], v164 offset:3072
	ds_read_b128 v[168:171], v180
	ds_read_b128 v[172:175], v180 offset:1024
	ds_read_b128 v[176:179], v180 offset:2048
	ds_read_b128 v[180:183], v180 offset:3072
	s_add_u32 s64, s64, 0x40000
	s_addc_u32 s65, s65, 0
	s_mov_b32 m0, s9
	v_lshl_add_u64 v[226:227], s[64:65], 0, v[128:129]
	ds_read_b128 v[184:187], v150 offset:32768
	ds_read_b128 v[188:191], v150 offset:33792
	ds_read_b128 v[192:195], v150 offset:34816
	ds_read_b128 v[196:199], v150 offset:35840
	ds_read_b128 v[200:203], v150 offset:36864
	ds_read_b128 v[204:207], v150 offset:37888
	ds_read_b128 v[208:211], v150 offset:38912
	ds_read_b128 v[216:219], v150 offset:39936
	global_load_lds_dwordx4 v[226:227], off
	v_lshl_add_u64 v[226:227], s[64:65], 0, v[132:133]
	s_mov_b32 m0, s10
	s_nop 0
	global_load_lds_dwordx4 v[226:227], off
	s_waitcnt vmcnt(8)
	s_waitcnt lgkmcnt(0)
	s_barrier
	s_setprio 1
	s_waitcnt lgkmcnt(0)
	v_mfma_f32_16x16x32_bf16 v[124:127], v[152:155], v[184:187], v[124:127]
	v_mfma_f32_16x16x32_bf16 v[120:123], v[160:163], v[184:187], v[120:123]
	v_mfma_f32_16x16x32_bf16 v[108:111], v[152:155], v[192:195], v[108:111]
	v_mfma_f32_16x16x32_bf16 v[104:107], v[160:163], v[192:195], v[104:107]
	v_mfma_f32_16x16x32_bf16 v[92:95], v[152:155], v[200:203], v[92:95]
	v_mfma_f32_16x16x32_bf16 v[88:91], v[160:163], v[200:203], v[88:91]
	v_mfma_f32_16x16x32_bf16 v[76:79], v[152:155], v[208:211], v[76:79]
	v_mfma_f32_16x16x32_bf16 v[72:75], v[160:163], v[208:211], v[72:75]
	v_mfma_f32_16x16x32_bf16 v[124:127], v[156:159], v[188:191], v[124:127]
	v_mfma_f32_16x16x32_bf16 v[120:123], v[164:167], v[188:191], v[120:123]
	v_mfma_f32_16x16x32_bf16 v[108:111], v[156:159], v[196:199], v[108:111]
	v_mfma_f32_16x16x32_bf16 v[104:107], v[164:167], v[196:199], v[104:107]
	v_mfma_f32_16x16x32_bf16 v[92:95], v[156:159], v[204:207], v[92:95]
	v_mfma_f32_16x16x32_bf16 v[88:91], v[164:167], v[204:207], v[88:91]
	v_mfma_f32_16x16x32_bf16 v[76:79], v[156:159], v[216:219], v[76:79]
	v_mfma_f32_16x16x32_bf16 v[72:75], v[164:167], v[216:219], v[72:75]
	v_mfma_f32_16x16x32_bf16 v[116:119], v[168:171], v[184:187], v[116:119]
	v_mfma_f32_16x16x32_bf16 v[112:115], v[176:179], v[184:187], v[112:115]
	v_mfma_f32_16x16x32_bf16 v[100:103], v[168:171], v[192:195], v[100:103]
	v_mfma_f32_16x16x32_bf16 v[96:99], v[176:179], v[192:195], v[96:99]
	v_mfma_f32_16x16x32_bf16 v[84:87], v[168:171], v[200:203], v[84:87]
	v_mfma_f32_16x16x32_bf16 v[80:83], v[176:179], v[200:203], v[80:83]
	v_mfma_f32_16x16x32_bf16 v[68:71], v[168:171], v[208:211], v[68:71]
	v_mfma_f32_16x16x32_bf16 v[64:67], v[176:179], v[208:211], v[64:67]
	v_mfma_f32_16x16x32_bf16 v[116:119], v[172:175], v[188:191], v[116:119]
	v_mfma_f32_16x16x32_bf16 v[112:115], v[180:183], v[188:191], v[112:115]
	v_mfma_f32_16x16x32_bf16 v[100:103], v[172:175], v[196:199], v[100:103]
	v_mfma_f32_16x16x32_bf16 v[96:99], v[180:183], v[196:199], v[96:99]
	v_mfma_f32_16x16x32_bf16 v[84:87], v[172:175], v[204:207], v[84:87]
	v_mfma_f32_16x16x32_bf16 v[80:83], v[180:183], v[204:207], v[80:83]
	v_mfma_f32_16x16x32_bf16 v[68:71], v[172:175], v[216:219], v[68:71]
	v_mfma_f32_16x16x32_bf16 v[64:67], v[180:183], v[216:219], v[64:67]
	s_setprio 0
	s_barrier
; #define STAGE(bufoff, gbase) STAGE_(bufoff, gbase, voffA)
; #define STAGEB(bufoff, gbase) STAGE_(bufoff, gbase, voffB)
; #define LDA(dst, b, h) do { _Pragma("unroll") for (int m = 0; m < 4; ++m) _Pragma("unroll") for (int k = 0; k < 2; ++k) dst[m][k] = *LDSP(const bf16x8, lds + SA(b, h) + aoff + m * 2048 + k * 1024); } while (0)
; #define LDB(dst, b, h) do { _Pragma("unroll") for (int n = 0; n < 2; ++n) _Pragma("unroll") for (int k = 0; k < 2; ++k) dst[n][k] = *LDSP(const bf16x8, lds + SB(b, h) + boff + n * 2048 + k * 1024); } while (0)
; #define MMA(ai, bj, AT, BT) do { __builtin_amdgcn_s_setprio(1); \
;     _Pragma("unroll") for (int m = 0; m < 4; ++m) _Pragma("unroll") for (int n = 0; n < 2; ++n) _Pragma("unroll") for (int k = 0; k < 2; ++k) \
;       acc[ai][bj][m][n] = __builtin_amdgcn_mfma_f32_16x16x32_bf16(BT[n][k], AT[m][k], acc[ai][bj][m][n], 0, 0, 0); \
;     __builtin_amdgcn_s_setprio(0); } while (0)
; #define WAIT_V(n) asm volatile("s_waitcnt vmcnt(" #n ")" ::: "memory")
; #define WAIT_L(n) asm volatile("s_waitcnt lgkmcnt(" #n ")" ::: "memory")
; template <bool SP2, bool ALIGN_EPI, bool DUAL, class Epi> DI void gemm_phase2(const bf16_t* A, const bf16_t* Bt, const bf16_t* A2, const bf16_t* Bt2, int M, int N, int K, const Epi& E, lds_t* lds) {
;     ...
;     for (int t = 0; t < nt; t += 2) {
;       const bool last = (t == nt - 2);
;       const char* a1 = cA + (size_t)(t + 1) * kstep;
;       const char* a2 = last ? nA : cA + (size_t)(t + 2) * kstep; const char* b2 = last ? nB : cB + (size_t)(t + 2) * kstep;
;       const char* a3 = a2 + kstep; const char* b3 = b2 + kstep;
;       if constexpr (SP2) {
;         LDB(B0, 0, 0); LDB(B1, 0, 1); SCHED; LDA(At, 0, 0); STAGE(SA(1, 1), a1 + hstep);
;         WAIT_V(8); WAIT_L(0); BAR; MMA(0, 0, At, B0); MMA(0, 1, At, B1); BAR; SCHED;
;         LDA(At, 0, 1); STAGEB(SB(0, 0), b2); STAGEB(SB(0, 1), b2 + bstep); STAGE(SA(0, 0), a2);
;         WAIT_V(8); WAIT_L(0); BAR; MMA(1, 0, At, B0); MMA(1, 1, At, B1); BAR; SCHED;
;         LDB(B0, 1, 0); LDB(B1, 1, 1); SCHED; LDA(At, 1, 0); STAGE(SA(0, 1), a2 + hstep);
;         WAIT_V(8); WAIT_L(0); BAR; MMA(0, 0, At, B0); MMA(0, 1, At, B1); BAR; SCHED;
;         LDA(At, 1, 1); STAGEB(SB(1, 0), b3); STAGEB(SB(1, 1), b3 + bstep); STAGE(SA(1, 0), a3);
;         WAIT_V(8); WAIT_L(0); BAR; MMA(1, 0, At, B0); MMA(1, 1, At, B1); BAR; SCHED;
	s_add_i32 s35, s35, s2
	v_lshl_add_u64 v[140:141], v[140:141], 0, s[30:31]
	s_mov_b32 m0, s35
	ds_read_b128 v[184:187], v150 offset:49152
	ds_read_b128 v[188:191], v150 offset:50176
	ds_read_b128 v[192:195], v150 offset:51200
	ds_read_b128 v[196:199], v150 offset:52224
	ds_read_b128 v[200:203], v150 offset:53248
	ds_read_b128 v[204:207], v150 offset:54272
	ds_read_b128 v[208:211], v150 offset:55296
	ds_read_b128 v[216:219], v150 offset:56320
	global_load_lds_dwordx4 v[140:141], off
	s_add_i32 m0, s35, 0x2000
	s_add_u32 s62, s62, 0x10080
	v_lshl_add_u64 v[140:141], v[220:221], 0, s[30:31]
	s_addc_u32 s63, s63, 0
	s_add_i32 s35, s37, s2
	global_load_lds_dwordx4 v[140:141], off
	v_lshl_add_u64 v[140:141], s[62:63], 0, v[130:131]
	s_mov_b32 m0, s35
	s_nop 0
	global_load_lds_dwordx4 v[140:141], off
	v_lshl_add_u64 v[140:141], s[62:63], 0, v[134:135]
	s_add_i32 m0, s35, 0x2000
	s_nop 0
	global_load_lds_dwordx4 v[140:141], off
	v_lshl_add_u64 v[140:141], v[222:223], 0, s[30:31]
	s_mov_b32 m0, s14
	s_nop 0
	global_load_lds_dwordx4 v[140:141], off
	v_lshl_add_u64 v[140:141], v[224:225], 0, s[30:31]
	s_mov_b32 m0, s15
	s_nop 0
	global_load_lds_dwordx4 v[140:141], off
	s_waitcnt vmcnt(8)
	s_waitcnt lgkmcnt(0)
	s_barrier
	s_setprio 1
	s_waitcnt lgkmcnt(0)
	v_mfma_f32_16x16x32_bf16 v[60:63], v[152:155], v[184:187], v[60:63]
	v_mfma_f32_16x16x32_bf16 v[56:59], v[160:163], v[184:187], v[56:59]
	v_mfma_f32_16x16x32_bf16 v[44:47], v[152:155], v[192:195], v[44:47]
	v_mfma_f32_16x16x32_bf16 v[40:43], v[160:163], v[192:195], v[40:43]
	v_mfma_f32_16x16x32_bf16 v[28:31], v[152:155], v[200:203], v[28:31]
	v_mfma_f32_16x16x32_bf16 v[24:27], v[160:163], v[200:203], v[24:27]
	v_mfma_f32_16x16x32_bf16 v[12:15], v[152:155], v[208:211], v[12:15]
	v_mfma_f32_16x16x32_bf16 v[8:11], v[160:163], v[208:211], v[8:11]
	v_mfma_f32_16x16x32_bf16 v[60:63], v[156:159], v[188:191], v[60:63]
	v_mfma_f32_16x16x32_bf16 v[56:59], v[164:167], v[188:191], v[56:59]
	v_mfma_f32_16x16x32_bf16 v[44:47], v[156:159], v[196:199], v[44:47]
	v_mfma_f32_16x16x32_bf16 v[40:43], v[164:167], v[196:199], v[40:43]
	v_mfma_f32_16x16x32_bf16 v[28:31], v[156:159], v[204:207], v[28:31]
	v_mfma_f32_16x16x32_bf16 v[24:27], v[164:167], v[204:207], v[24:27]
	v_mfma_f32_16x16x32_bf16 v[12:15], v[156:159], v[216:219], v[12:15]
	v_mfma_f32_16x16x32_bf16 v[8:11], v[164:167], v[216:219], v[8:11]
	v_mfma_f32_16x16x32_bf16 v[52:55], v[168:171], v[184:187], v[52:55]
	v_mfma_f32_16x16x32_bf16 v[48:51], v[176:179], v[184:187], v[48:51]
	v_mfma_f32_16x16x32_bf16 v[36:39], v[168:171], v[192:195], v[36:39]
	v_mfma_f32_16x16x32_bf16 v[32:35], v[176:179], v[192:195], v[32:35]
	v_mfma_f32_16x16x32_bf16 v[20:23], v[168:171], v[200:203], v[20:23]
	v_mfma_f32_16x16x32_bf16 v[16:19], v[176:179], v[200:203], v[16:19]
	v_mfma_f32_16x16x32_bf16 v[4:7], v[168:171], v[208:211], v[4:7]
	v_mfma_f32_16x16x32_bf16 v[0:3], v[176:179], v[208:211], v[0:3]
	v_mfma_f32_16x16x32_bf16 v[52:55], v[172:175], v[188:191], v[52:55]
	v_mfma_f32_16x16x32_bf16 v[48:51], v[180:183], v[188:191], v[48:51]
	v_mfma_f32_16x16x32_bf16 v[36:39], v[172:175], v[196:199], v[36:39]
	v_mfma_f32_16x16x32_bf16 v[32:35], v[180:183], v[196:199], v[32:35]
	v_mfma_f32_16x16x32_bf16 v[20:23], v[172:175], v[204:207], v[20:23]
	v_mfma_f32_16x16x32_bf16 v[16:19], v[180:183], v[204:207], v[16:19]
	v_mfma_f32_16x16x32_bf16 v[4:7], v[172:175], v[216:219], v[4:7]
	v_mfma_f32_16x16x32_bf16 v[0:3], v[180:183], v[216:219], v[0:3]
	s_setprio 0
	s_barrier
	s_add_i32 s34, s34, 2
	s_add_u32 s60, s60, 0x100
	s_addc_u32 s61, s61, 0
	s_add_u32 s23, s23, 0x100
	s_addc_u32 s33, s33, 0
	s_cmp_gt_u32 s34, 13
	s_cbranch_scc0 .LBB0_551
	s_and_b64 vcc, exec, s[38:39]
	s_cbranch_vccz .LBB0_554
	s_barrier

; #define STAGE(bufoff, gbase) STAGE_(bufoff, gbase, voffA)
; #define STAGEB(bufoff, gbase) STAGE_(bufoff, gbase, voffB)
; #define LDA(dst, b, h) do { _Pragma("unroll") for (int m = 0; m < 4; ++m) _Pragma("unroll") for (int k = 0; k < 2; ++k) dst[m][k] = *LDSP(const bf16x8, lds + SA(b, h) + aoff + m * 2048 + k * 1024); } while (0)
; #define LDB(dst, b, h) do { _Pragma("unroll") for (int n = 0; n < 2; ++n) _Pragma("unroll") for (int k = 0; k < 2; ++k) dst[n][k] = *LDSP(const bf16x8, lds + SB(b, h) + boff + n * 2048 + k * 1024); } while (0)
; #define MMA(ai, bj, AT, BT) do { __builtin_amdgcn_s_setprio(1); \
;     _Pragma("unroll") for (int m = 0; m < 4; ++m) _Pragma("unroll") for (int n = 0; n < 2; ++n) _Pragma("unroll") for (int k = 0; k < 2; ++k) \
;       acc[ai][bj][m][n] = __builtin_amdgcn_mfma_f32_16x16x32_bf16(BT[n][k], AT[m][k], acc[ai][bj][m][n], 0, 0, 0); \
;     __builtin_amdgcn_s_setprio(0); } while (0)
; #define WAIT_V(n) asm volatile("s_waitcnt vmcnt(" #n ")" ::: "memory")
; #define WAIT_L(n) asm volatile("s_waitcnt lgkmcnt(" #n ")" ::: "memory")
; #define BAR __builtin_amdgcn_s_barrier()
; #define SCHED __builtin_amdgcn_sched_barrier(0)
; #define WAIT_V(n) asm volatile("s_waitcnt vmcnt(" #n ")" ::: "memory")
; #define BAR do { __builtin_amdgcn_sched_barrier(0); __builtin_amdgcn_s_barrier(); asm volatile("" ::: "memory"); __builtin_amdgcn_sched_barrier(0); } while (0)
; template <bool SP2, bool ALIGN_EPI, bool DUAL, class Epi> DI void gemm_phase2(const bf16_t* A, const bf16_t* Bt, const bf16_t* A2, const bf16_t* Bt2, int M, int N, int K, const Epi& E, lds_t* lds) {
;     ...
;       const bool last = (t == nt - 2);
;       const char* a1 = cA + (size_t)(t + 1) * kstep;
;       const char* a2 = last ? nA : cA + (size_t)(t + 2) * kstep; const char* b2 = last ? nB : cB + (size_t)(t + 2) * kstep;
;       const char* a3 = a2 + kstep; const char* b3 = b2 + kstep;
;       if constexpr (SP2) {
;         LDB(B0, 0, 0); LDB(B1, 0, 1); SCHED; LDA(At, 0, 0); STAGE(SA(1, 1), a1 + hstep);
;         WAIT_V(8); WAIT_L(0); BAR; MMA(0, 0, At, B0); MMA(0, 1, At, B1); BAR; SCHED;
;         LDA(At, 0, 1); STAGEB(SB(0, 0), b2); STAGEB(SB(0, 1), b2 + bstep); STAGE(SA(0, 0), a2);
;         WAIT_V(8); WAIT_L(0); BAR; MMA(1, 0, At, B0); MMA(1, 1, At, B1); BAR; SCHED;
.LBB0_620:
	ds_read_b128 v[150:153], v146
	ds_read_b128 v[154:157], v146 offset:1024
	ds_read_b128 v[158:161], v146 offset:2048
	ds_read_b128 v[162:165], v146 offset:3072
	ds_read_b128 v[166:169], v147
	ds_read_b128 v[170:173], v147 offset:1024
	ds_read_b128 v[174:177], v147 offset:2048
	ds_read_b128 v[178:181], v147 offset:3072
	s_add_u32 s47, s52, 0xfffc0080
	s_addc_u32 s54, s53, -1
	s_cmp_eq_u32 s37, 12
	s_cselect_b32 s57, s1, s54
	s_cselect_b32 s56, s23, s47
	s_cselect_b32 s55, s29, s35
	s_cselect_b32 s54, s33, s34
	v_lshl_add_u64 v[210:211], s[52:53], 0, v[136:137]
	s_add_i32 m0, s3, 0xc000
	ds_read_b128 v[182:185], v148
	ds_read_b128 v[186:189], v148 offset:1024
	ds_read_b128 v[190:193], v148 offset:2048
	ds_read_b128 v[194:197], v148 offset:3072
	ds_read_b128 v[198:201], v148 offset:4096
	ds_read_b128 v[202:205], v148 offset:5120
	ds_read_b128 v[206:209], v148 offset:6144
	ds_read_b128 v[216:219], v148 offset:7168
	global_load_lds_dwordx4 v[210:211], off
	v_lshl_add_u64 v[210:211], s[52:53], 0, v[138:139]
	s_add_i32 m0, s3, 0xe000
	s_nop 0
	global_load_lds_dwordx4 v[210:211], off
	s_waitcnt vmcnt(8)
	s_waitcnt lgkmcnt(0)
	s_barrier
	s_setprio 1
	s_waitcnt lgkmcnt(0)
	v_mfma_f32_16x16x32_bf16 v[124:127], v[150:153], v[182:185], v[124:127]
	v_mfma_f32_16x16x32_bf16 v[120:123], v[158:161], v[182:185], v[120:123]
	v_mfma_f32_16x16x32_bf16 v[108:111], v[150:153], v[190:193], v[108:111]
	v_mfma_f32_16x16x32_bf16 v[104:107], v[158:161], v[190:193], v[104:107]
	v_mfma_f32_16x16x32_bf16 v[92:95], v[150:153], v[198:201], v[92:95]
	v_mfma_f32_16x16x32_bf16 v[88:91], v[158:161], v[198:201], v[88:91]
	v_mfma_f32_16x16x32_bf16 v[76:79], v[150:153], v[206:209], v[76:79]
	v_mfma_f32_16x16x32_bf16 v[72:75], v[158:161], v[206:209], v[72:75]
	v_mfma_f32_16x16x32_bf16 v[124:127], v[154:157], v[186:189], v[124:127]
	v_mfma_f32_16x16x32_bf16 v[120:123], v[162:165], v[186:189], v[120:123]
	v_mfma_f32_16x16x32_bf16 v[108:111], v[154:157], v[194:197], v[108:111]
	v_mfma_f32_16x16x32_bf16 v[104:107], v[162:165], v[194:197], v[104:107]
	v_mfma_f32_16x16x32_bf16 v[92:95], v[154:157], v[202:205], v[92:95]
	v_mfma_f32_16x16x32_bf16 v[88:91], v[162:165], v[202:205], v[88:91]
	v_mfma_f32_16x16x32_bf16 v[76:79], v[154:157], v[216:219], v[76:79]
	v_mfma_f32_16x16x32_bf16 v[72:75], v[162:165], v[216:219], v[72:75]
	v_mfma_f32_16x16x32_bf16 v[116:119], v[166:169], v[182:185], v[116:119]
	v_mfma_f32_16x16x32_bf16 v[112:115], v[174:177], v[182:185], v[112:115]
	v_mfma_f32_16x16x32_bf16 v[100:103], v[166:169], v[190:193], v[100:103]
	v_mfma_f32_16x16x32_bf16 v[96:99], v[174:177], v[190:193], v[96:99]
	v_mfma_f32_16x16x32_bf16 v[84:87], v[166:169], v[198:201], v[84:87]
	v_mfma_f32_16x16x32_bf16 v[80:83], v[174:177], v[198:201], v[80:83]
	v_mfma_f32_16x16x32_bf16 v[68:71], v[166:169], v[206:209], v[68:71]
	v_mfma_f32_16x16x32_bf16 v[64:67], v[174:177], v[206:209], v[64:67]
	v_mfma_f32_16x16x32_bf16 v[116:119], v[170:173], v[186:189], v[116:119]
	v_mfma_f32_16x16x32_bf16 v[112:115], v[178:181], v[186:189], v[112:115]
	v_mfma_f32_16x16x32_bf16 v[100:103], v[170:173], v[194:197], v[100:103]
	v_mfma_f32_16x16x32_bf16 v[96:99], v[178:181], v[194:197], v[96:99]
	v_mfma_f32_16x16x32_bf16 v[84:87], v[170:173], v[202:205], v[84:87]
	v_mfma_f32_16x16x32_bf16 v[80:83], v[178:181], v[202:205], v[80:83]
	v_mfma_f32_16x16x32_bf16 v[68:71], v[170:173], v[216:219], v[68:71]
	v_mfma_f32_16x16x32_bf16 v[64:67], v[178:181], v[216:219], v[64:67]
	s_setprio 0
	s_barrier
	s_add_i32 s47, s19, s2
	v_lshl_add_u64 v[210:211], s[54:55], 0, v[132:133]
	s_mov_b32 m0, s47
	ds_read_b128 v[182:185], v148 offset:16384
	ds_read_b128 v[186:189], v148 offset:17408
	ds_read_b128 v[190:193], v148 offset:18432
	ds_read_b128 v[194:197], v148 offset:19456
	ds_read_b128 v[198:201], v148 offset:20480
	ds_read_b128 v[202:205], v148 offset:21504
	ds_read_b128 v[206:209], v148 offset:22528
	ds_read_b128 v[216:219], v148 offset:23552
	global_load_lds_dwordx4 v[210:211], off
	s_add_i32 m0, s47, 0x2000
	s_add_u32 s58, s54, 0x10000
	v_lshl_add_u64 v[220:221], s[54:55], 0, v[128:129]
	s_addc_u32 s59, s55, 0
	s_add_i32 s47, s20, s2
	global_load_lds_dwordx4 v[220:221], off
	v_lshl_add_u64 v[222:223], s[58:59], 0, v[132:133]
	s_mov_b32 m0, s47
	v_lshl_add_u64 v[224:225], s[56:57], 0, v[130:131]
	global_load_lds_dwordx4 v[222:223], off
	v_lshl_add_u64 v[222:223], s[58:59], 0, v[128:129]
	s_add_i32 m0, s47, 0x2000
	s_nop 0
	global_load_lds_dwordx4 v[222:223], off
	v_lshl_add_u64 v[222:223], s[56:57], 0, v[134:135]
	s_mov_b32 m0, s3
	s_nop 0
	global_load_lds_dwordx4 v[222:223], off
	s_mov_b32 m0, s8
	s_nop 0
	global_load_lds_dwordx4 v[224:225], off
	s_waitcnt vmcnt(8)
	s_waitcnt lgkmcnt(0)
	s_barrier
; #define STAGE(bufoff, gbase) STAGE_(bufoff, gbase, voffA)
; #define LDA(dst, b, h) do { _Pragma("unroll") for (int m = 0; m < 4; ++m) _Pragma("unroll") for (int k = 0; k < 2; ++k) dst[m][k] = *LDSP(const bf16x8, lds + SA(b, h) + aoff + m * 2048 + k * 1024); } while (0)
; #define LDB(dst, b, h) do { _Pragma("unroll") for (int n = 0; n < 2; ++n) _Pragma("unroll") for (int k = 0; k < 2; ++k) dst[n][k] = *LDSP(const bf16x8, lds + SB(b, h) + boff + n * 2048 + k * 1024); } while (0)
; #define MMA(ai, bj, AT, BT) do { __builtin_amdgcn_s_setprio(1); \
;     _Pragma("unroll") for (int m = 0; m < 4; ++m) _Pragma("unroll") for (int n = 0; n < 2; ++n) _Pragma("unroll") for (int k = 0; k < 2; ++k) \
;       acc[ai][bj][m][n] = __builtin_amdgcn_mfma_f32_16x16x32_bf16(BT[n][k], AT[m][k], acc[ai][bj][m][n], 0, 0, 0); \
;     __builtin_amdgcn_s_setprio(0); } while (0)
; #define WAIT_V(n) asm volatile("s_waitcnt vmcnt(" #n ")" ::: "memory")
; #define WAIT_L(n) asm volatile("s_waitcnt lgkmcnt(" #n ")" ::: "memory")
; #define BAR __builtin_amdgcn_s_barrier()
; #define SCHED __builtin_amdgcn_sched_barrier(0)
; #define WAIT_V(n) asm volatile("s_waitcnt vmcnt(" #n ")" ::: "memory")
; #define BAR do { __builtin_amdgcn_sched_barrier(0); __builtin_amdgcn_s_barrier(); asm volatile("" ::: "memory"); __builtin_amdgcn_sched_barrier(0); } while (0)
; template <bool SP2, bool ALIGN_EPI, bool DUAL, class Epi> DI void gemm_phase2(const bf16_t* A, const bf16_t* Bt, const bf16_t* A2, const bf16_t* Bt2, int M, int N, int K, const Epi& E, lds_t* lds) {
;     ...
;         WAIT_V(8); WAIT_L(0); BAR; MMA(1, 0, At, B0); MMA(1, 1, At, B1); BAR; SCHED;
;         LDB(B0, 1, 0); LDB(B1, 1, 1); SCHED; LDA(At, 1, 0); STAGE(SA(0, 1), a2 + hstep);
;         WAIT_V(8); WAIT_L(0); BAR; MMA(0, 0, At, B0); MMA(0, 1, At, B1); BAR; SCHED;
	s_setprio 1
	s_waitcnt lgkmcnt(0)
	v_mfma_f32_16x16x32_bf16 v[60:63], v[150:153], v[182:185], v[60:63]
	v_mfma_f32_16x16x32_bf16 v[56:59], v[158:161], v[182:185], v[56:59]
	v_mfma_f32_16x16x32_bf16 v[44:47], v[150:153], v[190:193], v[44:47]
	v_mfma_f32_16x16x32_bf16 v[40:43], v[158:161], v[190:193], v[40:43]
	v_mfma_f32_16x16x32_bf16 v[28:31], v[150:153], v[198:201], v[28:31]
	v_mfma_f32_16x16x32_bf16 v[24:27], v[158:161], v[198:201], v[24:27]
	v_mfma_f32_16x16x32_bf16 v[12:15], v[150:153], v[206:209], v[12:15]
	v_mfma_f32_16x16x32_bf16 v[8:11], v[158:161], v[206:209], v[8:11]
	v_mfma_f32_16x16x32_bf16 v[60:63], v[154:157], v[186:189], v[60:63]
	v_mfma_f32_16x16x32_bf16 v[56:59], v[162:165], v[186:189], v[56:59]
	v_mfma_f32_16x16x32_bf16 v[44:47], v[154:157], v[194:197], v[44:47]
	v_mfma_f32_16x16x32_bf16 v[40:43], v[162:165], v[194:197], v[40:43]
	v_mfma_f32_16x16x32_bf16 v[28:31], v[154:157], v[202:205], v[28:31]
	v_mfma_f32_16x16x32_bf16 v[24:27], v[162:165], v[202:205], v[24:27]
	v_mfma_f32_16x16x32_bf16 v[12:15], v[154:157], v[216:219], v[12:15]
	v_mfma_f32_16x16x32_bf16 v[8:11], v[162:165], v[216:219], v[8:11]
	v_mfma_f32_16x16x32_bf16 v[52:55], v[166:169], v[182:185], v[52:55]
	v_mfma_f32_16x16x32_bf16 v[48:51], v[174:177], v[182:185], v[48:51]
	v_mfma_f32_16x16x32_bf16 v[36:39], v[166:169], v[190:193], v[36:39]
	v_mfma_f32_16x16x32_bf16 v[32:35], v[174:177], v[190:193], v[32:35]
	v_mfma_f32_16x16x32_bf16 v[20:23], v[166:169], v[198:201], v[20:23]
	v_mfma_f32_16x16x32_bf16 v[16:19], v[174:177], v[198:201], v[16:19]
	v_mfma_f32_16x16x32_bf16 v[4:7], v[166:169], v[206:209], v[4:7]
	v_mfma_f32_16x16x32_bf16 v[0:3], v[174:177], v[206:209], v[0:3]
	v_mfma_f32_16x16x32_bf16 v[52:55], v[170:173], v[186:189], v[52:55]
	v_mfma_f32_16x16x32_bf16 v[48:51], v[178:181], v[186:189], v[48:51]
	v_mfma_f32_16x16x32_bf16 v[36:39], v[170:173], v[194:197], v[36:39]
	v_mfma_f32_16x16x32_bf16 v[32:35], v[178:181], v[194:197], v[32:35]
	v_mfma_f32_16x16x32_bf16 v[20:23], v[170:173], v[202:205], v[20:23]
	v_mfma_f32_16x16x32_bf16 v[16:19], v[178:181], v[202:205], v[16:19]
	v_mfma_f32_16x16x32_bf16 v[4:7], v[170:173], v[216:219], v[4:7]
	v_mfma_f32_16x16x32_bf16 v[0:3], v[178:181], v[216:219], v[0:3]
	s_setprio 0
	s_barrier
	s_add_i32 s47, 0, 0x18000
	s_add_i32 s58, 0, 0x1c000
	v_add_u32_e32 v162, s47, v141
	v_add_u32_e32 v178, s58, v141
	ds_read_b128 v[150:153], v162
	ds_read_b128 v[154:157], v162 offset:1024
	ds_read_b128 v[158:161], v162 offset:2048
	ds_read_b128 v[162:165], v162 offset:3072
	ds_read_b128 v[166:169], v178
	ds_read_b128 v[170:173], v178 offset:1024
	ds_read_b128 v[174:177], v178 offset:2048
	ds_read_b128 v[178:181], v178 offset:3072
	s_add_u32 s56, s56, 0x40000
	s_addc_u32 s57, s57, 0
	s_mov_b32 m0, s9
	v_lshl_add_u64 v[226:227], s[56:57], 0, v[134:135]
	ds_read_b128 v[182:185], v148 offset:32768
	ds_read_b128 v[186:189], v148 offset:33792
	ds_read_b128 v[190:193], v148 offset:34816
	ds_read_b128 v[194:197], v148 offset:35840
	ds_read_b128 v[198:201], v148 offset:36864
	ds_read_b128 v[202:205], v148 offset:37888
	ds_read_b128 v[206:209], v148 offset:38912
	ds_read_b128 v[216:219], v148 offset:39936
	global_load_lds_dwordx4 v[226:227], off
	v_lshl_add_u64 v[226:227], s[56:57], 0, v[130:131]
	s_mov_b32 m0, s10
	s_nop 0
	global_load_lds_dwordx4 v[226:227], off
	s_waitcnt vmcnt(8)
	s_waitcnt lgkmcnt(0)
	s_barrier
	s_setprio 1
	s_waitcnt lgkmcnt(0)
	v_mfma_f32_16x16x32_bf16 v[124:127], v[150:153], v[182:185], v[124:127]
	v_mfma_f32_16x16x32_bf16 v[120:123], v[158:161], v[182:185], v[120:123]
	v_mfma_f32_16x16x32_bf16 v[108:111], v[150:153], v[190:193], v[108:111]
	v_mfma_f32_16x16x32_bf16 v[104:107], v[158:161], v[190:193], v[104:107]
	v_mfma_f32_16x16x32_bf16 v[92:95], v[150:153], v[198:201], v[92:95]
	v_mfma_f32_16x16x32_bf16 v[88:91], v[158:161], v[198:201], v[88:91]
	v_mfma_f32_16x16x32_bf16 v[76:79], v[150:153], v[206:209], v[76:79]
	v_mfma_f32_16x16x32_bf16 v[72:75], v[158:161], v[206:209], v[72:75]
	v_mfma_f32_16x16x32_bf16 v[124:127], v[154:157], v[186:189], v[124:127]
	v_mfma_f32_16x16x32_bf16 v[120:123], v[162:165], v[186:189], v[120:123]
	v_mfma_f32_16x16x32_bf16 v[108:111], v[154:157], v[194:197], v[108:111]
	v_mfma_f32_16x16x32_bf16 v[104:107], v[162:165], v[194:197], v[104:107]
	v_mfma_f32_16x16x32_bf16 v[92:95], v[154:157], v[202:205], v[92:95]
	v_mfma_f32_16x16x32_bf16 v[88:91], v[162:165], v[202:205], v[88:91]
	v_mfma_f32_16x16x32_bf16 v[76:79], v[154:157], v[216:219], v[76:79]
	v_mfma_f32_16x16x32_bf16 v[72:75], v[162:165], v[216:219], v[72:75]
	v_mfma_f32_16x16x32_bf16 v[116:119], v[166:169], v[182:185], v[116:119]
	v_mfma_f32_16x16x32_bf16 v[112:115], v[174:177], v[182:185], v[112:115]
	v_mfma_f32_16x16x32_bf16 v[100:103], v[166:169], v[190:193], v[100:103]
	v_mfma_f32_16x16x32_bf16 v[96:99], v[174:177], v[190:193], v[96:99]
	v_mfma_f32_16x16x32_bf16 v[84:87], v[166:169], v[198:201], v[84:87]
	v_mfma_f32_16x16x32_bf16 v[80:83], v[174:177], v[198:201], v[80:83]
	v_mfma_f32_16x16x32_bf16 v[68:71], v[166:169], v[206:209], v[68:71]
	v_mfma_f32_16x16x32_bf16 v[64:67], v[174:177], v[206:209], v[64:67]
	v_mfma_f32_16x16x32_bf16 v[116:119], v[170:173], v[186:189], v[116:119]
	v_mfma_f32_16x16x32_bf16 v[112:115], v[178:181], v[186:189], v[112:115]
	v_mfma_f32_16x16x32_bf16 v[100:103], v[170:173], v[194:197], v[100:103]
	v_mfma_f32_16x16x32_bf16 v[96:99], v[178:181], v[194:197], v[96:99]
	v_mfma_f32_16x16x32_bf16 v[84:87], v[170:173], v[202:205], v[84:87]
	v_mfma_f32_16x16x32_bf16 v[80:83], v[178:181], v[202:205], v[80:83]
	v_mfma_f32_16x16x32_bf16 v[68:71], v[170:173], v[216:219], v[68:71]
	v_mfma_f32_16x16x32_bf16 v[64:67], v[178:181], v[216:219], v[64:67]
	s_setprio 0
	s_barrier
; #define STAGE(bufoff, gbase) STAGE_(bufoff, gbase, voffA)
; #define STAGEB(bufoff, gbase) STAGE_(bufoff, gbase, voffB)
; #define LDA(dst, b, h) do { _Pragma("unroll") for (int m = 0; m < 4; ++m) _Pragma("unroll") for (int k = 0; k < 2; ++k) dst[m][k] = *LDSP(const bf16x8, lds + SA(b, h) + aoff + m * 2048 + k * 1024); } while (0)
; #define LDB(dst, b, h) do { _Pragma("unroll") for (int n = 0; n < 2; ++n) _Pragma("unroll") for (int k = 0; k < 2; ++k) dst[n][k] = *LDSP(const bf16x8, lds + SB(b, h) + boff + n * 2048 + k * 1024); } while (0)
; #define MMA(ai, bj, AT, BT) do { __builtin_amdgcn_s_setprio(1); \
;     _Pragma("unroll") for (int m = 0; m < 4; ++m) _Pragma("unroll") for (int n = 0; n < 2; ++n) _Pragma("unroll") for (int k = 0; k < 2; ++k) \
;       acc[ai][bj][m][n] = __builtin_amdgcn_mfma_f32_16x16x32_bf16(BT[n][k], AT[m][k], acc[ai][bj][m][n], 0, 0, 0); \
;     __builtin_amdgcn_s_setprio(0); } while (0)
; #define WAIT_V(n) asm volatile("s_waitcnt vmcnt(" #n ")" ::: "memory")
; #define WAIT_L(n) asm volatile("s_waitcnt lgkmcnt(" #n ")" ::: "memory")
; template <bool SP2, bool ALIGN_EPI, bool DUAL, class Epi> DI void gemm_phase2(const bf16_t* A, const bf16_t* Bt, const bf16_t* A2, const bf16_t* Bt2, int M, int N, int K, const Epi& E, lds_t* lds) {
;     ...
;     for (int t = 0; t < nt; t += 2) {
;       const bool last = (t == nt - 2);
;       const char* a1 = cA + (size_t)(t + 1) * kstep;
;       const char* a2 = last ? nA : cA + (size_t)(t + 2) * kstep; const char* b2 = last ? nB : cB + (size_t)(t + 2) * kstep;
;       const char* a3 = a2 + kstep; const char* b3 = b2 + kstep;
;       if constexpr (SP2) {
;         LDB(B0, 0, 0); LDB(B1, 0, 1); SCHED; LDA(At, 0, 0); STAGE(SA(1, 1), a1 + hstep);
;         WAIT_V(8); WAIT_L(0); BAR; MMA(0, 0, At, B0); MMA(0, 1, At, B1); BAR; SCHED;
;         LDA(At, 0, 1); STAGEB(SB(0, 0), b2); STAGEB(SB(0, 1), b2 + bstep); STAGE(SA(0, 0), a2);
;         WAIT_V(8); WAIT_L(0); BAR; MMA(1, 0, At, B0); MMA(1, 1, At, B1); BAR; SCHED;
;         LDB(B0, 1, 0); LDB(B1, 1, 1); SCHED; LDA(At, 1, 0); STAGE(SA(0, 1), a2 + hstep);
;         WAIT_V(8); WAIT_L(0); BAR; MMA(0, 0, At, B0); MMA(0, 1, At, B1); BAR; SCHED;
;         LDA(At, 1, 1); STAGEB(SB(1, 0), b3); STAGEB(SB(1, 1), b3 + bstep); STAGE(SA(1, 0), a3);
;         WAIT_V(8); WAIT_L(0); BAR; MMA(1, 0, At, B0); MMA(1, 1, At, B1); BAR; SCHED;
	s_add_i32 s47, s47, s2
	v_lshl_add_u64 v[210:211], v[210:211], 0, s[16:17]
	s_mov_b32 m0, s47
	ds_read_b128 v[182:185], v148 offset:49152
	ds_read_b128 v[186:189], v148 offset:50176
	ds_read_b128 v[190:193], v148 offset:51200
	ds_read_b128 v[194:197], v148 offset:52224
	ds_read_b128 v[198:201], v148 offset:53248
	ds_read_b128 v[202:205], v148 offset:54272
	ds_read_b128 v[206:209], v148 offset:55296
	ds_read_b128 v[216:219], v148 offset:56320
	global_load_lds_dwordx4 v[210:211], off
	s_add_i32 m0, s47, 0x2000
	s_add_u32 s54, s54, 0x10080
	v_lshl_add_u64 v[210:211], v[220:221], 0, s[16:17]
	s_addc_u32 s55, s55, 0
	s_add_i32 s47, s58, s2
	global_load_lds_dwordx4 v[210:211], off
	v_lshl_add_u64 v[210:211], s[54:55], 0, v[132:133]
	s_mov_b32 m0, s47
	s_nop 0
	global_load_lds_dwordx4 v[210:211], off
	v_lshl_add_u64 v[210:211], s[54:55], 0, v[128:129]
	s_add_i32 m0, s47, 0x2000
	s_nop 0
	global_load_lds_dwordx4 v[210:211], off
	v_lshl_add_u64 v[210:211], v[222:223], 0, s[16:17]
	s_mov_b32 m0, s15
	s_nop 0
	global_load_lds_dwordx4 v[210:211], off
	v_lshl_add_u64 v[210:211], v[224:225], 0, s[16:17]
	s_mov_b32 m0, s18
	s_nop 0
	global_load_lds_dwordx4 v[210:211], off
	s_waitcnt vmcnt(8)
	s_waitcnt lgkmcnt(0)
	s_barrier
	s_setprio 1
	s_waitcnt lgkmcnt(0)
	v_mfma_f32_16x16x32_bf16 v[60:63], v[150:153], v[182:185], v[60:63]
	v_mfma_f32_16x16x32_bf16 v[56:59], v[158:161], v[182:185], v[56:59]
	v_mfma_f32_16x16x32_bf16 v[44:47], v[150:153], v[190:193], v[44:47]
	v_mfma_f32_16x16x32_bf16 v[40:43], v[158:161], v[190:193], v[40:43]
	v_mfma_f32_16x16x32_bf16 v[28:31], v[150:153], v[198:201], v[28:31]
	v_mfma_f32_16x16x32_bf16 v[24:27], v[158:161], v[198:201], v[24:27]
	v_mfma_f32_16x16x32_bf16 v[12:15], v[150:153], v[206:209], v[12:15]
	v_mfma_f32_16x16x32_bf16 v[8:11], v[158:161], v[206:209], v[8:11]
	v_mfma_f32_16x16x32_bf16 v[60:63], v[154:157], v[186:189], v[60:63]
	v_mfma_f32_16x16x32_bf16 v[56:59], v[162:165], v[186:189], v[56:59]
	v_mfma_f32_16x16x32_bf16 v[44:47], v[154:157], v[194:197], v[44:47]
	v_mfma_f32_16x16x32_bf16 v[40:43], v[162:165], v[194:197], v[40:43]
	v_mfma_f32_16x16x32_bf16 v[28:31], v[154:157], v[202:205], v[28:31]
	v_mfma_f32_16x16x32_bf16 v[24:27], v[162:165], v[202:205], v[24:27]
	v_mfma_f32_16x16x32_bf16 v[12:15], v[154:157], v[216:219], v[12:15]
	v_mfma_f32_16x16x32_bf16 v[8:11], v[162:165], v[216:219], v[8:11]
	v_mfma_f32_16x16x32_bf16 v[52:55], v[166:169], v[182:185], v[52:55]
	v_mfma_f32_16x16x32_bf16 v[48:51], v[174:177], v[182:185], v[48:51]
	v_mfma_f32_16x16x32_bf16 v[36:39], v[166:169], v[190:193], v[36:39]
	v_mfma_f32_16x16x32_bf16 v[32:35], v[174:177], v[190:193], v[32:35]
	v_mfma_f32_16x16x32_bf16 v[20:23], v[166:169], v[198:201], v[20:23]
	v_mfma_f32_16x16x32_bf16 v[16:19], v[174:177], v[198:201], v[16:19]
	v_mfma_f32_16x16x32_bf16 v[4:7], v[166:169], v[206:209], v[4:7]
	v_mfma_f32_16x16x32_bf16 v[0:3], v[174:177], v[206:209], v[0:3]
	v_mfma_f32_16x16x32_bf16 v[52:55], v[170:173], v[186:189], v[52:55]
	v_mfma_f32_16x16x32_bf16 v[48:51], v[178:181], v[186:189], v[48:51]
	v_mfma_f32_16x16x32_bf16 v[36:39], v[170:173], v[194:197], v[36:39]
	v_mfma_f32_16x16x32_bf16 v[32:35], v[178:181], v[194:197], v[32:35]
	v_mfma_f32_16x16x32_bf16 v[20:23], v[170:173], v[202:205], v[20:23]
	v_mfma_f32_16x16x32_bf16 v[16:19], v[178:181], v[202:205], v[16:19]
	v_mfma_f32_16x16x32_bf16 v[4:7], v[170:173], v[216:219], v[4:7]
	v_mfma_f32_16x16x32_bf16 v[0:3], v[178:181], v[216:219], v[0:3]
	s_setprio 0
	s_barrier
	s_add_i32 s37, s37, 2
	s_add_u32 s52, s52, 0x100
	s_addc_u32 s53, s53, 0
	s_add_u32 s34, s34, 0x100
	s_addc_u32 s35, s35, 0
	s_cmp_gt_u32 s37, 13
	s_cbranch_scc0 .LBB0_620
	s_and_b64 vcc, exec, s[30:31]
	s_cbranch_vccz .LBB0_623
	s_barrier

; #define STAGE(bufoff, gbase) STAGE_(bufoff, gbase, voffA)
; #define STAGEB(bufoff, gbase) STAGE_(bufoff, gbase, voffB)
; #define LDA(dst, b, h) do { _Pragma("unroll") for (int m = 0; m < 4; ++m) _Pragma("unroll") for (int k = 0; k < 2; ++k) dst[m][k] = *LDSP(const bf16x8, lds + SA(b, h) + aoff + m * 2048 + k * 1024); } while (0)
; #define LDB(dst, b, h) do { _Pragma("unroll") for (int n = 0; n < 2; ++n) _Pragma("unroll") for (int k = 0; k < 2; ++k) dst[n][k] = *LDSP(const bf16x8, lds + SB(b, h) + boff + n * 2048 + k * 1024); } while (0)
; #define MMA(ai, bj, AT, BT) do { __builtin_amdgcn_s_setprio(1); \
;     _Pragma("unroll") for (int m = 0; m < 4; ++m) _Pragma("unroll") for (int n = 0; n < 2; ++n) _Pragma("unroll") for (int k = 0; k < 2; ++k) \
;       acc[ai][bj][m][n] = __builtin_amdgcn_mfma_f32_16x16x32_bf16(BT[n][k], AT[m][k], acc[ai][bj][m][n], 0, 0, 0); \
;     __builtin_amdgcn_s_setprio(0); } while (0)
; #define WAIT_V(n) asm volatile("s_waitcnt vmcnt(" #n ")" ::: "memory")
; #define WAIT_L(n) asm volatile("s_waitcnt lgkmcnt(" #n ")" ::: "memory")
; #define BAR __builtin_amdgcn_s_barrier()
; #define SCHED __builtin_amdgcn_sched_barrier(0)
; #define WAIT_V(n) asm volatile("s_waitcnt vmcnt(" #n ")" ::: "memory")
; #define BAR do { __builtin_amdgcn_sched_barrier(0); __builtin_amdgcn_s_barrier(); asm volatile("" ::: "memory"); __builtin_amdgcn_sched_barrier(0); } while (0)
; template <bool SP2, bool ALIGN_EPI, bool DUAL, class Epi> DI void gemm_phase2(const bf16_t* A, const bf16_t* Bt, const bf16_t* A2, const bf16_t* Bt2, int M, int N, int K, const Epi& E, lds_t* lds) {
;     ...
;       const bool last = (t == nt - 2);
;       const char* a1 = cA + (size_t)(t + 1) * kstep;
;       const char* a2 = last ? nA : cA + (size_t)(t + 2) * kstep; const char* b2 = last ? nB : cB + (size_t)(t + 2) * kstep;
;       const char* a3 = a2 + kstep; const char* b3 = b2 + kstep;
;       if constexpr (SP2) {
;         LDB(B0, 0, 0); LDB(B1, 0, 1); SCHED; LDA(At, 0, 0); STAGE(SA(1, 1), a1 + hstep);
;         WAIT_V(8); WAIT_L(0); BAR; MMA(0, 0, At, B0); MMA(0, 1, At, B1); BAR; SCHED;
;         LDA(At, 0, 1); STAGEB(SB(0, 0), b2); STAGEB(SB(0, 1), b2 + bstep); STAGE(SA(0, 0), a2);
;         WAIT_V(8); WAIT_L(0); BAR; MMA(1, 0, At, B0); MMA(1, 1, At, B1); BAR; SCHED;
.LBB0_691:
	ds_read_b128 v[152:155], v148
	ds_read_b128 v[156:159], v148 offset:1024
	ds_read_b128 v[160:163], v148 offset:2048
	ds_read_b128 v[164:167], v148 offset:3072
	ds_read_b128 v[168:171], v149
	ds_read_b128 v[172:175], v149 offset:1024
	ds_read_b128 v[176:179], v149 offset:2048
	ds_read_b128 v[180:183], v149 offset:3072
	s_add_u32 s34, s52, 0xfffc0080
	s_addc_u32 s35, s53, -1
	s_cmp_eq_u32 s33, 12
	s_cselect_b32 s57, s0, s35
	s_cselect_b32 s56, s1, s34
	s_cselect_b32 s55, s21, s31
	s_cselect_b32 s54, s22, s23
	v_lshl_add_u64 v[140:141], s[52:53], 0, v[136:137]
	s_add_i32 m0, s3, 0xc000
	ds_read_b128 v[184:187], v150
	ds_read_b128 v[188:191], v150 offset:1024
	ds_read_b128 v[192:195], v150 offset:2048
	ds_read_b128 v[196:199], v150 offset:3072
	ds_read_b128 v[200:203], v150 offset:4096
	ds_read_b128 v[204:207], v150 offset:5120
	ds_read_b128 v[208:211], v150 offset:6144
	ds_read_b128 v[216:219], v150 offset:7168
	global_load_lds_dwordx4 v[140:141], off
	v_lshl_add_u64 v[140:141], s[52:53], 0, v[138:139]
	s_add_i32 m0, s3, 0xe000
	s_nop 0
	global_load_lds_dwordx4 v[140:141], off
	s_waitcnt vmcnt(8)
	s_waitcnt lgkmcnt(0)
	s_barrier
	s_setprio 1
	s_waitcnt lgkmcnt(0)
	v_mfma_f32_16x16x32_bf16 v[124:127], v[152:155], v[184:187], v[124:127]
	v_mfma_f32_16x16x32_bf16 v[120:123], v[160:163], v[184:187], v[120:123]
	v_mfma_f32_16x16x32_bf16 v[108:111], v[152:155], v[192:195], v[108:111]
	v_mfma_f32_16x16x32_bf16 v[104:107], v[160:163], v[192:195], v[104:107]
	v_mfma_f32_16x16x32_bf16 v[92:95], v[152:155], v[200:203], v[92:95]
	v_mfma_f32_16x16x32_bf16 v[88:91], v[160:163], v[200:203], v[88:91]
	v_mfma_f32_16x16x32_bf16 v[76:79], v[152:155], v[208:211], v[76:79]
	v_mfma_f32_16x16x32_bf16 v[72:75], v[160:163], v[208:211], v[72:75]
	v_mfma_f32_16x16x32_bf16 v[124:127], v[156:159], v[188:191], v[124:127]
	v_mfma_f32_16x16x32_bf16 v[120:123], v[164:167], v[188:191], v[120:123]
	v_mfma_f32_16x16x32_bf16 v[108:111], v[156:159], v[196:199], v[108:111]
	v_mfma_f32_16x16x32_bf16 v[104:107], v[164:167], v[196:199], v[104:107]
	v_mfma_f32_16x16x32_bf16 v[92:95], v[156:159], v[204:207], v[92:95]
	v_mfma_f32_16x16x32_bf16 v[88:91], v[164:167], v[204:207], v[88:91]
	v_mfma_f32_16x16x32_bf16 v[76:79], v[156:159], v[216:219], v[76:79]
	v_mfma_f32_16x16x32_bf16 v[72:75], v[164:167], v[216:219], v[72:75]
	v_mfma_f32_16x16x32_bf16 v[116:119], v[168:171], v[184:187], v[116:119]
	v_mfma_f32_16x16x32_bf16 v[112:115], v[176:179], v[184:187], v[112:115]
	v_mfma_f32_16x16x32_bf16 v[100:103], v[168:171], v[192:195], v[100:103]
	v_mfma_f32_16x16x32_bf16 v[96:99], v[176:179], v[192:195], v[96:99]
	v_mfma_f32_16x16x32_bf16 v[84:87], v[168:171], v[200:203], v[84:87]
	v_mfma_f32_16x16x32_bf16 v[80:83], v[176:179], v[200:203], v[80:83]
	v_mfma_f32_16x16x32_bf16 v[68:71], v[168:171], v[208:211], v[68:71]
	v_mfma_f32_16x16x32_bf16 v[64:67], v[176:179], v[208:211], v[64:67]
	v_mfma_f32_16x16x32_bf16 v[116:119], v[172:175], v[188:191], v[116:119]
	v_mfma_f32_16x16x32_bf16 v[112:115], v[180:183], v[188:191], v[112:115]
	v_mfma_f32_16x16x32_bf16 v[100:103], v[172:175], v[196:199], v[100:103]
	v_mfma_f32_16x16x32_bf16 v[96:99], v[180:183], v[196:199], v[96:99]
	v_mfma_f32_16x16x32_bf16 v[84:87], v[172:175], v[204:207], v[84:87]
	v_mfma_f32_16x16x32_bf16 v[80:83], v[180:183], v[204:207], v[80:83]
	v_mfma_f32_16x16x32_bf16 v[68:71], v[172:175], v[216:219], v[68:71]
	v_mfma_f32_16x16x32_bf16 v[64:67], v[180:183], v[216:219], v[64:67]
	s_setprio 0
	s_barrier
	s_add_i32 s34, s18, s2
	v_lshl_add_u64 v[140:141], s[54:55], 0, v[130:131]
	s_mov_b32 m0, s34
	ds_read_b128 v[184:187], v150 offset:16384
	ds_read_b128 v[188:191], v150 offset:17408
	ds_read_b128 v[192:195], v150 offset:18432
	ds_read_b128 v[196:199], v150 offset:19456
	ds_read_b128 v[200:203], v150 offset:20480
	ds_read_b128 v[204:207], v150 offset:21504
	ds_read_b128 v[208:211], v150 offset:22528
	ds_read_b128 v[216:219], v150 offset:23552
	global_load_lds_dwordx4 v[140:141], off
	s_add_i32 m0, s34, 0x2000
	s_add_u32 s34, s54, 0x10000
	v_lshl_add_u64 v[220:221], s[54:55], 0, v[134:135]
	s_addc_u32 s35, s55, 0
	s_add_i32 s41, s19, s2
	global_load_lds_dwordx4 v[220:221], off
	v_lshl_add_u64 v[222:223], s[34:35], 0, v[130:131]
	s_mov_b32 m0, s41
	v_lshl_add_u64 v[224:225], s[56:57], 0, v[132:133]
	global_load_lds_dwordx4 v[222:223], off
	v_lshl_add_u64 v[222:223], s[34:35], 0, v[134:135]
	s_add_i32 m0, s41, 0x2000
	s_nop 0
	global_load_lds_dwordx4 v[222:223], off
	v_lshl_add_u64 v[222:223], s[56:57], 0, v[128:129]
	s_mov_b32 m0, s3
	s_nop 0
	global_load_lds_dwordx4 v[222:223], off
	s_mov_b32 m0, s8
	s_nop 0
	global_load_lds_dwordx4 v[224:225], off
	s_waitcnt vmcnt(8)
	s_waitcnt lgkmcnt(0)
	s_barrier
; #define STAGE(bufoff, gbase) STAGE_(bufoff, gbase, voffA)
; #define LDA(dst, b, h) do { _Pragma("unroll") for (int m = 0; m < 4; ++m) _Pragma("unroll") for (int k = 0; k < 2; ++k) dst[m][k] = *LDSP(const bf16x8, lds + SA(b, h) + aoff + m * 2048 + k * 1024); } while (0)
; #define LDB(dst, b, h) do { _Pragma("unroll") for (int n = 0; n < 2; ++n) _Pragma("unroll") for (int k = 0; k < 2; ++k) dst[n][k] = *LDSP(const bf16x8, lds + SB(b, h) + boff + n * 2048 + k * 1024); } while (0)
; #define MMA(ai, bj, AT, BT) do { __builtin_amdgcn_s_setprio(1); \
;     _Pragma("unroll") for (int m = 0; m < 4; ++m) _Pragma("unroll") for (int n = 0; n < 2; ++n) _Pragma("unroll") for (int k = 0; k < 2; ++k) \
;       acc[ai][bj][m][n] = __builtin_amdgcn_mfma_f32_16x16x32_bf16(BT[n][k], AT[m][k], acc[ai][bj][m][n], 0, 0, 0); \
;     __builtin_amdgcn_s_setprio(0); } while (0)
; #define WAIT_V(n) asm volatile("s_waitcnt vmcnt(" #n ")" ::: "memory")
; #define WAIT_L(n) asm volatile("s_waitcnt lgkmcnt(" #n ")" ::: "memory")
; #define BAR __builtin_amdgcn_s_barrier()
; #define SCHED __builtin_amdgcn_sched_barrier(0)
; #define WAIT_V(n) asm volatile("s_waitcnt vmcnt(" #n ")" ::: "memory")
; #define BAR do { __builtin_amdgcn_sched_barrier(0); __builtin_amdgcn_s_barrier(); asm volatile("" ::: "memory"); __builtin_amdgcn_sched_barrier(0); } while (0)
; template <bool SP2, bool ALIGN_EPI, bool DUAL, class Epi> DI void gemm_phase2(const bf16_t* A, const bf16_t* Bt, const bf16_t* A2, const bf16_t* Bt2, int M, int N, int K, const Epi& E, lds_t* lds) {
;     ...
;         WAIT_V(8); WAIT_L(0); BAR; MMA(1, 0, At, B0); MMA(1, 1, At, B1); BAR; SCHED;
;         LDB(B0, 1, 0); LDB(B1, 1, 1); SCHED; LDA(At, 1, 0); STAGE(SA(0, 1), a2 + hstep);
;         WAIT_V(8); WAIT_L(0); BAR; MMA(0, 0, At, B0); MMA(0, 1, At, B1); BAR; SCHED;
	s_setprio 1
	s_waitcnt lgkmcnt(0)
	v_mfma_f32_16x16x32_bf16 v[60:63], v[152:155], v[184:187], v[60:63]
	v_mfma_f32_16x16x32_bf16 v[56:59], v[160:163], v[184:187], v[56:59]
	v_mfma_f32_16x16x32_bf16 v[44:47], v[152:155], v[192:195], v[44:47]
	v_mfma_f32_16x16x32_bf16 v[40:43], v[160:163], v[192:195], v[40:43]
	v_mfma_f32_16x16x32_bf16 v[28:31], v[152:155], v[200:203], v[28:31]
	v_mfma_f32_16x16x32_bf16 v[24:27], v[160:163], v[200:203], v[24:27]
	v_mfma_f32_16x16x32_bf16 v[12:15], v[152:155], v[208:211], v[12:15]
	v_mfma_f32_16x16x32_bf16 v[8:11], v[160:163], v[208:211], v[8:11]
	v_mfma_f32_16x16x32_bf16 v[60:63], v[156:159], v[188:191], v[60:63]
	v_mfma_f32_16x16x32_bf16 v[56:59], v[164:167], v[188:191], v[56:59]
	v_mfma_f32_16x16x32_bf16 v[44:47], v[156:159], v[196:199], v[44:47]
	v_mfma_f32_16x16x32_bf16 v[40:43], v[164:167], v[196:199], v[40:43]
	v_mfma_f32_16x16x32_bf16 v[28:31], v[156:159], v[204:207], v[28:31]
	v_mfma_f32_16x16x32_bf16 v[24:27], v[164:167], v[204:207], v[24:27]
	v_mfma_f32_16x16x32_bf16 v[12:15], v[156:159], v[216:219], v[12:15]
	v_mfma_f32_16x16x32_bf16 v[8:11], v[164:167], v[216:219], v[8:11]
	v_mfma_f32_16x16x32_bf16 v[52:55], v[168:171], v[184:187], v[52:55]
	v_mfma_f32_16x16x32_bf16 v[48:51], v[176:179], v[184:187], v[48:51]
	v_mfma_f32_16x16x32_bf16 v[36:39], v[168:171], v[192:195], v[36:39]
	v_mfma_f32_16x16x32_bf16 v[32:35], v[176:179], v[192:195], v[32:35]
	v_mfma_f32_16x16x32_bf16 v[20:23], v[168:171], v[200:203], v[20:23]
	v_mfma_f32_16x16x32_bf16 v[16:19], v[176:179], v[200:203], v[16:19]
	v_mfma_f32_16x16x32_bf16 v[4:7], v[168:171], v[208:211], v[4:7]
	v_mfma_f32_16x16x32_bf16 v[0:3], v[176:179], v[208:211], v[0:3]
	v_mfma_f32_16x16x32_bf16 v[52:55], v[172:175], v[188:191], v[52:55]
	v_mfma_f32_16x16x32_bf16 v[48:51], v[180:183], v[188:191], v[48:51]
	v_mfma_f32_16x16x32_bf16 v[36:39], v[172:175], v[196:199], v[36:39]
	v_mfma_f32_16x16x32_bf16 v[32:35], v[180:183], v[196:199], v[32:35]
	v_mfma_f32_16x16x32_bf16 v[20:23], v[172:175], v[204:207], v[20:23]
	v_mfma_f32_16x16x32_bf16 v[16:19], v[180:183], v[204:207], v[16:19]
	v_mfma_f32_16x16x32_bf16 v[4:7], v[172:175], v[216:219], v[4:7]
	v_mfma_f32_16x16x32_bf16 v[0:3], v[180:183], v[216:219], v[0:3]
	s_setprio 0
	s_barrier
	s_add_i32 s41, 0, 0x18000
	s_add_i32 s49, 0, 0x1c000
	v_add_u32_e32 v164, s41, v143
	v_add_u32_e32 v180, s49, v143
	ds_read_b128 v[152:155], v164
	ds_read_b128 v[156:159], v164 offset:1024
	ds_read_b128 v[160:163], v164 offset:2048
	ds_read_b128 v[164:167], v164 offset:3072
	ds_read_b128 v[168:171], v180
	ds_read_b128 v[172:175], v180 offset:1024
	ds_read_b128 v[176:179], v180 offset:2048
	ds_read_b128 v[180:183], v180 offset:3072
	s_add_u32 s34, s56, 0x40000
	s_addc_u32 s35, s57, 0
	s_mov_b32 m0, s9
	v_lshl_add_u64 v[226:227], s[34:35], 0, v[128:129]
	ds_read_b128 v[184:187], v150 offset:32768
	ds_read_b128 v[188:191], v150 offset:33792
	ds_read_b128 v[192:195], v150 offset:34816
	ds_read_b128 v[196:199], v150 offset:35840
	ds_read_b128 v[200:203], v150 offset:36864
	ds_read_b128 v[204:207], v150 offset:37888
	ds_read_b128 v[208:211], v150 offset:38912
	ds_read_b128 v[216:219], v150 offset:39936
	global_load_lds_dwordx4 v[226:227], off
	v_lshl_add_u64 v[226:227], s[34:35], 0, v[132:133]
	s_mov_b32 m0, s10
	s_nop 0
	global_load_lds_dwordx4 v[226:227], off
	s_waitcnt vmcnt(8)
	s_waitcnt lgkmcnt(0)
	s_barrier
	s_setprio 1
	s_waitcnt lgkmcnt(0)
	v_mfma_f32_16x16x32_bf16 v[124:127], v[152:155], v[184:187], v[124:127]
	v_mfma_f32_16x16x32_bf16 v[120:123], v[160:163], v[184:187], v[120:123]
	v_mfma_f32_16x16x32_bf16 v[108:111], v[152:155], v[192:195], v[108:111]
	v_mfma_f32_16x16x32_bf16 v[104:107], v[160:163], v[192:195], v[104:107]
	v_mfma_f32_16x16x32_bf16 v[92:95], v[152:155], v[200:203], v[92:95]
	v_mfma_f32_16x16x32_bf16 v[88:91], v[160:163], v[200:203], v[88:91]
	v_mfma_f32_16x16x32_bf16 v[76:79], v[152:155], v[208:211], v[76:79]
	v_mfma_f32_16x16x32_bf16 v[72:75], v[160:163], v[208:211], v[72:75]
	v_mfma_f32_16x16x32_bf16 v[124:127], v[156:159], v[188:191], v[124:127]
	v_mfma_f32_16x16x32_bf16 v[120:123], v[164:167], v[188:191], v[120:123]
	v_mfma_f32_16x16x32_bf16 v[108:111], v[156:159], v[196:199], v[108:111]
	v_mfma_f32_16x16x32_bf16 v[104:107], v[164:167], v[196:199], v[104:107]
	v_mfma_f32_16x16x32_bf16 v[92:95], v[156:159], v[204:207], v[92:95]
	v_mfma_f32_16x16x32_bf16 v[88:91], v[164:167], v[204:207], v[88:91]
	v_mfma_f32_16x16x32_bf16 v[76:79], v[156:159], v[216:219], v[76:79]
	v_mfma_f32_16x16x32_bf16 v[72:75], v[164:167], v[216:219], v[72:75]
	v_mfma_f32_16x16x32_bf16 v[116:119], v[168:171], v[184:187], v[116:119]
	v_mfma_f32_16x16x32_bf16 v[112:115], v[176:179], v[184:187], v[112:115]
	v_mfma_f32_16x16x32_bf16 v[100:103], v[168:171], v[192:195], v[100:103]
	v_mfma_f32_16x16x32_bf16 v[96:99], v[176:179], v[192:195], v[96:99]
	v_mfma_f32_16x16x32_bf16 v[84:87], v[168:171], v[200:203], v[84:87]
	v_mfma_f32_16x16x32_bf16 v[80:83], v[176:179], v[200:203], v[80:83]
	v_mfma_f32_16x16x32_bf16 v[68:71], v[168:171], v[208:211], v[68:71]
	v_mfma_f32_16x16x32_bf16 v[64:67], v[176:179], v[208:211], v[64:67]
	v_mfma_f32_16x16x32_bf16 v[116:119], v[172:175], v[188:191], v[116:119]
	v_mfma_f32_16x16x32_bf16 v[112:115], v[180:183], v[188:191], v[112:115]
	v_mfma_f32_16x16x32_bf16 v[100:103], v[172:175], v[196:199], v[100:103]
	v_mfma_f32_16x16x32_bf16 v[96:99], v[180:183], v[196:199], v[96:99]
	v_mfma_f32_16x16x32_bf16 v[84:87], v[172:175], v[204:207], v[84:87]
	v_mfma_f32_16x16x32_bf16 v[80:83], v[180:183], v[204:207], v[80:83]
	v_mfma_f32_16x16x32_bf16 v[68:71], v[172:175], v[216:219], v[68:71]
	v_mfma_f32_16x16x32_bf16 v[64:67], v[180:183], v[216:219], v[64:67]
	s_setprio 0
	s_barrier
; #define STAGE(bufoff, gbase) STAGE_(bufoff, gbase, voffA)
; #define STAGEB(bufoff, gbase) STAGE_(bufoff, gbase, voffB)
; #define LDA(dst, b, h) do { _Pragma("unroll") for (int m = 0; m < 4; ++m) _Pragma("unroll") for (int k = 0; k < 2; ++k) dst[m][k] = *LDSP(const bf16x8, lds + SA(b, h) + aoff + m * 2048 + k * 1024); } while (0)
; #define LDB(dst, b, h) do { _Pragma("unroll") for (int n = 0; n < 2; ++n) _Pragma("unroll") for (int k = 0; k < 2; ++k) dst[n][k] = *LDSP(const bf16x8, lds + SB(b, h) + boff + n * 2048 + k * 1024); } while (0)
; #define MMA(ai, bj, AT, BT) do { __builtin_amdgcn_s_setprio(1); \
;     _Pragma("unroll") for (int m = 0; m < 4; ++m) _Pragma("unroll") for (int n = 0; n < 2; ++n) _Pragma("unroll") for (int k = 0; k < 2; ++k) \
;       acc[ai][bj][m][n] = __builtin_amdgcn_mfma_f32_16x16x32_bf16(BT[n][k], AT[m][k], acc[ai][bj][m][n], 0, 0, 0); \
;     __builtin_amdgcn_s_setprio(0); } while (0)
; #define WAIT_V(n) asm volatile("s_waitcnt vmcnt(" #n ")" ::: "memory")
; #define WAIT_L(n) asm volatile("s_waitcnt lgkmcnt(" #n ")" ::: "memory")
; template <bool SP2, bool ALIGN_EPI, bool DUAL, class Epi> DI void gemm_phase2(const bf16_t* A, const bf16_t* Bt, const bf16_t* A2, const bf16_t* Bt2, int M, int N, int K, const Epi& E, lds_t* lds) {
;     ...
;     for (int t = 0; t < nt; t += 2) {
;       const bool last = (t == nt - 2);
;       const char* a1 = cA + (size_t)(t + 1) * kstep;
;       const char* a2 = last ? nA : cA + (size_t)(t + 2) * kstep; const char* b2 = last ? nB : cB + (size_t)(t + 2) * kstep;
;       const char* a3 = a2 + kstep; const char* b3 = b2 + kstep;
;       if constexpr (SP2) {
;         LDB(B0, 0, 0); LDB(B1, 0, 1); SCHED; LDA(At, 0, 0); STAGE(SA(1, 1), a1 + hstep);
;         WAIT_V(8); WAIT_L(0); BAR; MMA(0, 0, At, B0); MMA(0, 1, At, B1); BAR; SCHED;
;         LDA(At, 0, 1); STAGEB(SB(0, 0), b2); STAGEB(SB(0, 1), b2 + bstep); STAGE(SA(0, 0), a2);
;         WAIT_V(8); WAIT_L(0); BAR; MMA(1, 0, At, B0); MMA(1, 1, At, B1); BAR; SCHED;
;         LDB(B0, 1, 0); LDB(B1, 1, 1); SCHED; LDA(At, 1, 0); STAGE(SA(0, 1), a2 + hstep);
;         WAIT_V(8); WAIT_L(0); BAR; MMA(0, 0, At, B0); MMA(0, 1, At, B1); BAR; SCHED;
;         LDA(At, 1, 1); STAGEB(SB(1, 0), b3); STAGEB(SB(1, 1), b3 + bstep); STAGE(SA(1, 0), a3);
;         WAIT_V(8); WAIT_L(0); BAR; MMA(1, 0, At, B0); MMA(1, 1, At, B1); BAR; SCHED;
	s_add_i32 s34, s41, s2
	v_lshl_add_u64 v[140:141], v[140:141], 0, s[28:29]
	s_mov_b32 m0, s34
	ds_read_b128 v[184:187], v150 offset:49152
	ds_read_b128 v[188:191], v150 offset:50176
	ds_read_b128 v[192:195], v150 offset:51200
	ds_read_b128 v[196:199], v150 offset:52224
	ds_read_b128 v[200:203], v150 offset:53248
	ds_read_b128 v[204:207], v150 offset:54272
	ds_read_b128 v[208:211], v150 offset:55296
	ds_read_b128 v[216:219], v150 offset:56320
	global_load_lds_dwordx4 v[140:141], off
	s_add_i32 m0, s34, 0x2000
	s_add_u32 s34, s54, 0x10080
	v_lshl_add_u64 v[140:141], v[220:221], 0, s[28:29]
	s_addc_u32 s35, s55, 0
	s_add_i32 s41, s49, s2
	global_load_lds_dwordx4 v[140:141], off
	v_lshl_add_u64 v[140:141], s[34:35], 0, v[130:131]
	s_mov_b32 m0, s41
	s_nop 0
	global_load_lds_dwordx4 v[140:141], off
	v_lshl_add_u64 v[140:141], s[34:35], 0, v[134:135]
	s_add_i32 m0, s41, 0x2000
	s_nop 0
	global_load_lds_dwordx4 v[140:141], off
	v_lshl_add_u64 v[140:141], v[222:223], 0, s[28:29]
	s_mov_b32 m0, s14
	s_nop 0
	global_load_lds_dwordx4 v[140:141], off
	v_lshl_add_u64 v[140:141], v[224:225], 0, s[28:29]
	s_mov_b32 m0, s15
	s_nop 0
	global_load_lds_dwordx4 v[140:141], off
	s_waitcnt vmcnt(8)
	s_waitcnt lgkmcnt(0)
	s_barrier
	s_setprio 1
	s_waitcnt lgkmcnt(0)
	v_mfma_f32_16x16x32_bf16 v[60:63], v[152:155], v[184:187], v[60:63]
	v_mfma_f32_16x16x32_bf16 v[56:59], v[160:163], v[184:187], v[56:59]
	v_mfma_f32_16x16x32_bf16 v[44:47], v[152:155], v[192:195], v[44:47]
	v_mfma_f32_16x16x32_bf16 v[40:43], v[160:163], v[192:195], v[40:43]
	v_mfma_f32_16x16x32_bf16 v[28:31], v[152:155], v[200:203], v[28:31]
	v_mfma_f32_16x16x32_bf16 v[24:27], v[160:163], v[200:203], v[24:27]
	v_mfma_f32_16x16x32_bf16 v[12:15], v[152:155], v[208:211], v[12:15]
	v_mfma_f32_16x16x32_bf16 v[8:11], v[160:163], v[208:211], v[8:11]
	v_mfma_f32_16x16x32_bf16 v[60:63], v[156:159], v[188:191], v[60:63]
	v_mfma_f32_16x16x32_bf16 v[56:59], v[164:167], v[188:191], v[56:59]
	v_mfma_f32_16x16x32_bf16 v[44:47], v[156:159], v[196:199], v[44:47]
	v_mfma_f32_16x16x32_bf16 v[40:43], v[164:167], v[196:199], v[40:43]
	v_mfma_f32_16x16x32_bf16 v[28:31], v[156:159], v[204:207], v[28:31]
	v_mfma_f32_16x16x32_bf16 v[24:27], v[164:167], v[204:207], v[24:27]
	v_mfma_f32_16x16x32_bf16 v[12:15], v[156:159], v[216:219], v[12:15]
	v_mfma_f32_16x16x32_bf16 v[8:11], v[164:167], v[216:219], v[8:11]
	v_mfma_f32_16x16x32_bf16 v[52:55], v[168:171], v[184:187], v[52:55]
	v_mfma_f32_16x16x32_bf16 v[48:51], v[176:179], v[184:187], v[48:51]
	v_mfma_f32_16x16x32_bf16 v[36:39], v[168:171], v[192:195], v[36:39]
	v_mfma_f32_16x16x32_bf16 v[32:35], v[176:179], v[192:195], v[32:35]
	v_mfma_f32_16x16x32_bf16 v[20:23], v[168:171], v[200:203], v[20:23]
	v_mfma_f32_16x16x32_bf16 v[16:19], v[176:179], v[200:203], v[16:19]
	v_mfma_f32_16x16x32_bf16 v[4:7], v[168:171], v[208:211], v[4:7]
	v_mfma_f32_16x16x32_bf16 v[0:3], v[176:179], v[208:211], v[0:3]
	v_mfma_f32_16x16x32_bf16 v[52:55], v[172:175], v[188:191], v[52:55]
	v_mfma_f32_16x16x32_bf16 v[48:51], v[180:183], v[188:191], v[48:51]
	v_mfma_f32_16x16x32_bf16 v[36:39], v[172:175], v[196:199], v[36:39]
	v_mfma_f32_16x16x32_bf16 v[32:35], v[180:183], v[196:199], v[32:35]
	v_mfma_f32_16x16x32_bf16 v[20:23], v[172:175], v[204:207], v[20:23]
	v_mfma_f32_16x16x32_bf16 v[16:19], v[180:183], v[204:207], v[16:19]
	v_mfma_f32_16x16x32_bf16 v[4:7], v[172:175], v[216:219], v[4:7]
	v_mfma_f32_16x16x32_bf16 v[0:3], v[180:183], v[216:219], v[0:3]
	s_setprio 0
	s_barrier
	s_add_i32 s33, s33, 2
	s_add_u32 s52, s52, 0x100
	s_addc_u32 s53, s53, 0
	s_add_u32 s23, s23, 0x100
	s_addc_u32 s31, s31, 0
	s_cmp_gt_u32 s33, 13
	s_cbranch_scc0 .LBB0_691
	s_and_b64 vcc, exec, s[36:37]
	s_cbranch_vccz .LBB0_694
	s_barrier

; #define STAGE(bufoff, gbase) STAGE_(bufoff, gbase, voffA)
; #define STAGEB(bufoff, gbase) STAGE_(bufoff, gbase, voffB)
; #define LDA(dst, b, h) do { _Pragma("unroll") for (int m = 0; m < 4; ++m) _Pragma("unroll") for (int k = 0; k < 2; ++k) dst[m][k] = *LDSP(const bf16x8, lds + SA(b, h) + aoff + m * 2048 + k * 1024); } while (0)
; #define LDB(dst, b, h) do { _Pragma("unroll") for (int n = 0; n < 2; ++n) _Pragma("unroll") for (int k = 0; k < 2; ++k) dst[n][k] = *LDSP(const bf16x8, lds + SB(b, h) + boff + n * 2048 + k * 1024); } while (0)
; #define MMA(ai, bj, AT, BT) do { __builtin_amdgcn_s_setprio(1); \
;     _Pragma("unroll") for (int m = 0; m < 4; ++m) _Pragma("unroll") for (int n = 0; n < 2; ++n) _Pragma("unroll") for (int k = 0; k < 2; ++k) \
;       acc[ai][bj][m][n] = __builtin_amdgcn_mfma_f32_16x16x32_bf16(BT[n][k], AT[m][k], acc[ai][bj][m][n], 0, 0, 0); \
;     __builtin_amdgcn_s_setprio(0); } while (0)
; #define WAIT_V(n) asm volatile("s_waitcnt vmcnt(" #n ")" ::: "memory")
; #define WAIT_L(n) asm volatile("s_waitcnt lgkmcnt(" #n ")" ::: "memory")
; #define BAR __builtin_amdgcn_s_barrier()
; #define SCHED __builtin_amdgcn_sched_barrier(0)
; #define WAIT_V(n) asm volatile("s_waitcnt vmcnt(" #n ")" ::: "memory")
; #define BAR do { __builtin_amdgcn_sched_barrier(0); __builtin_amdgcn_s_barrier(); asm volatile("" ::: "memory"); __builtin_amdgcn_sched_barrier(0); } while (0)
; template <bool SP2, bool ALIGN_EPI, bool DUAL, class Epi> DI void gemm_phase2(const bf16_t* A, const bf16_t* Bt, const bf16_t* A2, const bf16_t* Bt2, int M, int N, int K, const Epi& E, lds_t* lds) {
;     ...
;       const bool last = (t == nt - 2);
;       const char* a1 = cA + (size_t)(t + 1) * kstep;
;       const char* a2 = last ? nA : cA + (size_t)(t + 2) * kstep; const char* b2 = last ? nB : cB + (size_t)(t + 2) * kstep;
;       const char* a3 = a2 + kstep; const char* b3 = b2 + kstep;
;       if constexpr (SP2) {
;         LDB(B0, 0, 0); LDB(B1, 0, 1); SCHED; LDA(At, 0, 0); STAGE(SA(1, 1), a1 + hstep);
;         WAIT_V(8); WAIT_L(0); BAR; MMA(0, 0, At, B0); MMA(0, 1, At, B1); BAR; SCHED;
;         LDA(At, 0, 1); STAGEB(SB(0, 0), b2); STAGEB(SB(0, 1), b2 + bstep); STAGE(SA(0, 0), a2);
;         WAIT_V(8); WAIT_L(0); BAR; MMA(1, 0, At, B0); MMA(1, 1, At, B1); BAR; SCHED;
.LBB0_760:
	ds_read_b128 v[150:153], v146
	ds_read_b128 v[154:157], v146 offset:1024
	ds_read_b128 v[158:161], v146 offset:2048
	ds_read_b128 v[162:165], v146 offset:3072
	ds_read_b128 v[166:169], v147
	ds_read_b128 v[170:173], v147 offset:1024
	ds_read_b128 v[174:177], v147 offset:2048
	ds_read_b128 v[178:181], v147 offset:3072
	s_add_u32 s46, s44, 0xfffc0080
	s_addc_u32 s47, s45, -1
	s_cmp_eq_u32 s50, 12
	s_cselect_b32 s49, s0, s47
	s_cselect_b32 s48, s27, s46
	s_cselect_b32 s47, s31, s43
	s_cselect_b32 s46, s34, s35
	v_lshl_add_u64 v[210:211], s[44:45], 0, v[136:137]
	s_add_i32 m0, s3, 0xc000
	ds_read_b128 v[182:185], v148
	ds_read_b128 v[186:189], v148 offset:1024
	ds_read_b128 v[190:193], v148 offset:2048
	ds_read_b128 v[194:197], v148 offset:3072
	ds_read_b128 v[198:201], v148 offset:4096
	ds_read_b128 v[202:205], v148 offset:5120
	ds_read_b128 v[206:209], v148 offset:6144
	ds_read_b128 v[216:219], v148 offset:7168
	global_load_lds_dwordx4 v[210:211], off
	v_lshl_add_u64 v[210:211], s[44:45], 0, v[138:139]
	s_add_i32 m0, s3, 0xe000
	s_nop 0
	global_load_lds_dwordx4 v[210:211], off
	s_waitcnt vmcnt(8)
	s_waitcnt lgkmcnt(0)
	s_barrier
	s_setprio 1
	s_waitcnt lgkmcnt(0)
	v_mfma_f32_16x16x32_bf16 v[124:127], v[150:153], v[182:185], v[124:127]
	v_mfma_f32_16x16x32_bf16 v[120:123], v[158:161], v[182:185], v[120:123]
	v_mfma_f32_16x16x32_bf16 v[108:111], v[150:153], v[190:193], v[108:111]
	v_mfma_f32_16x16x32_bf16 v[104:107], v[158:161], v[190:193], v[104:107]
	v_mfma_f32_16x16x32_bf16 v[92:95], v[150:153], v[198:201], v[92:95]
	v_mfma_f32_16x16x32_bf16 v[88:91], v[158:161], v[198:201], v[88:91]
	v_mfma_f32_16x16x32_bf16 v[76:79], v[150:153], v[206:209], v[76:79]
	v_mfma_f32_16x16x32_bf16 v[72:75], v[158:161], v[206:209], v[72:75]
	v_mfma_f32_16x16x32_bf16 v[124:127], v[154:157], v[186:189], v[124:127]
	v_mfma_f32_16x16x32_bf16 v[120:123], v[162:165], v[186:189], v[120:123]
	v_mfma_f32_16x16x32_bf16 v[108:111], v[154:157], v[194:197], v[108:111]
	v_mfma_f32_16x16x32_bf16 v[104:107], v[162:165], v[194:197], v[104:107]
	v_mfma_f32_16x16x32_bf16 v[92:95], v[154:157], v[202:205], v[92:95]
	v_mfma_f32_16x16x32_bf16 v[88:91], v[162:165], v[202:205], v[88:91]
	v_mfma_f32_16x16x32_bf16 v[76:79], v[154:157], v[216:219], v[76:79]
	v_mfma_f32_16x16x32_bf16 v[72:75], v[162:165], v[216:219], v[72:75]
	v_mfma_f32_16x16x32_bf16 v[116:119], v[166:169], v[182:185], v[116:119]
	v_mfma_f32_16x16x32_bf16 v[112:115], v[174:177], v[182:185], v[112:115]
	v_mfma_f32_16x16x32_bf16 v[100:103], v[166:169], v[190:193], v[100:103]
	v_mfma_f32_16x16x32_bf16 v[96:99], v[174:177], v[190:193], v[96:99]
	v_mfma_f32_16x16x32_bf16 v[84:87], v[166:169], v[198:201], v[84:87]
	v_mfma_f32_16x16x32_bf16 v[80:83], v[174:177], v[198:201], v[80:83]
	v_mfma_f32_16x16x32_bf16 v[68:71], v[166:169], v[206:209], v[68:71]
	v_mfma_f32_16x16x32_bf16 v[64:67], v[174:177], v[206:209], v[64:67]
	v_mfma_f32_16x16x32_bf16 v[116:119], v[170:173], v[186:189], v[116:119]
	v_mfma_f32_16x16x32_bf16 v[112:115], v[178:181], v[186:189], v[112:115]
	v_mfma_f32_16x16x32_bf16 v[100:103], v[170:173], v[194:197], v[100:103]
	v_mfma_f32_16x16x32_bf16 v[96:99], v[178:181], v[194:197], v[96:99]
	v_mfma_f32_16x16x32_bf16 v[84:87], v[170:173], v[202:205], v[84:87]
	v_mfma_f32_16x16x32_bf16 v[80:83], v[178:181], v[202:205], v[80:83]
	v_mfma_f32_16x16x32_bf16 v[68:71], v[170:173], v[216:219], v[68:71]
	v_mfma_f32_16x16x32_bf16 v[64:67], v[178:181], v[216:219], v[64:67]
	s_setprio 0
	s_barrier
	s_add_i32 s51, s19, s2
	v_lshl_add_u64 v[210:211], s[46:47], 0, v[132:133]
	s_mov_b32 m0, s51
	ds_read_b128 v[182:185], v148 offset:16384
	ds_read_b128 v[186:189], v148 offset:17408
	ds_read_b128 v[190:193], v148 offset:18432
	ds_read_b128 v[194:197], v148 offset:19456
	ds_read_b128 v[198:201], v148 offset:20480
	ds_read_b128 v[202:205], v148 offset:21504
	ds_read_b128 v[206:209], v148 offset:22528
	ds_read_b128 v[216:219], v148 offset:23552
	global_load_lds_dwordx4 v[210:211], off
	s_add_i32 m0, s51, 0x2000
	s_add_u32 s52, s46, 0x10000
	v_lshl_add_u64 v[220:221], s[46:47], 0, v[128:129]
	s_addc_u32 s53, s47, 0
	s_add_i32 s51, s20, s2
	global_load_lds_dwordx4 v[220:221], off
	v_lshl_add_u64 v[222:223], s[52:53], 0, v[132:133]
	s_mov_b32 m0, s51
	v_lshl_add_u64 v[224:225], s[48:49], 0, v[130:131]
	global_load_lds_dwordx4 v[222:223], off
	v_lshl_add_u64 v[222:223], s[52:53], 0, v[128:129]
	s_add_i32 m0, s51, 0x2000
	s_nop 0
	global_load_lds_dwordx4 v[222:223], off
	v_lshl_add_u64 v[222:223], s[48:49], 0, v[134:135]
	s_mov_b32 m0, s3
	s_nop 0
	global_load_lds_dwordx4 v[222:223], off
	s_mov_b32 m0, s8
	s_nop 0
	global_load_lds_dwordx4 v[224:225], off
	s_waitcnt vmcnt(8)
	s_waitcnt lgkmcnt(0)
	s_barrier
; #define STAGE(bufoff, gbase) STAGE_(bufoff, gbase, voffA)
; #define LDA(dst, b, h) do { _Pragma("unroll") for (int m = 0; m < 4; ++m) _Pragma("unroll") for (int k = 0; k < 2; ++k) dst[m][k] = *LDSP(const bf16x8, lds + SA(b, h) + aoff + m * 2048 + k * 1024); } while (0)
; #define LDB(dst, b, h) do { _Pragma("unroll") for (int n = 0; n < 2; ++n) _Pragma("unroll") for (int k = 0; k < 2; ++k) dst[n][k] = *LDSP(const bf16x8, lds + SB(b, h) + boff + n * 2048 + k * 1024); } while (0)
; #define MMA(ai, bj, AT, BT) do { __builtin_amdgcn_s_setprio(1); \
;     _Pragma("unroll") for (int m = 0; m < 4; ++m) _Pragma("unroll") for (int n = 0; n < 2; ++n) _Pragma("unroll") for (int k = 0; k < 2; ++k) \
;       acc[ai][bj][m][n] = __builtin_amdgcn_mfma_f32_16x16x32_bf16(BT[n][k], AT[m][k], acc[ai][bj][m][n], 0, 0, 0); \
;     __builtin_amdgcn_s_setprio(0); } while (0)
; #define WAIT_V(n) asm volatile("s_waitcnt vmcnt(" #n ")" ::: "memory")
; #define WAIT_L(n) asm volatile("s_waitcnt lgkmcnt(" #n ")" ::: "memory")
; #define BAR __builtin_amdgcn_s_barrier()
; #define SCHED __builtin_amdgcn_sched_barrier(0)
; #define WAIT_V(n) asm volatile("s_waitcnt vmcnt(" #n ")" ::: "memory")
; #define BAR do { __builtin_amdgcn_sched_barrier(0); __builtin_amdgcn_s_barrier(); asm volatile("" ::: "memory"); __builtin_amdgcn_sched_barrier(0); } while (0)
; template <bool SP2, bool ALIGN_EPI, bool DUAL, class Epi> DI void gemm_phase2(const bf16_t* A, const bf16_t* Bt, const bf16_t* A2, const bf16_t* Bt2, int M, int N, int K, const Epi& E, lds_t* lds) {
;     ...
;         WAIT_V(8); WAIT_L(0); BAR; MMA(1, 0, At, B0); MMA(1, 1, At, B1); BAR; SCHED;
;         LDB(B0, 1, 0); LDB(B1, 1, 1); SCHED; LDA(At, 1, 0); STAGE(SA(0, 1), a2 + hstep);
;         WAIT_V(8); WAIT_L(0); BAR; MMA(0, 0, At, B0); MMA(0, 1, At, B1); BAR; SCHED;
	s_setprio 1
	s_waitcnt lgkmcnt(0)
	v_mfma_f32_16x16x32_bf16 v[60:63], v[150:153], v[182:185], v[60:63]
	v_mfma_f32_16x16x32_bf16 v[56:59], v[158:161], v[182:185], v[56:59]
	v_mfma_f32_16x16x32_bf16 v[44:47], v[150:153], v[190:193], v[44:47]
	v_mfma_f32_16x16x32_bf16 v[40:43], v[158:161], v[190:193], v[40:43]
	v_mfma_f32_16x16x32_bf16 v[28:31], v[150:153], v[198:201], v[28:31]
	v_mfma_f32_16x16x32_bf16 v[24:27], v[158:161], v[198:201], v[24:27]
	v_mfma_f32_16x16x32_bf16 v[12:15], v[150:153], v[206:209], v[12:15]
	v_mfma_f32_16x16x32_bf16 v[8:11], v[158:161], v[206:209], v[8:11]
	v_mfma_f32_16x16x32_bf16 v[60:63], v[154:157], v[186:189], v[60:63]
	v_mfma_f32_16x16x32_bf16 v[56:59], v[162:165], v[186:189], v[56:59]
	v_mfma_f32_16x16x32_bf16 v[44:47], v[154:157], v[194:197], v[44:47]
	v_mfma_f32_16x16x32_bf16 v[40:43], v[162:165], v[194:197], v[40:43]
	v_mfma_f32_16x16x32_bf16 v[28:31], v[154:157], v[202:205], v[28:31]
	v_mfma_f32_16x16x32_bf16 v[24:27], v[162:165], v[202:205], v[24:27]
	v_mfma_f32_16x16x32_bf16 v[12:15], v[154:157], v[216:219], v[12:15]
	v_mfma_f32_16x16x32_bf16 v[8:11], v[162:165], v[216:219], v[8:11]
	v_mfma_f32_16x16x32_bf16 v[52:55], v[166:169], v[182:185], v[52:55]
	v_mfma_f32_16x16x32_bf16 v[48:51], v[174:177], v[182:185], v[48:51]
	v_mfma_f32_16x16x32_bf16 v[36:39], v[166:169], v[190:193], v[36:39]
	v_mfma_f32_16x16x32_bf16 v[32:35], v[174:177], v[190:193], v[32:35]
	v_mfma_f32_16x16x32_bf16 v[20:23], v[166:169], v[198:201], v[20:23]
	v_mfma_f32_16x16x32_bf16 v[16:19], v[174:177], v[198:201], v[16:19]
	v_mfma_f32_16x16x32_bf16 v[4:7], v[166:169], v[206:209], v[4:7]
	v_mfma_f32_16x16x32_bf16 v[0:3], v[174:177], v[206:209], v[0:3]
	v_mfma_f32_16x16x32_bf16 v[52:55], v[170:173], v[186:189], v[52:55]
	v_mfma_f32_16x16x32_bf16 v[48:51], v[178:181], v[186:189], v[48:51]
	v_mfma_f32_16x16x32_bf16 v[36:39], v[170:173], v[194:197], v[36:39]
	v_mfma_f32_16x16x32_bf16 v[32:35], v[178:181], v[194:197], v[32:35]
	v_mfma_f32_16x16x32_bf16 v[20:23], v[170:173], v[202:205], v[20:23]
	v_mfma_f32_16x16x32_bf16 v[16:19], v[178:181], v[202:205], v[16:19]
	v_mfma_f32_16x16x32_bf16 v[4:7], v[170:173], v[216:219], v[4:7]
	v_mfma_f32_16x16x32_bf16 v[0:3], v[178:181], v[216:219], v[0:3]
	s_setprio 0
	s_barrier
	s_add_i32 s51, 0, 0x18000
	s_add_i32 s52, 0, 0x1c000
	v_add_u32_e32 v162, s51, v141
	v_add_u32_e32 v178, s52, v141
	ds_read_b128 v[150:153], v162
	ds_read_b128 v[154:157], v162 offset:1024
	ds_read_b128 v[158:161], v162 offset:2048
	ds_read_b128 v[162:165], v162 offset:3072
	ds_read_b128 v[166:169], v178
	ds_read_b128 v[170:173], v178 offset:1024
	ds_read_b128 v[174:177], v178 offset:2048
	ds_read_b128 v[178:181], v178 offset:3072
	s_add_u32 s48, s48, 0x40000
	s_addc_u32 s49, s49, 0
	s_mov_b32 m0, s9
	v_lshl_add_u64 v[226:227], s[48:49], 0, v[134:135]
	ds_read_b128 v[182:185], v148 offset:32768
	ds_read_b128 v[186:189], v148 offset:33792
	ds_read_b128 v[190:193], v148 offset:34816
	ds_read_b128 v[194:197], v148 offset:35840
	ds_read_b128 v[198:201], v148 offset:36864
	ds_read_b128 v[202:205], v148 offset:37888
	ds_read_b128 v[206:209], v148 offset:38912
	ds_read_b128 v[216:219], v148 offset:39936
	global_load_lds_dwordx4 v[226:227], off
	v_lshl_add_u64 v[226:227], s[48:49], 0, v[130:131]
	s_mov_b32 m0, s10
	s_nop 0
	global_load_lds_dwordx4 v[226:227], off
	s_waitcnt vmcnt(8)
	s_waitcnt lgkmcnt(0)
	s_barrier
	s_setprio 1
	s_waitcnt lgkmcnt(0)
	v_mfma_f32_16x16x32_bf16 v[124:127], v[150:153], v[182:185], v[124:127]
	v_mfma_f32_16x16x32_bf16 v[120:123], v[158:161], v[182:185], v[120:123]
	v_mfma_f32_16x16x32_bf16 v[108:111], v[150:153], v[190:193], v[108:111]
	v_mfma_f32_16x16x32_bf16 v[104:107], v[158:161], v[190:193], v[104:107]
	v_mfma_f32_16x16x32_bf16 v[92:95], v[150:153], v[198:201], v[92:95]
	v_mfma_f32_16x16x32_bf16 v[88:91], v[158:161], v[198:201], v[88:91]
	v_mfma_f32_16x16x32_bf16 v[76:79], v[150:153], v[206:209], v[76:79]
	v_mfma_f32_16x16x32_bf16 v[72:75], v[158:161], v[206:209], v[72:75]
	v_mfma_f32_16x16x32_bf16 v[124:127], v[154:157], v[186:189], v[124:127]
	v_mfma_f32_16x16x32_bf16 v[120:123], v[162:165], v[186:189], v[120:123]
	v_mfma_f32_16x16x32_bf16 v[108:111], v[154:157], v[194:197], v[108:111]
	v_mfma_f32_16x16x32_bf16 v[104:107], v[162:165], v[194:197], v[104:107]
	v_mfma_f32_16x16x32_bf16 v[92:95], v[154:157], v[202:205], v[92:95]
	v_mfma_f32_16x16x32_bf16 v[88:91], v[162:165], v[202:205], v[88:91]
	v_mfma_f32_16x16x32_bf16 v[76:79], v[154:157], v[216:219], v[76:79]
	v_mfma_f32_16x16x32_bf16 v[72:75], v[162:165], v[216:219], v[72:75]
	v_mfma_f32_16x16x32_bf16 v[116:119], v[166:169], v[182:185], v[116:119]
	v_mfma_f32_16x16x32_bf16 v[112:115], v[174:177], v[182:185], v[112:115]
	v_mfma_f32_16x16x32_bf16 v[100:103], v[166:169], v[190:193], v[100:103]
	v_mfma_f32_16x16x32_bf16 v[96:99], v[174:177], v[190:193], v[96:99]
	v_mfma_f32_16x16x32_bf16 v[84:87], v[166:169], v[198:201], v[84:87]
	v_mfma_f32_16x16x32_bf16 v[80:83], v[174:177], v[198:201], v[80:83]
	v_mfma_f32_16x16x32_bf16 v[68:71], v[166:169], v[206:209], v[68:71]
	v_mfma_f32_16x16x32_bf16 v[64:67], v[174:177], v[206:209], v[64:67]
	v_mfma_f32_16x16x32_bf16 v[116:119], v[170:173], v[186:189], v[116:119]
	v_mfma_f32_16x16x32_bf16 v[112:115], v[178:181], v[186:189], v[112:115]
	v_mfma_f32_16x16x32_bf16 v[100:103], v[170:173], v[194:197], v[100:103]
	v_mfma_f32_16x16x32_bf16 v[96:99], v[178:181], v[194:197], v[96:99]
	v_mfma_f32_16x16x32_bf16 v[84:87], v[170:173], v[202:205], v[84:87]
	v_mfma_f32_16x16x32_bf16 v[80:83], v[178:181], v[202:205], v[80:83]
	v_mfma_f32_16x16x32_bf16 v[68:71], v[170:173], v[216:219], v[68:71]
	v_mfma_f32_16x16x32_bf16 v[64:67], v[178:181], v[216:219], v[64:67]
	s_setprio 0
	s_barrier
; #define STAGE(bufoff, gbase) STAGE_(bufoff, gbase, voffA)
; #define STAGEB(bufoff, gbase) STAGE_(bufoff, gbase, voffB)
; #define LDA(dst, b, h) do { _Pragma("unroll") for (int m = 0; m < 4; ++m) _Pragma("unroll") for (int k = 0; k < 2; ++k) dst[m][k] = *LDSP(const bf16x8, lds + SA(b, h) + aoff + m * 2048 + k * 1024); } while (0)
; #define LDB(dst, b, h) do { _Pragma("unroll") for (int n = 0; n < 2; ++n) _Pragma("unroll") for (int k = 0; k < 2; ++k) dst[n][k] = *LDSP(const bf16x8, lds + SB(b, h) + boff + n * 2048 + k * 1024); } while (0)
; #define MMA(ai, bj, AT, BT) do { __builtin_amdgcn_s_setprio(1); \
;     _Pragma("unroll") for (int m = 0; m < 4; ++m) _Pragma("unroll") for (int n = 0; n < 2; ++n) _Pragma("unroll") for (int k = 0; k < 2; ++k) \
;       acc[ai][bj][m][n] = __builtin_amdgcn_mfma_f32_16x16x32_bf16(BT[n][k], AT[m][k], acc[ai][bj][m][n], 0, 0, 0); \
;     __builtin_amdgcn_s_setprio(0); } while (0)
; #define WAIT_V(n) asm volatile("s_waitcnt vmcnt(" #n ")" ::: "memory")
; #define WAIT_L(n) asm volatile("s_waitcnt lgkmcnt(" #n ")" ::: "memory")
; template <bool SP2, bool ALIGN_EPI, bool DUAL, class Epi> DI void gemm_phase2(const bf16_t* A, const bf16_t* Bt, const bf16_t* A2, const bf16_t* Bt2, int M, int N, int K, const Epi& E, lds_t* lds) {
;     ...
;     for (int t = 0; t < nt; t += 2) {
;       const bool last = (t == nt - 2);
;       const char* a1 = cA + (size_t)(t + 1) * kstep;
;       const char* a2 = last ? nA : cA + (size_t)(t + 2) * kstep; const char* b2 = last ? nB : cB + (size_t)(t + 2) * kstep;
;       const char* a3 = a2 + kstep; const char* b3 = b2 + kstep;
;       if constexpr (SP2) {
;         LDB(B0, 0, 0); LDB(B1, 0, 1); SCHED; LDA(At, 0, 0); STAGE(SA(1, 1), a1 + hstep);
;         WAIT_V(8); WAIT_L(0); BAR; MMA(0, 0, At, B0); MMA(0, 1, At, B1); BAR; SCHED;
;         LDA(At, 0, 1); STAGEB(SB(0, 0), b2); STAGEB(SB(0, 1), b2 + bstep); STAGE(SA(0, 0), a2);
;         WAIT_V(8); WAIT_L(0); BAR; MMA(1, 0, At, B0); MMA(1, 1, At, B1); BAR; SCHED;
;         LDB(B0, 1, 0); LDB(B1, 1, 1); SCHED; LDA(At, 1, 0); STAGE(SA(0, 1), a2 + hstep);
;         WAIT_V(8); WAIT_L(0); BAR; MMA(0, 0, At, B0); MMA(0, 1, At, B1); BAR; SCHED;
;         LDA(At, 1, 1); STAGEB(SB(1, 0), b3); STAGEB(SB(1, 1), b3 + bstep); STAGE(SA(1, 0), a3);
;         WAIT_V(8); WAIT_L(0); BAR; MMA(1, 0, At, B0); MMA(1, 1, At, B1); BAR; SCHED;
	s_add_i32 s48, s51, s2
	v_lshl_add_u64 v[210:211], v[210:211], 0, s[22:23]
	s_mov_b32 m0, s48
	ds_read_b128 v[182:185], v148 offset:49152
	ds_read_b128 v[186:189], v148 offset:50176
	ds_read_b128 v[190:193], v148 offset:51200
	ds_read_b128 v[194:197], v148 offset:52224
	ds_read_b128 v[198:201], v148 offset:53248
	ds_read_b128 v[202:205], v148 offset:54272
	ds_read_b128 v[206:209], v148 offset:55296
	ds_read_b128 v[216:219], v148 offset:56320
	global_load_lds_dwordx4 v[210:211], off
	s_add_i32 m0, s48, 0x2000
	s_add_u32 s46, s46, 0x10080
	v_lshl_add_u64 v[210:211], v[220:221], 0, s[22:23]
	s_addc_u32 s47, s47, 0
	s_add_i32 s48, s52, s2
	global_load_lds_dwordx4 v[210:211], off
	v_lshl_add_u64 v[210:211], s[46:47], 0, v[132:133]
	s_mov_b32 m0, s48
	s_nop 0
	global_load_lds_dwordx4 v[210:211], off
	v_lshl_add_u64 v[210:211], s[46:47], 0, v[128:129]
	s_add_i32 m0, s48, 0x2000
	s_nop 0
	global_load_lds_dwordx4 v[210:211], off
	v_lshl_add_u64 v[210:211], v[222:223], 0, s[22:23]
	s_mov_b32 m0, s15
	s_nop 0
	global_load_lds_dwordx4 v[210:211], off
	v_lshl_add_u64 v[210:211], v[224:225], 0, s[22:23]
	s_mov_b32 m0, s18
	s_nop 0
	global_load_lds_dwordx4 v[210:211], off
	s_waitcnt vmcnt(8)
	s_waitcnt lgkmcnt(0)
	s_barrier
	s_setprio 1
	s_waitcnt lgkmcnt(0)
	v_mfma_f32_16x16x32_bf16 v[60:63], v[150:153], v[182:185], v[60:63]
	v_mfma_f32_16x16x32_bf16 v[56:59], v[158:161], v[182:185], v[56:59]
	v_mfma_f32_16x16x32_bf16 v[44:47], v[150:153], v[190:193], v[44:47]
	v_mfma_f32_16x16x32_bf16 v[40:43], v[158:161], v[190:193], v[40:43]
	v_mfma_f32_16x16x32_bf16 v[28:31], v[150:153], v[198:201], v[28:31]
	v_mfma_f32_16x16x32_bf16 v[24:27], v[158:161], v[198:201], v[24:27]
	v_mfma_f32_16x16x32_bf16 v[12:15], v[150:153], v[206:209], v[12:15]
	v_mfma_f32_16x16x32_bf16 v[8:11], v[158:161], v[206:209], v[8:11]
	v_mfma_f32_16x16x32_bf16 v[60:63], v[154:157], v[186:189], v[60:63]
	v_mfma_f32_16x16x32_bf16 v[56:59], v[162:165], v[186:189], v[56:59]
	v_mfma_f32_16x16x32_bf16 v[44:47], v[154:157], v[194:197], v[44:47]
	v_mfma_f32_16x16x32_bf16 v[40:43], v[162:165], v[194:197], v[40:43]
	v_mfma_f32_16x16x32_bf16 v[28:31], v[154:157], v[202:205], v[28:31]
	v_mfma_f32_16x16x32_bf16 v[24:27], v[162:165], v[202:205], v[24:27]
	v_mfma_f32_16x16x32_bf16 v[12:15], v[154:157], v[216:219], v[12:15]
	v_mfma_f32_16x16x32_bf16 v[8:11], v[162:165], v[216:219], v[8:11]
	v_mfma_f32_16x16x32_bf16 v[52:55], v[166:169], v[182:185], v[52:55]
	v_mfma_f32_16x16x32_bf16 v[48:51], v[174:177], v[182:185], v[48:51]
	v_mfma_f32_16x16x32_bf16 v[36:39], v[166:169], v[190:193], v[36:39]
	v_mfma_f32_16x16x32_bf16 v[32:35], v[174:177], v[190:193], v[32:35]
	v_mfma_f32_16x16x32_bf16 v[20:23], v[166:169], v[198:201], v[20:23]
	v_mfma_f32_16x16x32_bf16 v[16:19], v[174:177], v[198:201], v[16:19]
	v_mfma_f32_16x16x32_bf16 v[4:7], v[166:169], v[206:209], v[4:7]
	v_mfma_f32_16x16x32_bf16 v[0:3], v[174:177], v[206:209], v[0:3]
	v_mfma_f32_16x16x32_bf16 v[52:55], v[170:173], v[186:189], v[52:55]
	v_mfma_f32_16x16x32_bf16 v[48:51], v[178:181], v[186:189], v[48:51]
	v_mfma_f32_16x16x32_bf16 v[36:39], v[170:173], v[194:197], v[36:39]
	v_mfma_f32_16x16x32_bf16 v[32:35], v[178:181], v[194:197], v[32:35]
	v_mfma_f32_16x16x32_bf16 v[20:23], v[170:173], v[202:205], v[20:23]
	v_mfma_f32_16x16x32_bf16 v[16:19], v[178:181], v[202:205], v[16:19]
	v_mfma_f32_16x16x32_bf16 v[4:7], v[170:173], v[216:219], v[4:7]
	v_mfma_f32_16x16x32_bf16 v[0:3], v[178:181], v[216:219], v[0:3]
	s_setprio 0
	s_barrier
	s_add_i32 s50, s50, 2
	s_add_u32 s44, s44, 0x100
	s_addc_u32 s45, s45, 0
	s_add_u32 s35, s35, 0x100
	s_addc_u32 s43, s43, 0
	s_cmp_gt_u32 s50, 13
	s_cbranch_scc0 .LBB0_760
	s_and_b64 vcc, exec, s[28:29]
	s_cbranch_vccz .LBB0_763
	s_barrier

; #define STAGE(bufoff, gbase) STAGE_(bufoff, gbase, voffA)
; #define STAGEB(bufoff, gbase) STAGE_(bufoff, gbase, voffB)
; #define LDA(dst, b, h) do { _Pragma("unroll") for (int m = 0; m < 4; ++m) _Pragma("unroll") for (int k = 0; k < 2; ++k) dst[m][k] = *LDSP(const bf16x8, lds + SA(b, h) + aoff + m * 2048 + k * 1024); } while (0)
; #define LDB(dst, b, h) do { _Pragma("unroll") for (int n = 0; n < 2; ++n) _Pragma("unroll") for (int k = 0; k < 2; ++k) dst[n][k] = *LDSP(const bf16x8, lds + SB(b, h) + boff + n * 2048 + k * 1024); } while (0)
; #define MMA(ai, bj, AT, BT) do { __builtin_amdgcn_s_setprio(1); \
;     _Pragma("unroll") for (int m = 0; m < 4; ++m) _Pragma("unroll") for (int n = 0; n < 2; ++n) _Pragma("unroll") for (int k = 0; k < 2; ++k) \
;       acc[ai][bj][m][n] = __builtin_amdgcn_mfma_f32_16x16x32_bf16(BT[n][k], AT[m][k], acc[ai][bj][m][n], 0, 0, 0); \
;     __builtin_amdgcn_s_setprio(0); } while (0)
; #define WAIT_V(n) asm volatile("s_waitcnt vmcnt(" #n ")" ::: "memory")
; #define WAIT_L(n) asm volatile("s_waitcnt lgkmcnt(" #n ")" ::: "memory")
; #define BAR __builtin_amdgcn_s_barrier()
; #define SCHED __builtin_amdgcn_sched_barrier(0)
; #define WAIT_V(n) asm volatile("s_waitcnt vmcnt(" #n ")" ::: "memory")
; #define BAR do { __builtin_amdgcn_sched_barrier(0); __builtin_amdgcn_s_barrier(); asm volatile("" ::: "memory"); __builtin_amdgcn_sched_barrier(0); } while (0)
; template <bool SP2, bool ALIGN_EPI, bool DUAL, class Epi> DI void gemm_phase2(const bf16_t* A, const bf16_t* Bt, const bf16_t* A2, const bf16_t* Bt2, int M, int N, int K, const Epi& E, lds_t* lds) {
;     ...
;       const bool last = (t == nt - 2);
;       const char* a1 = cA + (size_t)(t + 1) * kstep;
;       const char* a2 = last ? nA : cA + (size_t)(t + 2) * kstep; const char* b2 = last ? nB : cB + (size_t)(t + 2) * kstep;
;       const char* a3 = a2 + kstep; const char* b3 = b2 + kstep;
;       if constexpr (SP2) {
;         LDB(B0, 0, 0); LDB(B1, 0, 1); SCHED; LDA(At, 0, 0); STAGE(SA(1, 1), a1 + hstep);
;         WAIT_V(8); WAIT_L(0); BAR; MMA(0, 0, At, B0); MMA(0, 1, At, B1); BAR; SCHED;
;         LDA(At, 0, 1); STAGEB(SB(0, 0), b2); STAGEB(SB(0, 1), b2 + bstep); STAGE(SA(0, 0), a2);
;         WAIT_V(8); WAIT_L(0); BAR; MMA(1, 0, At, B0); MMA(1, 1, At, B1); BAR; SCHED;
.LBB0_824:
	ds_read_b128 v[152:155], v149
	ds_read_b128 v[156:159], v149 offset:1024
	ds_read_b128 v[160:163], v149 offset:2048
	ds_read_b128 v[164:167], v149 offset:3072
	ds_read_b128 v[168:171], v150
	ds_read_b128 v[172:175], v150 offset:1024
	ds_read_b128 v[176:179], v150 offset:2048
	ds_read_b128 v[180:183], v150 offset:3072
	s_add_u32 s45, s46, 0xfff00080
	s_addc_u32 s48, s47, -1
	s_cmp_eq_u32 s39, 60
	s_cselect_b32 s51, s0, s48
	s_cselect_b32 s50, s1, s45
	s_cselect_b32 s49, s7, s35
	s_cselect_b32 s48, s27, s34
	v_lshl_add_u64 v[140:141], s[46:47], 0, v[136:137]
	s_add_i32 m0, s3, 0xc000
	ds_read_b128 v[184:187], v151
	ds_read_b128 v[188:191], v151 offset:1024
	ds_read_b128 v[192:195], v151 offset:2048
	ds_read_b128 v[196:199], v151 offset:3072
	ds_read_b128 v[200:203], v151 offset:4096
	ds_read_b128 v[204:207], v151 offset:5120
	ds_read_b128 v[208:211], v151 offset:6144
	ds_read_b128 v[216:219], v151 offset:7168
	global_load_lds_dwordx4 v[140:141], off
	v_lshl_add_u64 v[140:141], s[46:47], 0, v[138:139]
	s_add_i32 m0, s3, 0xe000
	s_nop 0
	global_load_lds_dwordx4 v[140:141], off
	s_waitcnt vmcnt(8)
	s_waitcnt lgkmcnt(0)
	s_barrier
	s_setprio 1
	s_waitcnt lgkmcnt(0)
	v_mfma_f32_16x16x32_bf16 v[124:127], v[152:155], v[184:187], v[124:127]
	v_mfma_f32_16x16x32_bf16 v[120:123], v[160:163], v[184:187], v[120:123]
	v_mfma_f32_16x16x32_bf16 v[108:111], v[152:155], v[192:195], v[108:111]
	v_mfma_f32_16x16x32_bf16 v[104:107], v[160:163], v[192:195], v[104:107]
	v_mfma_f32_16x16x32_bf16 v[92:95], v[152:155], v[200:203], v[92:95]
	v_mfma_f32_16x16x32_bf16 v[88:91], v[160:163], v[200:203], v[88:91]
	v_mfma_f32_16x16x32_bf16 v[76:79], v[152:155], v[208:211], v[76:79]
	v_mfma_f32_16x16x32_bf16 v[72:75], v[160:163], v[208:211], v[72:75]
	v_mfma_f32_16x16x32_bf16 v[124:127], v[156:159], v[188:191], v[124:127]
	v_mfma_f32_16x16x32_bf16 v[120:123], v[164:167], v[188:191], v[120:123]
	v_mfma_f32_16x16x32_bf16 v[108:111], v[156:159], v[196:199], v[108:111]
	v_mfma_f32_16x16x32_bf16 v[104:107], v[164:167], v[196:199], v[104:107]
	v_mfma_f32_16x16x32_bf16 v[92:95], v[156:159], v[204:207], v[92:95]
	v_mfma_f32_16x16x32_bf16 v[88:91], v[164:167], v[204:207], v[88:91]
	v_mfma_f32_16x16x32_bf16 v[76:79], v[156:159], v[216:219], v[76:79]
	v_mfma_f32_16x16x32_bf16 v[72:75], v[164:167], v[216:219], v[72:75]
	v_mfma_f32_16x16x32_bf16 v[116:119], v[168:171], v[184:187], v[116:119]
	v_mfma_f32_16x16x32_bf16 v[112:115], v[176:179], v[184:187], v[112:115]
	v_mfma_f32_16x16x32_bf16 v[100:103], v[168:171], v[192:195], v[100:103]
	v_mfma_f32_16x16x32_bf16 v[96:99], v[176:179], v[192:195], v[96:99]
	v_mfma_f32_16x16x32_bf16 v[84:87], v[168:171], v[200:203], v[84:87]
	v_mfma_f32_16x16x32_bf16 v[80:83], v[176:179], v[200:203], v[80:83]
	v_mfma_f32_16x16x32_bf16 v[68:71], v[168:171], v[208:211], v[68:71]
	v_mfma_f32_16x16x32_bf16 v[64:67], v[176:179], v[208:211], v[64:67]
	v_mfma_f32_16x16x32_bf16 v[116:119], v[172:175], v[188:191], v[116:119]
	v_mfma_f32_16x16x32_bf16 v[112:115], v[180:183], v[188:191], v[112:115]
	v_mfma_f32_16x16x32_bf16 v[100:103], v[172:175], v[196:199], v[100:103]
	v_mfma_f32_16x16x32_bf16 v[96:99], v[180:183], v[196:199], v[96:99]
	v_mfma_f32_16x16x32_bf16 v[84:87], v[172:175], v[204:207], v[84:87]
	v_mfma_f32_16x16x32_bf16 v[80:83], v[180:183], v[204:207], v[80:83]
	v_mfma_f32_16x16x32_bf16 v[68:71], v[172:175], v[216:219], v[68:71]
	v_mfma_f32_16x16x32_bf16 v[64:67], v[180:183], v[216:219], v[64:67]
	s_setprio 0
	s_barrier
	s_add_i32 s45, s18, s2
	v_lshl_add_u64 v[140:141], s[48:49], 0, v[130:131]
	s_mov_b32 m0, s45
	ds_read_b128 v[184:187], v151 offset:16384
	ds_read_b128 v[188:191], v151 offset:17408
	ds_read_b128 v[192:195], v151 offset:18432
	ds_read_b128 v[196:199], v151 offset:19456
	ds_read_b128 v[200:203], v151 offset:20480
	ds_read_b128 v[204:207], v151 offset:21504
	ds_read_b128 v[208:211], v151 offset:22528
	ds_read_b128 v[216:219], v151 offset:23552
	global_load_lds_dwordx4 v[140:141], off
	s_add_i32 m0, s45, 0x2000
	s_add_u32 s52, s48, 0x40000
	v_lshl_add_u64 v[220:221], s[48:49], 0, v[134:135]
	s_addc_u32 s53, s49, 0
	s_add_i32 s45, s19, s2
	global_load_lds_dwordx4 v[220:221], off
	v_lshl_add_u64 v[222:223], s[52:53], 0, v[130:131]
	s_mov_b32 m0, s45
	v_lshl_add_u64 v[224:225], s[50:51], 0, v[132:133]
	global_load_lds_dwordx4 v[222:223], off
	v_lshl_add_u64 v[222:223], s[52:53], 0, v[134:135]
	s_add_i32 m0, s45, 0x2000
	s_nop 0
	global_load_lds_dwordx4 v[222:223], off
	v_lshl_add_u64 v[222:223], s[50:51], 0, v[128:129]
	s_mov_b32 m0, s3
	s_nop 0
	global_load_lds_dwordx4 v[222:223], off
	s_mov_b32 m0, s8
	s_nop 0
	global_load_lds_dwordx4 v[224:225], off
	s_waitcnt vmcnt(8)
	s_waitcnt lgkmcnt(0)
	s_barrier
; #define STAGE(bufoff, gbase) STAGE_(bufoff, gbase, voffA)
; #define LDA(dst, b, h) do { _Pragma("unroll") for (int m = 0; m < 4; ++m) _Pragma("unroll") for (int k = 0; k < 2; ++k) dst[m][k] = *LDSP(const bf16x8, lds + SA(b, h) + aoff + m * 2048 + k * 1024); } while (0)
; #define LDB(dst, b, h) do { _Pragma("unroll") for (int n = 0; n < 2; ++n) _Pragma("unroll") for (int k = 0; k < 2; ++k) dst[n][k] = *LDSP(const bf16x8, lds + SB(b, h) + boff + n * 2048 + k * 1024); } while (0)
; #define MMA(ai, bj, AT, BT) do { __builtin_amdgcn_s_setprio(1); \
;     _Pragma("unroll") for (int m = 0; m < 4; ++m) _Pragma("unroll") for (int n = 0; n < 2; ++n) _Pragma("unroll") for (int k = 0; k < 2; ++k) \
;       acc[ai][bj][m][n] = __builtin_amdgcn_mfma_f32_16x16x32_bf16(BT[n][k], AT[m][k], acc[ai][bj][m][n], 0, 0, 0); \
;     __builtin_amdgcn_s_setprio(0); } while (0)
; #define WAIT_V(n) asm volatile("s_waitcnt vmcnt(" #n ")" ::: "memory")
; #define WAIT_L(n) asm volatile("s_waitcnt lgkmcnt(" #n ")" ::: "memory")
; #define BAR __builtin_amdgcn_s_barrier()
; #define SCHED __builtin_amdgcn_sched_barrier(0)
; #define WAIT_V(n) asm volatile("s_waitcnt vmcnt(" #n ")" ::: "memory")
; #define BAR do { __builtin_amdgcn_sched_barrier(0); __builtin_amdgcn_s_barrier(); asm volatile("" ::: "memory"); __builtin_amdgcn_sched_barrier(0); } while (0)
; template <bool SP2, bool ALIGN_EPI, bool DUAL, class Epi> DI void gemm_phase2(const bf16_t* A, const bf16_t* Bt, const bf16_t* A2, const bf16_t* Bt2, int M, int N, int K, const Epi& E, lds_t* lds) {
;     ...
;         WAIT_V(8); WAIT_L(0); BAR; MMA(1, 0, At, B0); MMA(1, 1, At, B1); BAR; SCHED;
;         LDB(B0, 1, 0); LDB(B1, 1, 1); SCHED; LDA(At, 1, 0); STAGE(SA(0, 1), a2 + hstep);
;         WAIT_V(8); WAIT_L(0); BAR; MMA(0, 0, At, B0); MMA(0, 1, At, B1); BAR; SCHED;
	s_setprio 1
	s_waitcnt lgkmcnt(0)
	v_mfma_f32_16x16x32_bf16 v[60:63], v[152:155], v[184:187], v[60:63]
	v_mfma_f32_16x16x32_bf16 v[56:59], v[160:163], v[184:187], v[56:59]
	v_mfma_f32_16x16x32_bf16 v[44:47], v[152:155], v[192:195], v[44:47]
	v_mfma_f32_16x16x32_bf16 v[40:43], v[160:163], v[192:195], v[40:43]
	v_mfma_f32_16x16x32_bf16 v[28:31], v[152:155], v[200:203], v[28:31]
	v_mfma_f32_16x16x32_bf16 v[24:27], v[160:163], v[200:203], v[24:27]
	v_mfma_f32_16x16x32_bf16 v[12:15], v[152:155], v[208:211], v[12:15]
	v_mfma_f32_16x16x32_bf16 v[8:11], v[160:163], v[208:211], v[8:11]
	v_mfma_f32_16x16x32_bf16 v[60:63], v[156:159], v[188:191], v[60:63]
	v_mfma_f32_16x16x32_bf16 v[56:59], v[164:167], v[188:191], v[56:59]
	v_mfma_f32_16x16x32_bf16 v[44:47], v[156:159], v[196:199], v[44:47]
	v_mfma_f32_16x16x32_bf16 v[40:43], v[164:167], v[196:199], v[40:43]
	v_mfma_f32_16x16x32_bf16 v[28:31], v[156:159], v[204:207], v[28:31]
	v_mfma_f32_16x16x32_bf16 v[24:27], v[164:167], v[204:207], v[24:27]
	v_mfma_f32_16x16x32_bf16 v[12:15], v[156:159], v[216:219], v[12:15]
	v_mfma_f32_16x16x32_bf16 v[8:11], v[164:167], v[216:219], v[8:11]
	v_mfma_f32_16x16x32_bf16 v[52:55], v[168:171], v[184:187], v[52:55]
	v_mfma_f32_16x16x32_bf16 v[48:51], v[176:179], v[184:187], v[48:51]
	v_mfma_f32_16x16x32_bf16 v[36:39], v[168:171], v[192:195], v[36:39]
	v_mfma_f32_16x16x32_bf16 v[32:35], v[176:179], v[192:195], v[32:35]
	v_mfma_f32_16x16x32_bf16 v[20:23], v[168:171], v[200:203], v[20:23]
	v_mfma_f32_16x16x32_bf16 v[16:19], v[176:179], v[200:203], v[16:19]
	v_mfma_f32_16x16x32_bf16 v[4:7], v[168:171], v[208:211], v[4:7]
	v_mfma_f32_16x16x32_bf16 v[0:3], v[176:179], v[208:211], v[0:3]
	v_mfma_f32_16x16x32_bf16 v[52:55], v[172:175], v[188:191], v[52:55]
	v_mfma_f32_16x16x32_bf16 v[48:51], v[180:183], v[188:191], v[48:51]
	v_mfma_f32_16x16x32_bf16 v[36:39], v[172:175], v[196:199], v[36:39]
	v_mfma_f32_16x16x32_bf16 v[32:35], v[180:183], v[196:199], v[32:35]
	v_mfma_f32_16x16x32_bf16 v[20:23], v[172:175], v[204:207], v[20:23]
	v_mfma_f32_16x16x32_bf16 v[16:19], v[180:183], v[204:207], v[16:19]
	v_mfma_f32_16x16x32_bf16 v[4:7], v[172:175], v[216:219], v[4:7]
	v_mfma_f32_16x16x32_bf16 v[0:3], v[180:183], v[216:219], v[0:3]
	s_setprio 0
	s_barrier
	s_add_i32 s45, 0, 0x18000
	s_add_i32 s52, 0, 0x1c000
	v_add_u32_e32 v164, s45, v143
	v_add_u32_e32 v180, s52, v143
	ds_read_b128 v[152:155], v164
	ds_read_b128 v[156:159], v164 offset:1024
	ds_read_b128 v[160:163], v164 offset:2048
	ds_read_b128 v[164:167], v164 offset:3072
	ds_read_b128 v[168:171], v180
	ds_read_b128 v[172:175], v180 offset:1024
	ds_read_b128 v[176:179], v180 offset:2048
	ds_read_b128 v[180:183], v180 offset:3072
	s_add_u32 s50, s50, 0x100000
	s_addc_u32 s51, s51, 0
	s_mov_b32 m0, s9
	v_lshl_add_u64 v[226:227], s[50:51], 0, v[128:129]
	ds_read_b128 v[184:187], v151 offset:32768
	ds_read_b128 v[188:191], v151 offset:33792
	ds_read_b128 v[192:195], v151 offset:34816
	ds_read_b128 v[196:199], v151 offset:35840
	ds_read_b128 v[200:203], v151 offset:36864
	ds_read_b128 v[204:207], v151 offset:37888
	ds_read_b128 v[208:211], v151 offset:38912
	ds_read_b128 v[216:219], v151 offset:39936
	global_load_lds_dwordx4 v[226:227], off
	v_lshl_add_u64 v[226:227], s[50:51], 0, v[132:133]
	s_mov_b32 m0, s10
	s_nop 0
	global_load_lds_dwordx4 v[226:227], off
	s_waitcnt vmcnt(8)
	s_waitcnt lgkmcnt(0)
	s_barrier
	s_setprio 1
	s_waitcnt lgkmcnt(0)
	v_mfma_f32_16x16x32_bf16 v[124:127], v[152:155], v[184:187], v[124:127]
	v_mfma_f32_16x16x32_bf16 v[120:123], v[160:163], v[184:187], v[120:123]
	v_mfma_f32_16x16x32_bf16 v[108:111], v[152:155], v[192:195], v[108:111]
	v_mfma_f32_16x16x32_bf16 v[104:107], v[160:163], v[192:195], v[104:107]
	v_mfma_f32_16x16x32_bf16 v[92:95], v[152:155], v[200:203], v[92:95]
	v_mfma_f32_16x16x32_bf16 v[88:91], v[160:163], v[200:203], v[88:91]
	v_mfma_f32_16x16x32_bf16 v[76:79], v[152:155], v[208:211], v[76:79]
	v_mfma_f32_16x16x32_bf16 v[72:75], v[160:163], v[208:211], v[72:75]
	v_mfma_f32_16x16x32_bf16 v[124:127], v[156:159], v[188:191], v[124:127]
	v_mfma_f32_16x16x32_bf16 v[120:123], v[164:167], v[188:191], v[120:123]
	v_mfma_f32_16x16x32_bf16 v[108:111], v[156:159], v[196:199], v[108:111]
	v_mfma_f32_16x16x32_bf16 v[104:107], v[164:167], v[196:199], v[104:107]
	v_mfma_f32_16x16x32_bf16 v[92:95], v[156:159], v[204:207], v[92:95]
	v_mfma_f32_16x16x32_bf16 v[88:91], v[164:167], v[204:207], v[88:91]
	v_mfma_f32_16x16x32_bf16 v[76:79], v[156:159], v[216:219], v[76:79]
	v_mfma_f32_16x16x32_bf16 v[72:75], v[164:167], v[216:219], v[72:75]
	v_mfma_f32_16x16x32_bf16 v[116:119], v[168:171], v[184:187], v[116:119]
	v_mfma_f32_16x16x32_bf16 v[112:115], v[176:179], v[184:187], v[112:115]
	v_mfma_f32_16x16x32_bf16 v[100:103], v[168:171], v[192:195], v[100:103]
	v_mfma_f32_16x16x32_bf16 v[96:99], v[176:179], v[192:195], v[96:99]
	v_mfma_f32_16x16x32_bf16 v[84:87], v[168:171], v[200:203], v[84:87]
	v_mfma_f32_16x16x32_bf16 v[80:83], v[176:179], v[200:203], v[80:83]
	v_mfma_f32_16x16x32_bf16 v[68:71], v[168:171], v[208:211], v[68:71]
	v_mfma_f32_16x16x32_bf16 v[64:67], v[176:179], v[208:211], v[64:67]
	v_mfma_f32_16x16x32_bf16 v[116:119], v[172:175], v[188:191], v[116:119]
	v_mfma_f32_16x16x32_bf16 v[112:115], v[180:183], v[188:191], v[112:115]
	v_mfma_f32_16x16x32_bf16 v[100:103], v[172:175], v[196:199], v[100:103]
	v_mfma_f32_16x16x32_bf16 v[96:99], v[180:183], v[196:199], v[96:99]
	v_mfma_f32_16x16x32_bf16 v[84:87], v[172:175], v[204:207], v[84:87]
	v_mfma_f32_16x16x32_bf16 v[80:83], v[180:183], v[204:207], v[80:83]
	v_mfma_f32_16x16x32_bf16 v[68:71], v[172:175], v[216:219], v[68:71]
	v_mfma_f32_16x16x32_bf16 v[64:67], v[180:183], v[216:219], v[64:67]
	s_setprio 0
	s_barrier
; #define STAGE(bufoff, gbase) STAGE_(bufoff, gbase, voffA)
; #define STAGEB(bufoff, gbase) STAGE_(bufoff, gbase, voffB)
; #define LDA(dst, b, h) do { _Pragma("unroll") for (int m = 0; m < 4; ++m) _Pragma("unroll") for (int k = 0; k < 2; ++k) dst[m][k] = *LDSP(const bf16x8, lds + SA(b, h) + aoff + m * 2048 + k * 1024); } while (0)
; #define LDB(dst, b, h) do { _Pragma("unroll") for (int n = 0; n < 2; ++n) _Pragma("unroll") for (int k = 0; k < 2; ++k) dst[n][k] = *LDSP(const bf16x8, lds + SB(b, h) + boff + n * 2048 + k * 1024); } while (0)
; #define MMA(ai, bj, AT, BT) do { __builtin_amdgcn_s_setprio(1); \
;     _Pragma("unroll") for (int m = 0; m < 4; ++m) _Pragma("unroll") for (int n = 0; n < 2; ++n) _Pragma("unroll") for (int k = 0; k < 2; ++k) \
;       acc[ai][bj][m][n] = __builtin_amdgcn_mfma_f32_16x16x32_bf16(BT[n][k], AT[m][k], acc[ai][bj][m][n], 0, 0, 0); \
;     __builtin_amdgcn_s_setprio(0); } while (0)
; #define WAIT_V(n) asm volatile("s_waitcnt vmcnt(" #n ")" ::: "memory")
; #define WAIT_L(n) asm volatile("s_waitcnt lgkmcnt(" #n ")" ::: "memory")
; template <bool SP2, bool ALIGN_EPI, bool DUAL, class Epi> DI void gemm_phase2(const bf16_t* A, const bf16_t* Bt, const bf16_t* A2, const bf16_t* Bt2, int M, int N, int K, const Epi& E, lds_t* lds) {
;     ...
;     for (int t = 0; t < nt; t += 2) {
;       const bool last = (t == nt - 2);
;       const char* a1 = cA + (size_t)(t + 1) * kstep;
;       const char* a2 = last ? nA : cA + (size_t)(t + 2) * kstep; const char* b2 = last ? nB : cB + (size_t)(t + 2) * kstep;
;       const char* a3 = a2 + kstep; const char* b3 = b2 + kstep;
;       if constexpr (SP2) {
;         LDB(B0, 0, 0); LDB(B1, 0, 1); SCHED; LDA(At, 0, 0); STAGE(SA(1, 1), a1 + hstep);
;         WAIT_V(8); WAIT_L(0); BAR; MMA(0, 0, At, B0); MMA(0, 1, At, B1); BAR; SCHED;
;         LDA(At, 0, 1); STAGEB(SB(0, 0), b2); STAGEB(SB(0, 1), b2 + bstep); STAGE(SA(0, 0), a2);
;         WAIT_V(8); WAIT_L(0); BAR; MMA(1, 0, At, B0); MMA(1, 1, At, B1); BAR; SCHED;
;         LDB(B0, 1, 0); LDB(B1, 1, 1); SCHED; LDA(At, 1, 0); STAGE(SA(0, 1), a2 + hstep);
;         WAIT_V(8); WAIT_L(0); BAR; MMA(0, 0, At, B0); MMA(0, 1, At, B1); BAR; SCHED;
;         LDA(At, 1, 1); STAGEB(SB(1, 0), b3); STAGEB(SB(1, 1), b3 + bstep); STAGE(SA(1, 0), a3);
;         WAIT_V(8); WAIT_L(0); BAR; MMA(1, 0, At, B0); MMA(1, 1, At, B1); BAR; SCHED;
	s_add_i32 s45, s45, s2
	v_lshl_add_u64 v[140:141], v[140:141], 0, s[22:23]
	s_mov_b32 m0, s45
	ds_read_b128 v[184:187], v151 offset:49152
	ds_read_b128 v[188:191], v151 offset:50176
	ds_read_b128 v[192:195], v151 offset:51200
	ds_read_b128 v[196:199], v151 offset:52224
	ds_read_b128 v[200:203], v151 offset:53248
	ds_read_b128 v[204:207], v151 offset:54272
	ds_read_b128 v[208:211], v151 offset:55296
	ds_read_b128 v[216:219], v151 offset:56320
	global_load_lds_dwordx4 v[140:141], off
	s_add_i32 m0, s45, 0x2000
	s_add_u32 s48, s48, 0x40080
	v_lshl_add_u64 v[140:141], v[220:221], 0, s[22:23]
	s_addc_u32 s49, s49, 0
	s_add_i32 s45, s52, s2
	global_load_lds_dwordx4 v[140:141], off
	v_lshl_add_u64 v[140:141], s[48:49], 0, v[130:131]
	s_mov_b32 m0, s45
	s_nop 0
	global_load_lds_dwordx4 v[140:141], off
	v_lshl_add_u64 v[140:141], s[48:49], 0, v[134:135]
	s_add_i32 m0, s45, 0x2000
	s_nop 0
	global_load_lds_dwordx4 v[140:141], off
	v_lshl_add_u64 v[140:141], v[222:223], 0, s[22:23]
	s_mov_b32 m0, s14
	s_nop 0
	global_load_lds_dwordx4 v[140:141], off
	v_lshl_add_u64 v[140:141], v[224:225], 0, s[22:23]
	s_mov_b32 m0, s15
	s_nop 0
	global_load_lds_dwordx4 v[140:141], off
	s_waitcnt vmcnt(8)
	s_waitcnt lgkmcnt(0)
	s_barrier
	s_setprio 1
	s_waitcnt lgkmcnt(0)
	v_mfma_f32_16x16x32_bf16 v[60:63], v[152:155], v[184:187], v[60:63]
	v_mfma_f32_16x16x32_bf16 v[56:59], v[160:163], v[184:187], v[56:59]
	v_mfma_f32_16x16x32_bf16 v[44:47], v[152:155], v[192:195], v[44:47]
	v_mfma_f32_16x16x32_bf16 v[40:43], v[160:163], v[192:195], v[40:43]
	v_mfma_f32_16x16x32_bf16 v[28:31], v[152:155], v[200:203], v[28:31]
	v_mfma_f32_16x16x32_bf16 v[24:27], v[160:163], v[200:203], v[24:27]
	v_mfma_f32_16x16x32_bf16 v[12:15], v[152:155], v[208:211], v[12:15]
	v_mfma_f32_16x16x32_bf16 v[8:11], v[160:163], v[208:211], v[8:11]
	v_mfma_f32_16x16x32_bf16 v[60:63], v[156:159], v[188:191], v[60:63]
	v_mfma_f32_16x16x32_bf16 v[56:59], v[164:167], v[188:191], v[56:59]
	v_mfma_f32_16x16x32_bf16 v[44:47], v[156:159], v[196:199], v[44:47]
	v_mfma_f32_16x16x32_bf16 v[40:43], v[164:167], v[196:199], v[40:43]
	v_mfma_f32_16x16x32_bf16 v[28:31], v[156:159], v[204:207], v[28:31]
	v_mfma_f32_16x16x32_bf16 v[24:27], v[164:167], v[204:207], v[24:27]
	v_mfma_f32_16x16x32_bf16 v[12:15], v[156:159], v[216:219], v[12:15]
	v_mfma_f32_16x16x32_bf16 v[8:11], v[164:167], v[216:219], v[8:11]
	v_mfma_f32_16x16x32_bf16 v[52:55], v[168:171], v[184:187], v[52:55]
	v_mfma_f32_16x16x32_bf16 v[48:51], v[176:179], v[184:187], v[48:51]
	v_mfma_f32_16x16x32_bf16 v[36:39], v[168:171], v[192:195], v[36:39]
	v_mfma_f32_16x16x32_bf16 v[32:35], v[176:179], v[192:195], v[32:35]
	v_mfma_f32_16x16x32_bf16 v[20:23], v[168:171], v[200:203], v[20:23]
	v_mfma_f32_16x16x32_bf16 v[16:19], v[176:179], v[200:203], v[16:19]
	v_mfma_f32_16x16x32_bf16 v[4:7], v[168:171], v[208:211], v[4:7]
	v_mfma_f32_16x16x32_bf16 v[0:3], v[176:179], v[208:211], v[0:3]
	v_mfma_f32_16x16x32_bf16 v[52:55], v[172:175], v[188:191], v[52:55]
	v_mfma_f32_16x16x32_bf16 v[48:51], v[180:183], v[188:191], v[48:51]
	v_mfma_f32_16x16x32_bf16 v[36:39], v[172:175], v[196:199], v[36:39]
	v_mfma_f32_16x16x32_bf16 v[32:35], v[180:183], v[196:199], v[32:35]
	v_mfma_f32_16x16x32_bf16 v[20:23], v[172:175], v[204:207], v[20:23]
	v_mfma_f32_16x16x32_bf16 v[16:19], v[180:183], v[204:207], v[16:19]
	v_mfma_f32_16x16x32_bf16 v[4:7], v[172:175], v[216:219], v[4:7]
	v_mfma_f32_16x16x32_bf16 v[0:3], v[180:183], v[216:219], v[0:3]
	s_setprio 0
	s_barrier
	s_add_i32 s39, s39, 2
	s_add_u32 s46, s46, 0x100
	s_addc_u32 s47, s47, 0
	s_add_u32 s34, s34, 0x100
	s_addc_u32 s35, s35, 0
	s_cmp_gt_u32 s39, 61
	s_cbranch_scc0 .LBB0_824
	s_and_b64 vcc, exec, s[28:29]
	s_cbranch_vccz .LBB0_827
	s_barrier

; #define STAGE(bufoff, gbase) STAGE_(bufoff, gbase, voffA)
; #define STAGEB(bufoff, gbase) STAGE_(bufoff, gbase, voffB)
; #define LDA(dst, b, h) do { _Pragma("unroll") for (int m = 0; m < 4; ++m) _Pragma("unroll") for (int k = 0; k < 2; ++k) dst[m][k] = *LDSP(const bf16x8, lds + SA(b, h) + aoff + m * 2048 + k * 1024); } while (0)
; #define LDB(dst, b, h) do { _Pragma("unroll") for (int n = 0; n < 2; ++n) _Pragma("unroll") for (int k = 0; k < 2; ++k) dst[n][k] = *LDSP(const bf16x8, lds + SB(b, h) + boff + n * 2048 + k * 1024); } while (0)
; #define MMA(ai, bj, AT, BT) do { __builtin_amdgcn_s_setprio(1); \
;     _Pragma("unroll") for (int m = 0; m < 4; ++m) _Pragma("unroll") for (int n = 0; n < 2; ++n) _Pragma("unroll") for (int k = 0; k < 2; ++k) \
;       acc[ai][bj][m][n] = __builtin_amdgcn_mfma_f32_16x16x32_bf16(BT[n][k], AT[m][k], acc[ai][bj][m][n], 0, 0, 0); \
;     __builtin_amdgcn_s_setprio(0); } while (0)
; #define WAIT_V(n) asm volatile("s_waitcnt vmcnt(" #n ")" ::: "memory")
; #define WAIT_L(n) asm volatile("s_waitcnt lgkmcnt(" #n ")" ::: "memory")
; #define BAR __builtin_amdgcn_s_barrier()
; #define SCHED __builtin_amdgcn_sched_barrier(0)
; #define WAIT_V(n) asm volatile("s_waitcnt vmcnt(" #n ")" ::: "memory")
; #define BAR do { __builtin_amdgcn_sched_barrier(0); __builtin_amdgcn_s_barrier(); asm volatile("" ::: "memory"); __builtin_amdgcn_sched_barrier(0); } while (0)
; template <bool SP2, bool ALIGN_EPI, bool DUAL, class Epi> DI void gemm_phase2(const bf16_t* A, const bf16_t* Bt, const bf16_t* A2, const bf16_t* Bt2, int M, int N, int K, const Epi& E, lds_t* lds) {
;     ...
;       const bool last = (t == nt - 2);
;       const char* a1 = cA + (size_t)(t + 1) * kstep;
;       const char* a2 = last ? nA : cA + (size_t)(t + 2) * kstep; const char* b2 = last ? nB : cB + (size_t)(t + 2) * kstep;
;       const char* a3 = a2 + kstep; const char* b3 = b2 + kstep;
;       if constexpr (SP2) {
;         LDB(B0, 0, 0); LDB(B1, 0, 1); SCHED; LDA(At, 0, 0); STAGE(SA(1, 1), a1 + hstep);
;         WAIT_V(8); WAIT_L(0); BAR; MMA(0, 0, At, B0); MMA(0, 1, At, B1); BAR; SCHED;
;         LDA(At, 0, 1); STAGEB(SB(0, 0), b2); STAGEB(SB(0, 1), b2 + bstep); STAGE(SA(0, 0), a2);
;         WAIT_V(8); WAIT_L(0); BAR; MMA(1, 0, At, B0); MMA(1, 1, At, B1); BAR; SCHED;
.LBB0_900:
	ds_read_b128 v[140:143], v160
	ds_read_b128 v[144:147], v160 offset:1024
	ds_read_b128 v[148:151], v160 offset:2048
	ds_read_b128 v[152:155], v160 offset:3072
	ds_read_b128 v[164:167], v161
	ds_read_b128 v[168:171], v161 offset:1024
	ds_read_b128 v[172:175], v161 offset:2048
	ds_read_b128 v[176:179], v161 offset:3072
	s_add_u32 s27, s42, 0xfff00080
	s_addc_u32 s41, s43, -1
	s_cmp_eq_u32 s21, 60
	s_cselect_b32 s47, s0, s41
	s_cselect_b32 s46, s1, s27
	s_cselect_b32 s45, s2, s15
	s_cselect_b32 s44, s3, s14
	v_lshl_add_u64 v[216:217], s[42:43], 0, v[136:137]
	s_add_i32 m0, s11, 0xc000
	ds_read_b128 v[180:183], v162
	ds_read_b128 v[184:187], v162 offset:1024
	ds_read_b128 v[188:191], v162 offset:2048
	ds_read_b128 v[192:195], v162 offset:3072
	ds_read_b128 v[196:199], v162 offset:4096
	ds_read_b128 v[200:203], v162 offset:5120
	ds_read_b128 v[204:207], v162 offset:6144
	ds_read_b128 v[208:211], v162 offset:7168
	global_load_lds_dwordx4 v[216:217], off
	v_lshl_add_u64 v[216:217], s[42:43], 0, v[138:139]
	s_add_i32 m0, s11, 0xe000
	s_nop 0
	global_load_lds_dwordx4 v[216:217], off
	s_waitcnt vmcnt(8)
	s_waitcnt lgkmcnt(0)
	s_barrier
	s_setprio 1
	s_waitcnt lgkmcnt(0)
	v_mfma_f32_16x16x32_bf16 v[124:127], v[140:143], v[180:183], v[124:127]
	v_mfma_f32_16x16x32_bf16 v[120:123], v[148:151], v[180:183], v[120:123]
	v_mfma_f32_16x16x32_bf16 v[108:111], v[140:143], v[188:191], v[108:111]
	v_mfma_f32_16x16x32_bf16 v[104:107], v[148:151], v[188:191], v[104:107]
	v_mfma_f32_16x16x32_bf16 v[92:95], v[140:143], v[196:199], v[92:95]
	v_mfma_f32_16x16x32_bf16 v[88:91], v[148:151], v[196:199], v[88:91]
	v_mfma_f32_16x16x32_bf16 v[76:79], v[140:143], v[204:207], v[76:79]
	v_mfma_f32_16x16x32_bf16 v[72:75], v[148:151], v[204:207], v[72:75]
	v_mfma_f32_16x16x32_bf16 v[124:127], v[144:147], v[184:187], v[124:127]
	v_mfma_f32_16x16x32_bf16 v[120:123], v[152:155], v[184:187], v[120:123]
	v_mfma_f32_16x16x32_bf16 v[108:111], v[144:147], v[192:195], v[108:111]
	v_mfma_f32_16x16x32_bf16 v[104:107], v[152:155], v[192:195], v[104:107]
	v_mfma_f32_16x16x32_bf16 v[92:95], v[144:147], v[200:203], v[92:95]
	v_mfma_f32_16x16x32_bf16 v[88:91], v[152:155], v[200:203], v[88:91]
	v_mfma_f32_16x16x32_bf16 v[76:79], v[144:147], v[208:211], v[76:79]
	v_mfma_f32_16x16x32_bf16 v[72:75], v[152:155], v[208:211], v[72:75]
	v_mfma_f32_16x16x32_bf16 v[116:119], v[164:167], v[180:183], v[116:119]
	v_mfma_f32_16x16x32_bf16 v[112:115], v[172:175], v[180:183], v[112:115]
	v_mfma_f32_16x16x32_bf16 v[100:103], v[164:167], v[188:191], v[100:103]
	v_mfma_f32_16x16x32_bf16 v[96:99], v[172:175], v[188:191], v[96:99]
	v_mfma_f32_16x16x32_bf16 v[84:87], v[164:167], v[196:199], v[84:87]
	v_mfma_f32_16x16x32_bf16 v[80:83], v[172:175], v[196:199], v[80:83]
	v_mfma_f32_16x16x32_bf16 v[68:71], v[164:167], v[204:207], v[68:71]
	v_mfma_f32_16x16x32_bf16 v[64:67], v[172:175], v[204:207], v[64:67]
	v_mfma_f32_16x16x32_bf16 v[116:119], v[168:171], v[184:187], v[116:119]
	v_mfma_f32_16x16x32_bf16 v[112:115], v[176:179], v[184:187], v[112:115]
	v_mfma_f32_16x16x32_bf16 v[100:103], v[168:171], v[192:195], v[100:103]
	v_mfma_f32_16x16x32_bf16 v[96:99], v[176:179], v[192:195], v[96:99]
	v_mfma_f32_16x16x32_bf16 v[84:87], v[168:171], v[200:203], v[84:87]
	v_mfma_f32_16x16x32_bf16 v[80:83], v[176:179], v[200:203], v[80:83]
	v_mfma_f32_16x16x32_bf16 v[68:71], v[168:171], v[208:211], v[68:71]
	v_mfma_f32_16x16x32_bf16 v[64:67], v[176:179], v[208:211], v[64:67]
	s_setprio 0
	s_barrier
	s_add_i32 s27, s49, s10
	v_lshl_add_u64 v[216:217], s[44:45], 0, v[130:131]
	s_mov_b32 m0, s27
	ds_read_b128 v[180:183], v162 offset:16384
	ds_read_b128 v[184:187], v162 offset:17408
	ds_read_b128 v[188:191], v162 offset:18432
	ds_read_b128 v[192:195], v162 offset:19456
	ds_read_b128 v[196:199], v162 offset:20480
	ds_read_b128 v[200:203], v162 offset:21504
	ds_read_b128 v[204:207], v162 offset:22528
	ds_read_b128 v[208:211], v162 offset:23552
	global_load_lds_dwordx4 v[216:217], off
	s_add_i32 m0, s27, 0x2000
	s_add_u32 s54, s44, 0x40000
	v_lshl_add_u64 v[218:219], s[44:45], 0, v[134:135]
	s_addc_u32 s55, s45, 0
	s_add_i32 s27, s50, s10
	global_load_lds_dwordx4 v[218:219], off
	v_lshl_add_u64 v[220:221], s[54:55], 0, v[130:131]
	s_mov_b32 m0, s27
	v_lshl_add_u64 v[222:223], s[46:47], 0, v[132:133]
	global_load_lds_dwordx4 v[220:221], off
	v_lshl_add_u64 v[220:221], s[54:55], 0, v[134:135]
	s_add_i32 m0, s27, 0x2000
	s_nop 0
	global_load_lds_dwordx4 v[220:221], off
	v_lshl_add_u64 v[220:221], s[46:47], 0, v[128:129]
	s_mov_b32 m0, s11
	s_nop 0
	global_load_lds_dwordx4 v[220:221], off
	s_mov_b32 m0, s18
	s_nop 0
	global_load_lds_dwordx4 v[222:223], off
	s_waitcnt vmcnt(8)
	s_waitcnt lgkmcnt(0)
	s_barrier
; #define STAGE(bufoff, gbase) STAGE_(bufoff, gbase, voffA)
; #define LDA(dst, b, h) do { _Pragma("unroll") for (int m = 0; m < 4; ++m) _Pragma("unroll") for (int k = 0; k < 2; ++k) dst[m][k] = *LDSP(const bf16x8, lds + SA(b, h) + aoff + m * 2048 + k * 1024); } while (0)
; #define LDB(dst, b, h) do { _Pragma("unroll") for (int n = 0; n < 2; ++n) _Pragma("unroll") for (int k = 0; k < 2; ++k) dst[n][k] = *LDSP(const bf16x8, lds + SB(b, h) + boff + n * 2048 + k * 1024); } while (0)
; #define MMA(ai, bj, AT, BT) do { __builtin_amdgcn_s_setprio(1); \
;     _Pragma("unroll") for (int m = 0; m < 4; ++m) _Pragma("unroll") for (int n = 0; n < 2; ++n) _Pragma("unroll") for (int k = 0; k < 2; ++k) \
;       acc[ai][bj][m][n] = __builtin_amdgcn_mfma_f32_16x16x32_bf16(BT[n][k], AT[m][k], acc[ai][bj][m][n], 0, 0, 0); \
;     __builtin_amdgcn_s_setprio(0); } while (0)
; #define WAIT_V(n) asm volatile("s_waitcnt vmcnt(" #n ")" ::: "memory")
; #define WAIT_L(n) asm volatile("s_waitcnt lgkmcnt(" #n ")" ::: "memory")
; #define BAR __builtin_amdgcn_s_barrier()
; #define SCHED __builtin_amdgcn_sched_barrier(0)
; #define WAIT_V(n) asm volatile("s_waitcnt vmcnt(" #n ")" ::: "memory")
; #define BAR do { __builtin_amdgcn_sched_barrier(0); __builtin_amdgcn_s_barrier(); asm volatile("" ::: "memory"); __builtin_amdgcn_sched_barrier(0); } while (0)
; template <bool SP2, bool ALIGN_EPI, bool DUAL, class Epi> DI void gemm_phase2(const bf16_t* A, const bf16_t* Bt, const bf16_t* A2, const bf16_t* Bt2, int M, int N, int K, const Epi& E, lds_t* lds) {
;     ...
;         WAIT_V(8); WAIT_L(0); BAR; MMA(1, 0, At, B0); MMA(1, 1, At, B1); BAR; SCHED;
;         LDB(B0, 1, 0); LDB(B1, 1, 1); SCHED; LDA(At, 1, 0); STAGE(SA(0, 1), a2 + hstep);
;         WAIT_V(8); WAIT_L(0); BAR; MMA(0, 0, At, B0); MMA(0, 1, At, B1); BAR; SCHED;
	s_setprio 1
	s_waitcnt lgkmcnt(0)
	v_mfma_f32_16x16x32_bf16 v[60:63], v[140:143], v[180:183], v[60:63]
	v_mfma_f32_16x16x32_bf16 v[56:59], v[148:151], v[180:183], v[56:59]
	v_mfma_f32_16x16x32_bf16 v[44:47], v[140:143], v[188:191], v[44:47]
	v_mfma_f32_16x16x32_bf16 v[40:43], v[148:151], v[188:191], v[40:43]
	v_mfma_f32_16x16x32_bf16 v[28:31], v[140:143], v[196:199], v[28:31]
	v_mfma_f32_16x16x32_bf16 v[24:27], v[148:151], v[196:199], v[24:27]
	v_mfma_f32_16x16x32_bf16 v[12:15], v[140:143], v[204:207], v[12:15]
	v_mfma_f32_16x16x32_bf16 v[8:11], v[148:151], v[204:207], v[8:11]
	v_mfma_f32_16x16x32_bf16 v[60:63], v[144:147], v[184:187], v[60:63]
	v_mfma_f32_16x16x32_bf16 v[56:59], v[152:155], v[184:187], v[56:59]
	v_mfma_f32_16x16x32_bf16 v[44:47], v[144:147], v[192:195], v[44:47]
	v_mfma_f32_16x16x32_bf16 v[40:43], v[152:155], v[192:195], v[40:43]
	v_mfma_f32_16x16x32_bf16 v[28:31], v[144:147], v[200:203], v[28:31]
	v_mfma_f32_16x16x32_bf16 v[24:27], v[152:155], v[200:203], v[24:27]
	v_mfma_f32_16x16x32_bf16 v[12:15], v[144:147], v[208:211], v[12:15]
	v_mfma_f32_16x16x32_bf16 v[8:11], v[152:155], v[208:211], v[8:11]
	v_mfma_f32_16x16x32_bf16 v[52:55], v[164:167], v[180:183], v[52:55]
	v_mfma_f32_16x16x32_bf16 v[48:51], v[172:175], v[180:183], v[48:51]
	v_mfma_f32_16x16x32_bf16 v[36:39], v[164:167], v[188:191], v[36:39]
	v_mfma_f32_16x16x32_bf16 v[32:35], v[172:175], v[188:191], v[32:35]
	v_mfma_f32_16x16x32_bf16 v[20:23], v[164:167], v[196:199], v[20:23]
	v_mfma_f32_16x16x32_bf16 v[16:19], v[172:175], v[196:199], v[16:19]
	v_mfma_f32_16x16x32_bf16 v[4:7], v[164:167], v[204:207], v[4:7]
	v_mfma_f32_16x16x32_bf16 v[0:3], v[172:175], v[204:207], v[0:3]
	v_mfma_f32_16x16x32_bf16 v[52:55], v[168:171], v[184:187], v[52:55]
	v_mfma_f32_16x16x32_bf16 v[48:51], v[176:179], v[184:187], v[48:51]
	v_mfma_f32_16x16x32_bf16 v[36:39], v[168:171], v[192:195], v[36:39]
	v_mfma_f32_16x16x32_bf16 v[32:35], v[176:179], v[192:195], v[32:35]
	v_mfma_f32_16x16x32_bf16 v[20:23], v[168:171], v[200:203], v[20:23]
	v_mfma_f32_16x16x32_bf16 v[16:19], v[176:179], v[200:203], v[16:19]
	v_mfma_f32_16x16x32_bf16 v[4:7], v[168:171], v[208:211], v[4:7]
	v_mfma_f32_16x16x32_bf16 v[0:3], v[176:179], v[208:211], v[0:3]
	s_setprio 0
	s_barrier
	s_add_i32 s27, 0, 0x18000
	s_add_i32 s41, 0, 0x1c000
	v_add_u32_e32 v152, s27, v157
	v_add_u32_e32 v176, s41, v157
	ds_read_b128 v[140:143], v152
	ds_read_b128 v[144:147], v152 offset:1024
	ds_read_b128 v[148:151], v152 offset:2048
	ds_read_b128 v[152:155], v152 offset:3072
	ds_read_b128 v[164:167], v176
	ds_read_b128 v[168:171], v176 offset:1024
	ds_read_b128 v[172:175], v176 offset:2048
	ds_read_b128 v[176:179], v176 offset:3072
	s_add_u32 s46, s46, 0x100000
	s_addc_u32 s47, s47, 0
	s_mov_b32 m0, s19
	v_lshl_add_u64 v[224:225], s[46:47], 0, v[128:129]
	ds_read_b128 v[180:183], v162 offset:32768
	ds_read_b128 v[184:187], v162 offset:33792
	ds_read_b128 v[188:191], v162 offset:34816
	ds_read_b128 v[192:195], v162 offset:35840
	ds_read_b128 v[196:199], v162 offset:36864
	ds_read_b128 v[200:203], v162 offset:37888
	ds_read_b128 v[204:207], v162 offset:38912
	ds_read_b128 v[208:211], v162 offset:39936
	global_load_lds_dwordx4 v[224:225], off
	v_lshl_add_u64 v[224:225], s[46:47], 0, v[132:133]
	s_mov_b32 m0, s33
	s_nop 0
	global_load_lds_dwordx4 v[224:225], off
	s_waitcnt vmcnt(8)
	s_waitcnt lgkmcnt(0)
	s_barrier
	s_setprio 1
	s_waitcnt lgkmcnt(0)
	v_mfma_f32_16x16x32_bf16 v[124:127], v[140:143], v[180:183], v[124:127]
	v_mfma_f32_16x16x32_bf16 v[120:123], v[148:151], v[180:183], v[120:123]
	v_mfma_f32_16x16x32_bf16 v[108:111], v[140:143], v[188:191], v[108:111]
	v_mfma_f32_16x16x32_bf16 v[104:107], v[148:151], v[188:191], v[104:107]
	v_mfma_f32_16x16x32_bf16 v[92:95], v[140:143], v[196:199], v[92:95]
	v_mfma_f32_16x16x32_bf16 v[88:91], v[148:151], v[196:199], v[88:91]
	v_mfma_f32_16x16x32_bf16 v[76:79], v[140:143], v[204:207], v[76:79]
	v_mfma_f32_16x16x32_bf16 v[72:75], v[148:151], v[204:207], v[72:75]
	v_mfma_f32_16x16x32_bf16 v[124:127], v[144:147], v[184:187], v[124:127]
	v_mfma_f32_16x16x32_bf16 v[120:123], v[152:155], v[184:187], v[120:123]
	v_mfma_f32_16x16x32_bf16 v[108:111], v[144:147], v[192:195], v[108:111]
	v_mfma_f32_16x16x32_bf16 v[104:107], v[152:155], v[192:195], v[104:107]
	v_mfma_f32_16x16x32_bf16 v[92:95], v[144:147], v[200:203], v[92:95]
	v_mfma_f32_16x16x32_bf16 v[88:91], v[152:155], v[200:203], v[88:91]
	v_mfma_f32_16x16x32_bf16 v[76:79], v[144:147], v[208:211], v[76:79]
	v_mfma_f32_16x16x32_bf16 v[72:75], v[152:155], v[208:211], v[72:75]
	v_mfma_f32_16x16x32_bf16 v[116:119], v[164:167], v[180:183], v[116:119]
	v_mfma_f32_16x16x32_bf16 v[112:115], v[172:175], v[180:183], v[112:115]
	v_mfma_f32_16x16x32_bf16 v[100:103], v[164:167], v[188:191], v[100:103]
	v_mfma_f32_16x16x32_bf16 v[96:99], v[172:175], v[188:191], v[96:99]
	v_mfma_f32_16x16x32_bf16 v[84:87], v[164:167], v[196:199], v[84:87]
	v_mfma_f32_16x16x32_bf16 v[80:83], v[172:175], v[196:199], v[80:83]
	v_mfma_f32_16x16x32_bf16 v[68:71], v[164:167], v[204:207], v[68:71]
	v_mfma_f32_16x16x32_bf16 v[64:67], v[172:175], v[204:207], v[64:67]
	v_mfma_f32_16x16x32_bf16 v[116:119], v[168:171], v[184:187], v[116:119]
	v_mfma_f32_16x16x32_bf16 v[112:115], v[176:179], v[184:187], v[112:115]
	v_mfma_f32_16x16x32_bf16 v[100:103], v[168:171], v[192:195], v[100:103]
	v_mfma_f32_16x16x32_bf16 v[96:99], v[176:179], v[192:195], v[96:99]
	v_mfma_f32_16x16x32_bf16 v[84:87], v[168:171], v[200:203], v[84:87]
	v_mfma_f32_16x16x32_bf16 v[80:83], v[176:179], v[200:203], v[80:83]
	v_mfma_f32_16x16x32_bf16 v[68:71], v[168:171], v[208:211], v[68:71]
	v_mfma_f32_16x16x32_bf16 v[64:67], v[176:179], v[208:211], v[64:67]
	s_setprio 0
	s_barrier
; #define STAGE(bufoff, gbase) STAGE_(bufoff, gbase, voffA)
; #define STAGEB(bufoff, gbase) STAGE_(bufoff, gbase, voffB)
; #define LDA(dst, b, h) do { _Pragma("unroll") for (int m = 0; m < 4; ++m) _Pragma("unroll") for (int k = 0; k < 2; ++k) dst[m][k] = *LDSP(const bf16x8, lds + SA(b, h) + aoff + m * 2048 + k * 1024); } while (0)
; #define MMA(ai, bj, AT, BT) do { __builtin_amdgcn_s_setprio(1); \
;     _Pragma("unroll") for (int m = 0; m < 4; ++m) _Pragma("unroll") for (int n = 0; n < 2; ++n) _Pragma("unroll") for (int k = 0; k < 2; ++k) \
;       acc[ai][bj][m][n] = __builtin_amdgcn_mfma_f32_16x16x32_bf16(BT[n][k], AT[m][k], acc[ai][bj][m][n], 0, 0, 0); \
;     __builtin_amdgcn_s_setprio(0); } while (0)
; #define WAIT_V(n) asm volatile("s_waitcnt vmcnt(" #n ")" ::: "memory")
; #define WAIT_L(n) asm volatile("s_waitcnt lgkmcnt(" #n ")" ::: "memory")
; #define BAR __builtin_amdgcn_s_barrier()
; #define SCHED __builtin_amdgcn_sched_barrier(0)
; #define WAIT_V(n) asm volatile("s_waitcnt vmcnt(" #n ")" ::: "memory")
; #define BAR do { __builtin_amdgcn_sched_barrier(0); __builtin_amdgcn_s_barrier(); asm volatile("" ::: "memory"); __builtin_amdgcn_sched_barrier(0); } while (0)
; template <bool SP2, bool ALIGN_EPI, bool DUAL, class Epi> DI void gemm_phase2(const bf16_t* A, const bf16_t* Bt, const bf16_t* A2, const bf16_t* Bt2, int M, int N, int K, const Epi& E, lds_t* lds) {
;     ...
;         LDA(At, 1, 1); STAGEB(SB(1, 0), b3); STAGEB(SB(1, 1), b3 + bstep); STAGE(SA(1, 0), a3);
;         WAIT_V(8); WAIT_L(0); BAR; MMA(1, 0, At, B0); MMA(1, 1, At, B1); BAR; SCHED;
	s_add_i32 s27, s27, s10
	v_lshl_add_u64 v[216:217], v[216:217], 0, s[8:9]
	s_mov_b32 m0, s27
	ds_read_b128 v[180:183], v162 offset:49152
	ds_read_b128 v[184:187], v162 offset:50176
	ds_read_b128 v[188:191], v162 offset:51200
	ds_read_b128 v[192:195], v162 offset:52224
	ds_read_b128 v[196:199], v162 offset:53248
	ds_read_b128 v[200:203], v162 offset:54272
	ds_read_b128 v[204:207], v162 offset:55296
	ds_read_b128 v[208:211], v162 offset:56320
	global_load_lds_dwordx4 v[216:217], off
	s_add_i32 m0, s27, 0x2000
	s_add_u32 s44, s44, 0x40080
	v_lshl_add_u64 v[216:217], v[218:219], 0, s[8:9]
	s_addc_u32 s45, s45, 0
	s_add_i32 s27, s41, s10
	global_load_lds_dwordx4 v[216:217], off
	v_lshl_add_u64 v[216:217], s[44:45], 0, v[130:131]
	s_mov_b32 m0, s27
	s_nop 0
	global_load_lds_dwordx4 v[216:217], off
	v_lshl_add_u64 v[216:217], s[44:45], 0, v[134:135]
	s_add_i32 m0, s27, 0x2000
	s_nop 0
	global_load_lds_dwordx4 v[216:217], off
	v_lshl_add_u64 v[216:217], v[220:221], 0, s[8:9]
	s_mov_b32 m0, s39
	s_nop 0
	global_load_lds_dwordx4 v[216:217], off
	v_lshl_add_u64 v[216:217], v[222:223], 0, s[8:9]
	s_mov_b32 m0, s48
	s_nop 0
	global_load_lds_dwordx4 v[216:217], off
	s_waitcnt vmcnt(8)
	s_waitcnt lgkmcnt(0)
	s_barrier
	s_setprio 1
	s_waitcnt lgkmcnt(0)
	v_mfma_f32_16x16x32_bf16 v[60:63], v[140:143], v[180:183], v[60:63]
	v_mfma_f32_16x16x32_bf16 v[56:59], v[148:151], v[180:183], v[56:59]
	v_mfma_f32_16x16x32_bf16 v[44:47], v[140:143], v[188:191], v[44:47]
	v_mfma_f32_16x16x32_bf16 v[40:43], v[148:151], v[188:191], v[40:43]
	v_mfma_f32_16x16x32_bf16 v[28:31], v[140:143], v[196:199], v[28:31]
	v_mfma_f32_16x16x32_bf16 v[24:27], v[148:151], v[196:199], v[24:27]
	v_mfma_f32_16x16x32_bf16 v[12:15], v[140:143], v[204:207], v[12:15]
	v_mfma_f32_16x16x32_bf16 v[8:11], v[148:151], v[204:207], v[8:11]
	v_mfma_f32_16x16x32_bf16 v[60:63], v[144:147], v[184:187], v[60:63]
	v_mfma_f32_16x16x32_bf16 v[56:59], v[152:155], v[184:187], v[56:59]
	v_mfma_f32_16x16x32_bf16 v[44:47], v[144:147], v[192:195], v[44:47]
	v_mfma_f32_16x16x32_bf16 v[40:43], v[152:155], v[192:195], v[40:43]
	v_mfma_f32_16x16x32_bf16 v[28:31], v[144:147], v[200:203], v[28:31]
	v_mfma_f32_16x16x32_bf16 v[24:27], v[152:155], v[200:203], v[24:27]
	v_mfma_f32_16x16x32_bf16 v[12:15], v[144:147], v[208:211], v[12:15]
	v_mfma_f32_16x16x32_bf16 v[8:11], v[152:155], v[208:211], v[8:11]
	v_mfma_f32_16x16x32_bf16 v[52:55], v[164:167], v[180:183], v[52:55]
	v_mfma_f32_16x16x32_bf16 v[48:51], v[172:175], v[180:183], v[48:51]
	v_mfma_f32_16x16x32_bf16 v[36:39], v[164:167], v[188:191], v[36:39]
	v_mfma_f32_16x16x32_bf16 v[32:35], v[172:175], v[188:191], v[32:35]
	v_mfma_f32_16x16x32_bf16 v[20:23], v[164:167], v[196:199], v[20:23]
	v_mfma_f32_16x16x32_bf16 v[16:19], v[172:175], v[196:199], v[16:19]
	v_mfma_f32_16x16x32_bf16 v[4:7], v[164:167], v[204:207], v[4:7]
	v_mfma_f32_16x16x32_bf16 v[0:3], v[172:175], v[204:207], v[0:3]
	v_mfma_f32_16x16x32_bf16 v[52:55], v[168:171], v[184:187], v[52:55]
	v_mfma_f32_16x16x32_bf16 v[48:51], v[176:179], v[184:187], v[48:51]
	v_mfma_f32_16x16x32_bf16 v[36:39], v[168:171], v[192:195], v[36:39]
	v_mfma_f32_16x16x32_bf16 v[32:35], v[176:179], v[192:195], v[32:35]
	v_mfma_f32_16x16x32_bf16 v[20:23], v[168:171], v[200:203], v[20:23]
	v_mfma_f32_16x16x32_bf16 v[16:19], v[176:179], v[200:203], v[16:19]
	v_mfma_f32_16x16x32_bf16 v[4:7], v[168:171], v[208:211], v[4:7]
	v_mfma_f32_16x16x32_bf16 v[0:3], v[176:179], v[208:211], v[0:3]
	s_setprio 0
	s_barrier
	s_add_i32 s21, s21, 2
	s_add_u32 s42, s42, 0x100
	s_addc_u32 s43, s43, 0
	s_add_u32 s14, s14, 0x100
	s_addc_u32 s15, s15, 0
	s_cmp_gt_u32 s21, 61
	s_cbranch_scc0 .LBB0_900
	s_and_b64 vcc, exec, s[22:23]
	s_cbranch_vccz .LBB0_903
	s_barrier
